# baseline (speedup 1.0000x reference)
; __device__ __forceinline__ void gemm_gates6(f32x4 (&acc)[4][6], const bf16_t* __restrict__ A, int lda,
;                                             const bf16_t* __restrict__ Bt, int ldb, int bstr, bf16_t* sA0, bf16_t* sB0,
;                                             const int tidx) {
;   const int tid = tidx, lane = tid & 63, w = tid >> 6;
;   const int wm = w >> 1, wn = w & 1;
;   const int l15 = lane & 15, quad = lane >> 4;
;   constexpr int BUFE = (256 + 192) * GSTR;
;   const int cr = tid >> 3, ck = tid & 7;
;   const unsigned aoffb = (unsigned)(cr * lda + ck * 8) * 2u;
;   const unsigned boffb = (unsigned)(cr * ldb + ck * 8) * 2u;
;   const int brow = (cr >> 5) * 96 + (cr & 31);
;   u32x4 ra[4], rb[3];
;     ...
;   W_LOAD(0);
;   __syncthreads();
;   W_STORE(0);
;   W_LOAD(64);
;   __syncthreads();
; #pragma unroll
;   for (int ks = 0; ks < 16; ks++) {
;     const bf16_t* sA_ = sA0 + (ks & 1) * BUFE;
;     const bf16_t* sB_ = sB0 + (ks & 1) * BUFE;
; #pragma unroll
;     for (int kk = 0; kk < 64; kk += 32) {
;       bf16x8 a[4], b[6];
; #pragma unroll
;       for (int i = 0; i < 4; i++) a[i] = *(const bf16x8*)(sA_ + (wm * 64 + i * 16 + l15) * GSTR + kk + quad * 8);
; #pragma unroll
;       for (int j = 0; j < 6; j++) b[j] = *(const bf16x8*)(sB_ + (wn * 96 + j * 16 + l15) * GSTR + kk + quad * 8);
;       bf16_t* dA_ = sA0 + ((ks + 1) & 1) * BUFE;
;       bf16_t* dB_ = sB0 + ((ks + 1) & 1) * BUFE;
; #pragma unroll
;       for (int i = 0; i < 4; i++) {
; #pragma unroll
;         for (int j = 0; j < 6; j++) acc[i][j] = __builtin_amdgcn_mfma_f32_16x16x32_bf16(a[i], b[j], acc[i][j], 0, 0, 0);
;         if (kk == 32 && i == 0 && ks + 2 < 16) {
;           W_LOAD((ks + 2) * 64);
;           __builtin_amdgcn_sched_barrier(0);
;         }
;         if (kk == 0 && ks + 1 < 16) {
; __device__ __forceinline__ void phase_merge(const Params& p, const int tidx) {
;     ...
;   for (int tile = blockIdx.x, rnd = 0; tile < 128 * 16; tile += gridDim.x, rnd++) {
;     int mt = tile / 16, nt = tile % 16;
;     if (swz) {
;       nt = li & 15;
;       mt = (rnd * 8 + xcd) * 2 + (li >> 4);
;     }
;     unsigned gp[2][4][2][2];
;     unsigned* sGate = (unsigned*)(smem_raw + 122880);
;     {
;       f32x4 g6[4][6];
;       zero_acc<6>(g6);
;       gemm_gates6(g6, H + (size_t)mt * 256 * 1024, 1024, WinT + (size_t)(NP + nt * 64) * 1024, 1024, 1024, sA, sB, tidx);
.LBB0_85:
	s_ashr_i32 s0, s21, 31
	s_lshr_b32 s0, s0, 28
	s_add_i32 s0, s21, s0
	s_lshl_b32 s10, s20, 4
	v_readlane_b32 s11, v251, 25
	s_ashr_i32 s12, s0, 4
	s_and_b32 s0, s0, -16
	s_add_i32 s13, s11, s10
	v_readlane_b32 s10, v251, 12
	s_sub_i32 s0, s21, s0
	v_readlane_b32 s11, v251, 13
	s_and_b64 s[10:11], s[10:11], exec
	s_cselect_b32 s14, s13, s12
	v_readlane_b32 s10, v251, 24
	s_cselect_b32 s16, s10, s0
	s_ashr_i32 s15, s14, 31
	s_lshl_b64 s[10:11], s[14:15], 19
	s_add_u32 s10, s50, s10
	s_addc_u32 s11, s51, s11
	s_lshl_b32 s12, s16, 6
	s_add_i32 s0, s12, 0x1d00
	s_lshl_b64 s[18:19], s[0:1], 11
	v_lshl_add_u64 v[8:9], s[10:11], 0, v[0:1]
	s_mov_b32 s0, 0x20000
	v_add_co_u32_e64 v10, s[10:11], s0, v8
	s_mov_b32 s0, 0x40000
	s_nop 0
	v_addc_co_u32_e64 v11, s[10:11], 0, v9, s[10:11]
	v_readlane_b32 s22, v251, 20
	v_add_co_u32_e64 v12, s[10:11], s0, v8
	v_readlane_b32 s23, v251, 21
	s_add_u32 s18, s22, s18
	v_addc_co_u32_e64 v13, s[10:11], 0, v9, s[10:11]
	s_addc_u32 s19, s23, s19
	v_add_co_u32_e64 v14, s[10:11], s24, v8
	v_lshl_add_u64 v[16:17], s[18:19], 0, v[0:1]
	s_nop 0
	v_addc_co_u32_e64 v15, s[10:11], 0, v9, s[10:11]
	s_mov_b32 s0, 0x200000
	v_add_co_u32_e64 v18, s[10:11], s0, v16
	s_mul_hi_i32 s61, s14, 0x3a0000
	s_mul_i32 s60, s14, 0x3a0000
	s_add_u32 s60, s94, s60
	s_addc_u32 s61, s95, s61
	v_lshrrev_b32_e32 v24, 1, v150
	v_mul_u32_u24_e32 v24, 0x3a00, v24
	v_and_b32_e32 v25, 1, v150
	v_lshl_or_b32 v24, v25, 7, v24
	v_add_u32_e32 v24, 0x400, v24
	v_add_u32_e32 v26, 0x1000, v24
	v_add_u32_e32 v27, 0x2e00, v24
	global_load_dword v25, v24, s[60:61]
	global_load_dword v25, v26, s[60:61]
	global_load_dword v25, v27, s[60:61]
	global_load_dwordx4 v[24:27], v[8:9], off
	global_load_dwordx4 v[28:31], v[10:11], off
	global_load_dwordx4 v[32:35], v[12:13], off
	global_load_dwordx4 v[36:39], v[14:15], off
	v_addc_co_u32_e64 v19, s[10:11], 0, v17, s[10:11]
	global_load_dwordx4 v[40:43], v[16:17], off
	global_load_dwordx4 v[44:47], v[18:19], off
	s_mov_b32 s0, 0x400000
	v_add_co_u32_e64 v20, s[10:11], s0, v16
	v_add_u32_e32 v23, v118, v119
	s_nop 0
	v_addc_co_u32_e64 v21, s[10:11], 0, v17, s[10:11]
	global_load_dwordx4 v[48:51], v[20:21], off
	s_barrier
	global_load_dwordx4 v[52:55], v[8:9], off offset:128
	global_load_dwordx4 v[56:59], v[10:11], off offset:128
	global_load_dwordx4 v[60:63], v[12:13], off offset:128
	global_load_dwordx4 v[64:67], v[14:15], off offset:128
	global_load_dwordx4 v[68:71], v[16:17], off offset:128
	global_load_dwordx4 v[72:75], v[18:19], off offset:128
	global_load_dwordx4 v[76:79], v[20:21], off offset:128
	v_add_u32_e32 v22, v120, v121
	s_waitcnt vmcnt(13)
	ds_write_b128 v125, v[24:27]
	s_waitcnt vmcnt(12)
	ds_write_b128 v125, v[28:31] offset:10240
	s_waitcnt vmcnt(11)
	ds_write_b128 v125, v[32:35] offset:20480
	s_waitcnt vmcnt(10)
	ds_write_b128 v125, v[36:39] offset:30720
	s_waitcnt vmcnt(9)
	ds_write_b128 v23, v[40:43] offset:40960
	s_waitcnt vmcnt(8)
	ds_write_b128 v23, v[44:47] offset:46080
	s_waitcnt vmcnt(7)
	ds_write_b128 v23, v[48:51] offset:51200
	s_waitcnt lgkmcnt(0)
	s_barrier
	ds_read_b128 v[24:27], v124
	ds_read_b128 v[28:31], v22 offset:40960
	ds_read_b128 v[32:35], v124 offset:2560
	ds_read_b128 v[36:39], v22 offset:43520
	ds_read_b128 v[48:51], v22 offset:46080
	ds_read_b128 v[80:83], v22 offset:48640
	ds_read_b128 v[92:95], v22 offset:51200
	ds_read_b128 v[102:105], v22 offset:53760
	ds_read_b128 v[110:113], v124 offset:5120
	ds_read_b128 v[156:159], v124 offset:7680
	s_waitcnt lgkmcnt(8)
	v_mfma_f32_16x16x32_bf16 v[40:43], v[24:27], v[28:31], 0
	s_waitcnt vmcnt(6)
	ds_write_b128 v139, v[52:55]
	s_waitcnt vmcnt(2)
	ds_write_b128 v140, v[68:71]
	s_waitcnt lgkmcnt(8)
	v_mfma_f32_16x16x32_bf16 v[44:47], v[24:27], v[36:39], 0
	s_waitcnt lgkmcnt(7)
	v_mfma_f32_16x16x32_bf16 v[84:87], v[24:27], v[48:51], 0
	s_waitcnt lgkmcnt(6)
	v_mfma_f32_16x16x32_bf16 v[88:91], v[24:27], v[80:83], 0
	s_waitcnt lgkmcnt(5)
	v_mfma_f32_16x16x32_bf16 v[106:109], v[24:27], v[92:95], 0
	s_waitcnt lgkmcnt(4)
	v_mfma_f32_16x16x32_bf16 v[24:27], v[24:27], v[102:105], 0
	v_mfma_f32_16x16x32_bf16 v[52:55], v[32:35], v[28:31], 0
	ds_write_b128 v139, v[56:59] offset:10240
	s_waitcnt vmcnt(1)
	ds_write_b128 v140, v[72:75] offset:5120
	v_mfma_f32_16x16x32_bf16 v[68:71], v[32:35], v[36:39], 0
	v_mfma_f32_16x16x32_bf16 v[174:177], v[32:35], v[48:51], 0
	v_mfma_f32_16x16x32_bf16 v[178:181], v[32:35], v[80:83], 0
	v_mfma_f32_16x16x32_bf16 v[182:185], v[32:35], v[92:95], 0
	v_mfma_f32_16x16x32_bf16 v[32:35], v[32:35], v[102:105], 0
	s_waitcnt lgkmcnt(5)
	v_mfma_f32_16x16x32_bf16 v[56:59], v[110:113], v[28:31], 0
	ds_write_b128 v139, v[60:63] offset:20480
	s_waitcnt vmcnt(0)
	ds_write_b128 v140, v[76:79] offset:10240
	v_mfma_f32_16x16x32_bf16 v[72:75], v[110:113], v[36:39], 0
	v_mfma_f32_16x16x32_bf16 v[186:189], v[110:113], v[48:51], 0
	v_mfma_f32_16x16x32_bf16 v[190:193], v[110:113], v[80:83], 0
	v_mfma_f32_16x16x32_bf16 v[194:197], v[110:113], v[92:95], 0
	v_mfma_f32_16x16x32_bf16 v[60:63], v[110:113], v[102:105], 0
	s_waitcnt lgkmcnt(6)
	v_mfma_f32_16x16x32_bf16 v[28:31], v[156:159], v[28:31], 0
	ds_write_b128 v139, v[64:67] offset:30720
	v_mfma_f32_16x16x32_bf16 v[36:39], v[156:159], v[36:39], 0
	v_mfma_f32_16x16x32_bf16 v[48:51], v[156:159], v[48:51], 0
	v_mfma_f32_16x16x32_bf16 v[76:79], v[156:159], v[80:83], 0
	v_mfma_f32_16x16x32_bf16 v[80:83], v[156:159], v[92:95], 0
	v_mfma_f32_16x16x32_bf16 v[64:67], v[156:159], v[102:105], 0
	ds_read_b128 v[92:95], v124 offset:64
	ds_read_b128 v[102:105], v124 offset:2624
	ds_read_b128 v[110:113], v124 offset:5184
	ds_read_b128 v[156:159], v124 offset:7744
	ds_read_b128 v[198:201], v22 offset:41024
	ds_read_b128 v[202:205], v22 offset:43584
	ds_read_b128 v[206:209], v22 offset:46144
	ds_read_b128 v[210:213], v22 offset:48704
	ds_read_b128 v[214:217], v22 offset:51264
	ds_read_b128 v[218:221], v22 offset:53824
	s_waitcnt lgkmcnt(5)
; __device__ __forceinline__ void gemm_gates6(f32x4 (&acc)[4][6], const bf16_t* __restrict__ A, int lda,
;                                             const bf16_t* __restrict__ Bt, int ldb, int bstr, bf16_t* sA0, bf16_t* sB0,
;                                             const int tidx) {
;     ...
; #pragma unroll
;   for (int ks = 0; ks < 16; ks++) {
;     const bf16_t* sA_ = sA0 + (ks & 1) * BUFE;
;     const bf16_t* sB_ = sB0 + (ks & 1) * BUFE;
; #pragma unroll
;     for (int kk = 0; kk < 64; kk += 32) {
;       bf16x8 a[4], b[6];
; #pragma unroll
;       for (int i = 0; i < 4; i++) a[i] = *(const bf16x8*)(sA_ + (wm * 64 + i * 16 + l15) * GSTR + kk + quad * 8);
; #pragma unroll
;       for (int j = 0; j < 6; j++) b[j] = *(const bf16x8*)(sB_ + (wn * 96 + j * 16 + l15) * GSTR + kk + quad * 8);
;       bf16_t* dA_ = sA0 + ((ks + 1) & 1) * BUFE;
;       bf16_t* dB_ = sB0 + ((ks + 1) & 1) * BUFE;
; #pragma unroll
;       for (int i = 0; i < 4; i++) {
; #pragma unroll
;         for (int j = 0; j < 6; j++) acc[i][j] = __builtin_amdgcn_mfma_f32_16x16x32_bf16(a[i], b[j], acc[i][j], 0, 0, 0);
;         if (kk == 32 && i == 0 && ks + 2 < 16) {
;           W_LOAD((ks + 2) * 64);
;           __builtin_amdgcn_sched_barrier(0);
;         }
;         if (kk == 0 && ks + 1 < 16) {
;           *(u32x4*)(dA_ + (cr + 64 * i) * GSTR + ck * 8) = ra[i];
;           if (i < 3) *(u32x4*)(dB_ + (brow + i * 32) * GSTR + ck * 8) = rb[i];
;           __builtin_amdgcn_sched_barrier(0);
;         }
;       }
;       __builtin_amdgcn_sched_barrier(0);
;     }
;     if (ks + 1 < 16) __syncthreads();
;   }
	v_mfma_f32_16x16x32_bf16 v[40:43], v[92:95], v[198:201], v[40:43]
	s_waitcnt lgkmcnt(4)
	v_mfma_f32_16x16x32_bf16 v[44:47], v[92:95], v[202:205], v[44:47]
	s_waitcnt lgkmcnt(3)
	v_mfma_f32_16x16x32_bf16 v[84:87], v[92:95], v[206:209], v[84:87]
	s_waitcnt lgkmcnt(2)
	v_mfma_f32_16x16x32_bf16 v[88:91], v[92:95], v[210:213], v[88:91]
	s_waitcnt lgkmcnt(1)
	v_mfma_f32_16x16x32_bf16 v[106:109], v[92:95], v[214:217], v[106:109]
	s_waitcnt lgkmcnt(0)
	v_mfma_f32_16x16x32_bf16 v[24:27], v[92:95], v[218:221], v[24:27]
	global_load_dwordx4 v[92:95], v[8:9], off offset:256
	global_load_dwordx4 v[222:225], v[10:11], off offset:256
	global_load_dwordx4 v[226:229], v[12:13], off offset:256
	global_load_dwordx4 v[230:233], v[14:15], off offset:256
	global_load_dwordx4 v[234:237], v[16:17], off offset:256
	global_load_dwordx4 v[238:241], v[18:19], off offset:256
	global_load_dwordx4 v[242:245], v[20:21], off offset:256
	v_mfma_f32_16x16x32_bf16 v[52:55], v[102:105], v[198:201], v[52:55]
	v_mfma_f32_16x16x32_bf16 v[68:71], v[102:105], v[202:205], v[68:71]
	v_mfma_f32_16x16x32_bf16 v[174:177], v[102:105], v[206:209], v[174:177]
	v_mfma_f32_16x16x32_bf16 v[178:181], v[102:105], v[210:213], v[178:181]
	v_mfma_f32_16x16x32_bf16 v[182:185], v[102:105], v[214:217], v[182:185]
	v_mfma_f32_16x16x32_bf16 v[32:35], v[102:105], v[218:221], v[32:35]
	v_mfma_f32_16x16x32_bf16 v[56:59], v[110:113], v[198:201], v[56:59]
	v_mfma_f32_16x16x32_bf16 v[72:75], v[110:113], v[202:205], v[72:75]
	v_mfma_f32_16x16x32_bf16 v[102:105], v[110:113], v[206:209], v[186:189]
	v_mfma_f32_16x16x32_bf16 v[186:189], v[110:113], v[210:213], v[190:193]
	v_mfma_f32_16x16x32_bf16 v[190:193], v[110:113], v[214:217], v[194:197]
	v_mfma_f32_16x16x32_bf16 v[60:63], v[110:113], v[218:221], v[60:63]
	v_mfma_f32_16x16x32_bf16 v[28:31], v[156:159], v[198:201], v[28:31]
	v_mfma_f32_16x16x32_bf16 v[36:39], v[156:159], v[202:205], v[36:39]
	v_mfma_f32_16x16x32_bf16 v[48:51], v[156:159], v[206:209], v[48:51]
	v_mfma_f32_16x16x32_bf16 v[76:79], v[156:159], v[210:213], v[76:79]
	v_mfma_f32_16x16x32_bf16 v[80:83], v[156:159], v[214:217], v[80:83]
	v_mfma_f32_16x16x32_bf16 v[64:67], v[156:159], v[218:221], v[64:67]
	s_barrier
	ds_read_b128 v[110:113], v141
	ds_read_b128 v[156:159], v142
	ds_read_b128 v[194:197], v141 offset:2560
	ds_read_b128 v[198:201], v142 offset:2560
	ds_read_b128 v[202:205], v142 offset:5120
	ds_read_b128 v[206:209], v142 offset:7680
	ds_read_b128 v[210:213], v142 offset:10240
	ds_read_b128 v[214:217], v142 offset:12800
	ds_read_b128 v[218:221], v141 offset:5120
	ds_read_b128 v[246:249], v141 offset:7680
	s_waitcnt lgkmcnt(8)
	v_mfma_f32_16x16x32_bf16 v[40:43], v[110:113], v[156:159], v[40:43]
	s_waitcnt vmcnt(6)
	ds_write_b128 v125, v[92:95]
	s_waitcnt vmcnt(2)
	ds_write_b128 v23, v[234:237] offset:40960
	s_waitcnt lgkmcnt(8)
	v_mfma_f32_16x16x32_bf16 v[44:47], v[110:113], v[198:201], v[44:47]
	s_waitcnt lgkmcnt(7)
	v_mfma_f32_16x16x32_bf16 v[84:87], v[110:113], v[202:205], v[84:87]
	s_waitcnt lgkmcnt(6)
	v_mfma_f32_16x16x32_bf16 v[88:91], v[110:113], v[206:209], v[88:91]
	s_waitcnt lgkmcnt(5)
	v_mfma_f32_16x16x32_bf16 v[106:109], v[110:113], v[210:213], v[106:109]
	s_waitcnt lgkmcnt(4)
	v_mfma_f32_16x16x32_bf16 v[24:27], v[110:113], v[214:217], v[24:27]
	v_mfma_f32_16x16x32_bf16 v[52:55], v[194:197], v[156:159], v[52:55]
	ds_write_b128 v125, v[222:225] offset:10240
	s_waitcnt vmcnt(1)
	ds_write_b128 v23, v[238:241] offset:46080
	v_mfma_f32_16x16x32_bf16 v[68:71], v[194:197], v[198:201], v[68:71]
	v_mfma_f32_16x16x32_bf16 v[92:95], v[194:197], v[202:205], v[174:177]
	v_mfma_f32_16x16x32_bf16 v[110:113], v[194:197], v[206:209], v[178:181]
	v_mfma_f32_16x16x32_bf16 v[174:177], v[194:197], v[210:213], v[182:185]
	v_mfma_f32_16x16x32_bf16 v[32:35], v[194:197], v[214:217], v[32:35]
	s_waitcnt lgkmcnt(5)
	v_mfma_f32_16x16x32_bf16 v[56:59], v[218:221], v[156:159], v[56:59]
	ds_write_b128 v125, v[226:229] offset:20480
	s_waitcnt vmcnt(0)
	ds_write_b128 v23, v[242:245] offset:51200
	v_mfma_f32_16x16x32_bf16 v[72:75], v[218:221], v[198:201], v[72:75]
	v_mfma_f32_16x16x32_bf16 v[102:105], v[218:221], v[202:205], v[102:105]
	v_mfma_f32_16x16x32_bf16 v[178:181], v[218:221], v[206:209], v[186:189]
	v_mfma_f32_16x16x32_bf16 v[182:185], v[218:221], v[210:213], v[190:193]
	v_mfma_f32_16x16x32_bf16 v[60:63], v[218:221], v[214:217], v[60:63]
	s_waitcnt lgkmcnt(6)
	v_mfma_f32_16x16x32_bf16 v[28:31], v[246:249], v[156:159], v[28:31]
	ds_write_b128 v125, v[230:233] offset:30720
	v_mfma_f32_16x16x32_bf16 v[36:39], v[246:249], v[198:201], v[36:39]
	v_mfma_f32_16x16x32_bf16 v[48:51], v[246:249], v[202:205], v[48:51]
	v_mfma_f32_16x16x32_bf16 v[76:79], v[246:249], v[206:209], v[76:79]
	v_mfma_f32_16x16x32_bf16 v[80:83], v[246:249], v[210:213], v[80:83]
	v_mfma_f32_16x16x32_bf16 v[64:67], v[246:249], v[214:217], v[64:67]
	ds_read_b128 v[156:159], v143
	ds_read_b128 v[186:189], v143 offset:2560
	ds_read_b128 v[190:193], v143 offset:5120
	ds_read_b128 v[194:197], v143 offset:7680
	ds_read_b128 v[198:201], v144
	ds_read_b128 v[202:205], v144 offset:2560
	ds_read_b128 v[206:209], v144 offset:5120
	ds_read_b128 v[210:213], v144 offset:7680
	ds_read_b128 v[214:217], v144 offset:10240
	ds_read_b128 v[218:221], v144 offset:12800
	s_waitcnt lgkmcnt(5)
	v_mfma_f32_16x16x32_bf16 v[40:43], v[156:159], v[198:201], v[40:43]
	s_waitcnt lgkmcnt(4)
	v_mfma_f32_16x16x32_bf16 v[44:47], v[156:159], v[202:205], v[44:47]
	s_waitcnt lgkmcnt(3)
	v_mfma_f32_16x16x32_bf16 v[84:87], v[156:159], v[206:209], v[84:87]
	s_waitcnt lgkmcnt(2)
	v_mfma_f32_16x16x32_bf16 v[88:91], v[156:159], v[210:213], v[88:91]
	s_waitcnt lgkmcnt(1)
; __device__ __forceinline__ void gemm_gates6(f32x4 (&acc)[4][6], const bf16_t* __restrict__ A, int lda,
;                                             const bf16_t* __restrict__ Bt, int ldb, int bstr, bf16_t* sA0, bf16_t* sB0,
;                                             const int tidx) {
;     ...
; #pragma unroll
;   for (int ks = 0; ks < 16; ks++) {
;     const bf16_t* sA_ = sA0 + (ks & 1) * BUFE;
;     const bf16_t* sB_ = sB0 + (ks & 1) * BUFE;
; #pragma unroll
;     for (int kk = 0; kk < 64; kk += 32) {
;       bf16x8 a[4], b[6];
; #pragma unroll
;       for (int i = 0; i < 4; i++) a[i] = *(const bf16x8*)(sA_ + (wm * 64 + i * 16 + l15) * GSTR + kk + quad * 8);
; #pragma unroll
;       for (int j = 0; j < 6; j++) b[j] = *(const bf16x8*)(sB_ + (wn * 96 + j * 16 + l15) * GSTR + kk + quad * 8);
;       bf16_t* dA_ = sA0 + ((ks + 1) & 1) * BUFE;
;       bf16_t* dB_ = sB0 + ((ks + 1) & 1) * BUFE;
; #pragma unroll
;       for (int i = 0; i < 4; i++) {
; #pragma unroll
;         for (int j = 0; j < 6; j++) acc[i][j] = __builtin_amdgcn_mfma_f32_16x16x32_bf16(a[i], b[j], acc[i][j], 0, 0, 0);
;         if (kk == 32 && i == 0 && ks + 2 < 16) {
;           W_LOAD((ks + 2) * 64);
;           __builtin_amdgcn_sched_barrier(0);
;         }
;         if (kk == 0 && ks + 1 < 16) {
;           *(u32x4*)(dA_ + (cr + 64 * i) * GSTR + ck * 8) = ra[i];
;           if (i < 3) *(u32x4*)(dB_ + (brow + i * 32) * GSTR + ck * 8) = rb[i];
;           __builtin_amdgcn_sched_barrier(0);
;         }
;       }
;       __builtin_amdgcn_sched_barrier(0);
;     }
;     if (ks + 1 < 16) __syncthreads();
;   }
	v_mfma_f32_16x16x32_bf16 v[106:109], v[156:159], v[214:217], v[106:109]
	s_waitcnt lgkmcnt(0)
	v_mfma_f32_16x16x32_bf16 v[24:27], v[156:159], v[218:221], v[24:27]
	global_load_dwordx4 v[156:159], v[8:9], off offset:384
	global_load_dwordx4 v[222:225], v[10:11], off offset:384
	global_load_dwordx4 v[226:229], v[12:13], off offset:384
	global_load_dwordx4 v[230:233], v[14:15], off offset:384
	global_load_dwordx4 v[234:237], v[16:17], off offset:384
	global_load_dwordx4 v[238:241], v[18:19], off offset:384
	global_load_dwordx4 v[242:245], v[20:21], off offset:384
	v_mfma_f32_16x16x32_bf16 v[52:55], v[186:189], v[198:201], v[52:55]
	v_mfma_f32_16x16x32_bf16 v[68:71], v[186:189], v[202:205], v[68:71]
	v_mfma_f32_16x16x32_bf16 v[92:95], v[186:189], v[206:209], v[92:95]
	v_mfma_f32_16x16x32_bf16 v[110:113], v[186:189], v[210:213], v[110:113]
	v_mfma_f32_16x16x32_bf16 v[174:177], v[186:189], v[214:217], v[174:177]
	v_mfma_f32_16x16x32_bf16 v[32:35], v[186:189], v[218:221], v[32:35]
	v_mfma_f32_16x16x32_bf16 v[56:59], v[190:193], v[198:201], v[56:59]
	v_mfma_f32_16x16x32_bf16 v[72:75], v[190:193], v[202:205], v[72:75]
	v_mfma_f32_16x16x32_bf16 v[102:105], v[190:193], v[206:209], v[102:105]
	v_mfma_f32_16x16x32_bf16 v[178:181], v[190:193], v[210:213], v[178:181]
	v_mfma_f32_16x16x32_bf16 v[182:185], v[190:193], v[214:217], v[182:185]
	v_mfma_f32_16x16x32_bf16 v[60:63], v[190:193], v[218:221], v[60:63]
	v_mfma_f32_16x16x32_bf16 v[28:31], v[194:197], v[198:201], v[28:31]
	v_mfma_f32_16x16x32_bf16 v[36:39], v[194:197], v[202:205], v[36:39]
	v_mfma_f32_16x16x32_bf16 v[48:51], v[194:197], v[206:209], v[48:51]
	v_mfma_f32_16x16x32_bf16 v[76:79], v[194:197], v[210:213], v[76:79]
	v_mfma_f32_16x16x32_bf16 v[80:83], v[194:197], v[214:217], v[80:83]
	v_mfma_f32_16x16x32_bf16 v[64:67], v[194:197], v[218:221], v[64:67]
	s_barrier
	ds_read_b128 v[186:189], v124
	ds_read_b128 v[190:193], v22 offset:40960
	ds_read_b128 v[194:197], v124 offset:2560
	ds_read_b128 v[198:201], v22 offset:43520
	ds_read_b128 v[202:205], v22 offset:46080
	ds_read_b128 v[206:209], v22 offset:48640
	ds_read_b128 v[210:213], v22 offset:51200
	ds_read_b128 v[214:217], v22 offset:53760
	ds_read_b128 v[218:221], v124 offset:5120
	ds_read_b128 v[246:249], v124 offset:7680
	s_waitcnt lgkmcnt(8)
	v_mfma_f32_16x16x32_bf16 v[40:43], v[186:189], v[190:193], v[40:43]
	s_waitcnt vmcnt(6)
	ds_write_b128 v139, v[156:159]
	s_waitcnt vmcnt(2)
	ds_write_b128 v140, v[234:237]
	s_waitcnt lgkmcnt(8)
	v_mfma_f32_16x16x32_bf16 v[44:47], v[186:189], v[198:201], v[44:47]
	s_waitcnt lgkmcnt(7)
	v_mfma_f32_16x16x32_bf16 v[84:87], v[186:189], v[202:205], v[84:87]
	s_waitcnt lgkmcnt(6)
	v_mfma_f32_16x16x32_bf16 v[88:91], v[186:189], v[206:209], v[88:91]
	s_waitcnt lgkmcnt(5)
	v_mfma_f32_16x16x32_bf16 v[106:109], v[186:189], v[210:213], v[106:109]
	s_waitcnt lgkmcnt(4)
	v_mfma_f32_16x16x32_bf16 v[24:27], v[186:189], v[214:217], v[24:27]
	v_mfma_f32_16x16x32_bf16 v[52:55], v[194:197], v[190:193], v[52:55]
	ds_write_b128 v139, v[222:225] offset:10240
	s_waitcnt vmcnt(1)
	ds_write_b128 v140, v[238:241] offset:5120
	v_mfma_f32_16x16x32_bf16 v[68:71], v[194:197], v[198:201], v[68:71]
	v_mfma_f32_16x16x32_bf16 v[92:95], v[194:197], v[202:205], v[92:95]
	v_mfma_f32_16x16x32_bf16 v[110:113], v[194:197], v[206:209], v[110:113]
	v_mfma_f32_16x16x32_bf16 v[156:159], v[194:197], v[210:213], v[174:177]
	v_mfma_f32_16x16x32_bf16 v[32:35], v[194:197], v[214:217], v[32:35]
	s_waitcnt lgkmcnt(5)
	v_mfma_f32_16x16x32_bf16 v[56:59], v[218:221], v[190:193], v[56:59]
	ds_write_b128 v139, v[226:229] offset:20480
	s_waitcnt vmcnt(0)
	ds_write_b128 v140, v[242:245] offset:10240
	v_mfma_f32_16x16x32_bf16 v[72:75], v[218:221], v[198:201], v[72:75]
	v_mfma_f32_16x16x32_bf16 v[102:105], v[218:221], v[202:205], v[102:105]
	v_mfma_f32_16x16x32_bf16 v[174:177], v[218:221], v[206:209], v[178:181]
	v_mfma_f32_16x16x32_bf16 v[178:181], v[218:221], v[210:213], v[182:185]
	v_mfma_f32_16x16x32_bf16 v[60:63], v[218:221], v[214:217], v[60:63]
	s_waitcnt lgkmcnt(6)
	v_mfma_f32_16x16x32_bf16 v[28:31], v[246:249], v[190:193], v[28:31]
	ds_write_b128 v139, v[230:233] offset:30720
	v_mfma_f32_16x16x32_bf16 v[36:39], v[246:249], v[198:201], v[36:39]
	v_mfma_f32_16x16x32_bf16 v[48:51], v[246:249], v[202:205], v[48:51]
	v_mfma_f32_16x16x32_bf16 v[76:79], v[246:249], v[206:209], v[76:79]
	v_mfma_f32_16x16x32_bf16 v[80:83], v[246:249], v[210:213], v[80:83]
	v_mfma_f32_16x16x32_bf16 v[64:67], v[246:249], v[214:217], v[64:67]
	ds_read_b128 v[182:185], v124 offset:64
	ds_read_b128 v[186:189], v124 offset:2624
	ds_read_b128 v[190:193], v124 offset:5184
	ds_read_b128 v[194:197], v124 offset:7744
	ds_read_b128 v[198:201], v22 offset:41024
	ds_read_b128 v[202:205], v22 offset:43584
	ds_read_b128 v[206:209], v22 offset:46144
	ds_read_b128 v[210:213], v22 offset:48704
	ds_read_b128 v[214:217], v22 offset:51264
	ds_read_b128 v[218:221], v22 offset:53824
	s_waitcnt lgkmcnt(5)
	v_mfma_f32_16x16x32_bf16 v[40:43], v[182:185], v[198:201], v[40:43]
	s_waitcnt lgkmcnt(4)
	v_mfma_f32_16x16x32_bf16 v[44:47], v[182:185], v[202:205], v[44:47]
	s_waitcnt lgkmcnt(3)
	v_mfma_f32_16x16x32_bf16 v[84:87], v[182:185], v[206:209], v[84:87]
	s_waitcnt lgkmcnt(2)
	v_mfma_f32_16x16x32_bf16 v[88:91], v[182:185], v[210:213], v[88:91]
	s_waitcnt lgkmcnt(1)
	v_mfma_f32_16x16x32_bf16 v[106:109], v[182:185], v[214:217], v[106:109]
	s_waitcnt lgkmcnt(0)
; __device__ __forceinline__ void gemm_gates6(f32x4 (&acc)[4][6], const bf16_t* __restrict__ A, int lda,
;                                             const bf16_t* __restrict__ Bt, int ldb, int bstr, bf16_t* sA0, bf16_t* sB0,
;                                             const int tidx) {
;     ...
; #pragma unroll
;   for (int ks = 0; ks < 16; ks++) {
;     const bf16_t* sA_ = sA0 + (ks & 1) * BUFE;
;     const bf16_t* sB_ = sB0 + (ks & 1) * BUFE;
; #pragma unroll
;     for (int kk = 0; kk < 64; kk += 32) {
;       bf16x8 a[4], b[6];
; #pragma unroll
;       for (int i = 0; i < 4; i++) a[i] = *(const bf16x8*)(sA_ + (wm * 64 + i * 16 + l15) * GSTR + kk + quad * 8);
; #pragma unroll
;       for (int j = 0; j < 6; j++) b[j] = *(const bf16x8*)(sB_ + (wn * 96 + j * 16 + l15) * GSTR + kk + quad * 8);
;       bf16_t* dA_ = sA0 + ((ks + 1) & 1) * BUFE;
;       bf16_t* dB_ = sB0 + ((ks + 1) & 1) * BUFE;
; #pragma unroll
;       for (int i = 0; i < 4; i++) {
; #pragma unroll
;         for (int j = 0; j < 6; j++) acc[i][j] = __builtin_amdgcn_mfma_f32_16x16x32_bf16(a[i], b[j], acc[i][j], 0, 0, 0);
;         if (kk == 32 && i == 0 && ks + 2 < 16) {
;           W_LOAD((ks + 2) * 64);
;           __builtin_amdgcn_sched_barrier(0);
;         }
;         if (kk == 0 && ks + 1 < 16) {
;           *(u32x4*)(dA_ + (cr + 64 * i) * GSTR + ck * 8) = ra[i];
;           if (i < 3) *(u32x4*)(dB_ + (brow + i * 32) * GSTR + ck * 8) = rb[i];
;           __builtin_amdgcn_sched_barrier(0);
;         }
;       }
;       __builtin_amdgcn_sched_barrier(0);
;     }
;     if (ks + 1 < 16) __syncthreads();
;   }
	v_mfma_f32_16x16x32_bf16 v[24:27], v[182:185], v[218:221], v[24:27]
	global_load_dwordx4 v[182:185], v[8:9], off offset:512
	global_load_dwordx4 v[222:225], v[10:11], off offset:512
	global_load_dwordx4 v[226:229], v[12:13], off offset:512
	global_load_dwordx4 v[230:233], v[14:15], off offset:512
	global_load_dwordx4 v[234:237], v[16:17], off offset:512
	global_load_dwordx4 v[238:241], v[18:19], off offset:512
	global_load_dwordx4 v[242:245], v[20:21], off offset:512
	v_mfma_f32_16x16x32_bf16 v[52:55], v[186:189], v[198:201], v[52:55]
	v_mfma_f32_16x16x32_bf16 v[68:71], v[186:189], v[202:205], v[68:71]
	v_mfma_f32_16x16x32_bf16 v[92:95], v[186:189], v[206:209], v[92:95]
	v_mfma_f32_16x16x32_bf16 v[110:113], v[186:189], v[210:213], v[110:113]
	v_mfma_f32_16x16x32_bf16 v[156:159], v[186:189], v[214:217], v[156:159]
	v_mfma_f32_16x16x32_bf16 v[32:35], v[186:189], v[218:221], v[32:35]
	v_mfma_f32_16x16x32_bf16 v[56:59], v[190:193], v[198:201], v[56:59]
	v_mfma_f32_16x16x32_bf16 v[72:75], v[190:193], v[202:205], v[72:75]
	v_mfma_f32_16x16x32_bf16 v[102:105], v[190:193], v[206:209], v[102:105]
	v_mfma_f32_16x16x32_bf16 v[174:177], v[190:193], v[210:213], v[174:177]
	v_mfma_f32_16x16x32_bf16 v[178:181], v[190:193], v[214:217], v[178:181]
	v_mfma_f32_16x16x32_bf16 v[60:63], v[190:193], v[218:221], v[60:63]
	v_mfma_f32_16x16x32_bf16 v[28:31], v[194:197], v[198:201], v[28:31]
	v_mfma_f32_16x16x32_bf16 v[36:39], v[194:197], v[202:205], v[36:39]
	v_mfma_f32_16x16x32_bf16 v[48:51], v[194:197], v[206:209], v[48:51]
	v_mfma_f32_16x16x32_bf16 v[76:79], v[194:197], v[210:213], v[76:79]
	v_mfma_f32_16x16x32_bf16 v[80:83], v[194:197], v[214:217], v[80:83]
	v_mfma_f32_16x16x32_bf16 v[64:67], v[194:197], v[218:221], v[64:67]
	s_barrier
	ds_read_b128 v[186:189], v141
	ds_read_b128 v[190:193], v142
	ds_read_b128 v[194:197], v141 offset:2560
	ds_read_b128 v[198:201], v142 offset:2560
	ds_read_b128 v[202:205], v142 offset:5120
	ds_read_b128 v[206:209], v142 offset:7680
	ds_read_b128 v[210:213], v142 offset:10240
	ds_read_b128 v[214:217], v142 offset:12800
	ds_read_b128 v[218:221], v141 offset:5120
	ds_read_b128 v[246:249], v141 offset:7680
	s_waitcnt lgkmcnt(8)
	v_mfma_f32_16x16x32_bf16 v[40:43], v[186:189], v[190:193], v[40:43]
	s_waitcnt vmcnt(6)
	ds_write_b128 v125, v[182:185]
	s_waitcnt vmcnt(2)
	ds_write_b128 v23, v[234:237] offset:40960
	s_waitcnt lgkmcnt(8)
	v_mfma_f32_16x16x32_bf16 v[44:47], v[186:189], v[198:201], v[44:47]
	s_waitcnt lgkmcnt(7)
	v_mfma_f32_16x16x32_bf16 v[84:87], v[186:189], v[202:205], v[84:87]
	s_waitcnt lgkmcnt(6)
	v_mfma_f32_16x16x32_bf16 v[88:91], v[186:189], v[206:209], v[88:91]
	s_waitcnt lgkmcnt(5)
	v_mfma_f32_16x16x32_bf16 v[106:109], v[186:189], v[210:213], v[106:109]
	s_waitcnt lgkmcnt(4)
	v_mfma_f32_16x16x32_bf16 v[24:27], v[186:189], v[214:217], v[24:27]
	v_mfma_f32_16x16x32_bf16 v[52:55], v[194:197], v[190:193], v[52:55]
	ds_write_b128 v125, v[222:225] offset:10240
	s_waitcnt vmcnt(1)
	ds_write_b128 v23, v[238:241] offset:46080
	v_mfma_f32_16x16x32_bf16 v[68:71], v[194:197], v[198:201], v[68:71]
	v_mfma_f32_16x16x32_bf16 v[92:95], v[194:197], v[202:205], v[92:95]
	v_mfma_f32_16x16x32_bf16 v[110:113], v[194:197], v[206:209], v[110:113]
	v_mfma_f32_16x16x32_bf16 v[156:159], v[194:197], v[210:213], v[156:159]
	v_mfma_f32_16x16x32_bf16 v[32:35], v[194:197], v[214:217], v[32:35]
	s_waitcnt lgkmcnt(5)
	v_mfma_f32_16x16x32_bf16 v[56:59], v[218:221], v[190:193], v[56:59]
	ds_write_b128 v125, v[226:229] offset:20480
	s_waitcnt vmcnt(0)
	ds_write_b128 v23, v[242:245] offset:51200
	v_mfma_f32_16x16x32_bf16 v[72:75], v[218:221], v[198:201], v[72:75]
	v_mfma_f32_16x16x32_bf16 v[102:105], v[218:221], v[202:205], v[102:105]
	v_mfma_f32_16x16x32_bf16 v[174:177], v[218:221], v[206:209], v[174:177]
	v_mfma_f32_16x16x32_bf16 v[178:181], v[218:221], v[210:213], v[178:181]
	v_mfma_f32_16x16x32_bf16 v[60:63], v[218:221], v[214:217], v[60:63]
	s_waitcnt lgkmcnt(6)
	v_mfma_f32_16x16x32_bf16 v[28:31], v[246:249], v[190:193], v[28:31]
	ds_write_b128 v125, v[230:233] offset:30720
	v_mfma_f32_16x16x32_bf16 v[36:39], v[246:249], v[198:201], v[36:39]
	v_mfma_f32_16x16x32_bf16 v[48:51], v[246:249], v[202:205], v[48:51]
	v_mfma_f32_16x16x32_bf16 v[76:79], v[246:249], v[206:209], v[76:79]
	v_mfma_f32_16x16x32_bf16 v[80:83], v[246:249], v[210:213], v[80:83]
	v_mfma_f32_16x16x32_bf16 v[64:67], v[246:249], v[214:217], v[64:67]
	ds_read_b128 v[182:185], v143
	ds_read_b128 v[186:189], v143 offset:2560
	ds_read_b128 v[190:193], v143 offset:5120
	ds_read_b128 v[194:197], v143 offset:7680
	ds_read_b128 v[198:201], v144
	ds_read_b128 v[202:205], v144 offset:2560
	ds_read_b128 v[206:209], v144 offset:5120
	ds_read_b128 v[210:213], v144 offset:7680
	ds_read_b128 v[214:217], v144 offset:10240
	ds_read_b128 v[218:221], v144 offset:12800
	s_waitcnt lgkmcnt(5)
	v_mfma_f32_16x16x32_bf16 v[40:43], v[182:185], v[198:201], v[40:43]
	s_waitcnt lgkmcnt(4)
	v_mfma_f32_16x16x32_bf16 v[44:47], v[182:185], v[202:205], v[44:47]
	s_waitcnt lgkmcnt(3)
	v_mfma_f32_16x16x32_bf16 v[84:87], v[182:185], v[206:209], v[84:87]
	s_waitcnt lgkmcnt(2)
	v_mfma_f32_16x16x32_bf16 v[88:91], v[182:185], v[210:213], v[88:91]
	s_waitcnt lgkmcnt(1)
	v_mfma_f32_16x16x32_bf16 v[106:109], v[182:185], v[214:217], v[106:109]
	s_waitcnt lgkmcnt(0)
	v_mfma_f32_16x16x32_bf16 v[24:27], v[182:185], v[218:221], v[24:27]
	global_load_dwordx4 v[182:185], v[8:9], off offset:640
	global_load_dwordx4 v[222:225], v[10:11], off offset:640
	global_load_dwordx4 v[226:229], v[12:13], off offset:640
	global_load_dwordx4 v[230:233], v[14:15], off offset:640
	global_load_dwordx4 v[234:237], v[16:17], off offset:640
	global_load_dwordx4 v[238:241], v[18:19], off offset:640
	global_load_dwordx4 v[242:245], v[20:21], off offset:640
	v_mfma_f32_16x16x32_bf16 v[52:55], v[186:189], v[198:201], v[52:55]
	v_mfma_f32_16x16x32_bf16 v[68:71], v[186:189], v[202:205], v[68:71]
	v_mfma_f32_16x16x32_bf16 v[92:95], v[186:189], v[206:209], v[92:95]
	v_mfma_f32_16x16x32_bf16 v[110:113], v[186:189], v[210:213], v[110:113]
	v_mfma_f32_16x16x32_bf16 v[156:159], v[186:189], v[214:217], v[156:159]
	v_mfma_f32_16x16x32_bf16 v[32:35], v[186:189], v[218:221], v[32:35]
	v_mfma_f32_16x16x32_bf16 v[56:59], v[190:193], v[198:201], v[56:59]
	v_mfma_f32_16x16x32_bf16 v[72:75], v[190:193], v[202:205], v[72:75]
	v_mfma_f32_16x16x32_bf16 v[102:105], v[190:193], v[206:209], v[102:105]
	v_mfma_f32_16x16x32_bf16 v[174:177], v[190:193], v[210:213], v[174:177]
	v_mfma_f32_16x16x32_bf16 v[178:181], v[190:193], v[214:217], v[178:181]
	v_mfma_f32_16x16x32_bf16 v[60:63], v[190:193], v[218:221], v[60:63]
	v_mfma_f32_16x16x32_bf16 v[28:31], v[194:197], v[198:201], v[28:31]
	v_mfma_f32_16x16x32_bf16 v[36:39], v[194:197], v[202:205], v[36:39]
	v_mfma_f32_16x16x32_bf16 v[48:51], v[194:197], v[206:209], v[48:51]
	v_mfma_f32_16x16x32_bf16 v[76:79], v[194:197], v[210:213], v[76:79]
	v_mfma_f32_16x16x32_bf16 v[80:83], v[194:197], v[214:217], v[80:83]
	v_mfma_f32_16x16x32_bf16 v[64:67], v[194:197], v[218:221], v[64:67]
	s_barrier
; __device__ __forceinline__ void gemm_gates6(f32x4 (&acc)[4][6], const bf16_t* __restrict__ A, int lda,
;                                             const bf16_t* __restrict__ Bt, int ldb, int bstr, bf16_t* sA0, bf16_t* sB0,
;                                             const int tidx) {
;     ...
; #pragma unroll
;   for (int ks = 0; ks < 16; ks++) {
;     const bf16_t* sA_ = sA0 + (ks & 1) * BUFE;
;     const bf16_t* sB_ = sB0 + (ks & 1) * BUFE;
; #pragma unroll
;     for (int kk = 0; kk < 64; kk += 32) {
;       bf16x8 a[4], b[6];
; #pragma unroll
;       for (int i = 0; i < 4; i++) a[i] = *(const bf16x8*)(sA_ + (wm * 64 + i * 16 + l15) * GSTR + kk + quad * 8);
; #pragma unroll
;       for (int j = 0; j < 6; j++) b[j] = *(const bf16x8*)(sB_ + (wn * 96 + j * 16 + l15) * GSTR + kk + quad * 8);
;       bf16_t* dA_ = sA0 + ((ks + 1) & 1) * BUFE;
;       bf16_t* dB_ = sB0 + ((ks + 1) & 1) * BUFE;
; #pragma unroll
;       for (int i = 0; i < 4; i++) {
; #pragma unroll
;         for (int j = 0; j < 6; j++) acc[i][j] = __builtin_amdgcn_mfma_f32_16x16x32_bf16(a[i], b[j], acc[i][j], 0, 0, 0);
;         if (kk == 32 && i == 0 && ks + 2 < 16) {
;           W_LOAD((ks + 2) * 64);
;           __builtin_amdgcn_sched_barrier(0);
;         }
;         if (kk == 0 && ks + 1 < 16) {
;           *(u32x4*)(dA_ + (cr + 64 * i) * GSTR + ck * 8) = ra[i];
;           if (i < 3) *(u32x4*)(dB_ + (brow + i * 32) * GSTR + ck * 8) = rb[i];
;           __builtin_amdgcn_sched_barrier(0);
;         }
;       }
;       __builtin_amdgcn_sched_barrier(0);
;     }
;     if (ks + 1 < 16) __syncthreads();
;   }
	ds_read_b128 v[186:189], v124
	ds_read_b128 v[190:193], v22 offset:40960
	ds_read_b128 v[194:197], v124 offset:2560
	ds_read_b128 v[198:201], v22 offset:43520
	ds_read_b128 v[202:205], v22 offset:46080
	ds_read_b128 v[206:209], v22 offset:48640
	ds_read_b128 v[210:213], v22 offset:51200
	ds_read_b128 v[214:217], v22 offset:53760
	ds_read_b128 v[218:221], v124 offset:5120
	ds_read_b128 v[246:249], v124 offset:7680
	s_waitcnt lgkmcnt(8)
	v_mfma_f32_16x16x32_bf16 v[40:43], v[186:189], v[190:193], v[40:43]
	s_waitcnt vmcnt(6)
	ds_write_b128 v139, v[182:185]
	s_waitcnt vmcnt(2)
	ds_write_b128 v140, v[234:237]
	s_waitcnt lgkmcnt(8)
	v_mfma_f32_16x16x32_bf16 v[44:47], v[186:189], v[198:201], v[44:47]
	s_waitcnt lgkmcnt(7)
	v_mfma_f32_16x16x32_bf16 v[84:87], v[186:189], v[202:205], v[84:87]
	s_waitcnt lgkmcnt(6)
	v_mfma_f32_16x16x32_bf16 v[88:91], v[186:189], v[206:209], v[88:91]
	s_waitcnt lgkmcnt(5)
	v_mfma_f32_16x16x32_bf16 v[106:109], v[186:189], v[210:213], v[106:109]
	s_waitcnt lgkmcnt(4)
	v_mfma_f32_16x16x32_bf16 v[24:27], v[186:189], v[214:217], v[24:27]
	v_mfma_f32_16x16x32_bf16 v[52:55], v[194:197], v[190:193], v[52:55]
	ds_write_b128 v139, v[222:225] offset:10240
	s_waitcnt vmcnt(1)
	ds_write_b128 v140, v[238:241] offset:5120
	v_mfma_f32_16x16x32_bf16 v[68:71], v[194:197], v[198:201], v[68:71]
	v_mfma_f32_16x16x32_bf16 v[92:95], v[194:197], v[202:205], v[92:95]
	v_mfma_f32_16x16x32_bf16 v[110:113], v[194:197], v[206:209], v[110:113]
	v_mfma_f32_16x16x32_bf16 v[156:159], v[194:197], v[210:213], v[156:159]
	v_mfma_f32_16x16x32_bf16 v[32:35], v[194:197], v[214:217], v[32:35]
	s_waitcnt lgkmcnt(5)
	v_mfma_f32_16x16x32_bf16 v[56:59], v[218:221], v[190:193], v[56:59]
	ds_write_b128 v139, v[226:229] offset:20480
	s_waitcnt vmcnt(0)
	ds_write_b128 v140, v[242:245] offset:10240
	v_mfma_f32_16x16x32_bf16 v[72:75], v[218:221], v[198:201], v[72:75]
	v_mfma_f32_16x16x32_bf16 v[102:105], v[218:221], v[202:205], v[102:105]
	v_mfma_f32_16x16x32_bf16 v[174:177], v[218:221], v[206:209], v[174:177]
	v_mfma_f32_16x16x32_bf16 v[178:181], v[218:221], v[210:213], v[178:181]
	v_mfma_f32_16x16x32_bf16 v[60:63], v[218:221], v[214:217], v[60:63]
	s_waitcnt lgkmcnt(6)
	v_mfma_f32_16x16x32_bf16 v[28:31], v[246:249], v[190:193], v[28:31]
	ds_write_b128 v139, v[230:233] offset:30720
	v_mfma_f32_16x16x32_bf16 v[36:39], v[246:249], v[198:201], v[36:39]
	v_mfma_f32_16x16x32_bf16 v[48:51], v[246:249], v[202:205], v[48:51]
	v_mfma_f32_16x16x32_bf16 v[76:79], v[246:249], v[206:209], v[76:79]
	v_mfma_f32_16x16x32_bf16 v[80:83], v[246:249], v[210:213], v[80:83]
	v_mfma_f32_16x16x32_bf16 v[64:67], v[246:249], v[214:217], v[64:67]
	ds_read_b128 v[182:185], v124 offset:64
	ds_read_b128 v[186:189], v124 offset:2624
	ds_read_b128 v[190:193], v124 offset:5184
	ds_read_b128 v[194:197], v124 offset:7744
	ds_read_b128 v[198:201], v22 offset:41024
	ds_read_b128 v[202:205], v22 offset:43584
	ds_read_b128 v[206:209], v22 offset:46144
	ds_read_b128 v[210:213], v22 offset:48704
	ds_read_b128 v[214:217], v22 offset:51264
	ds_read_b128 v[218:221], v22 offset:53824
	s_waitcnt lgkmcnt(5)
	v_mfma_f32_16x16x32_bf16 v[40:43], v[182:185], v[198:201], v[40:43]
	s_waitcnt lgkmcnt(4)
	v_mfma_f32_16x16x32_bf16 v[44:47], v[182:185], v[202:205], v[44:47]
	s_waitcnt lgkmcnt(3)
	v_mfma_f32_16x16x32_bf16 v[84:87], v[182:185], v[206:209], v[84:87]
	s_waitcnt lgkmcnt(2)
	v_mfma_f32_16x16x32_bf16 v[88:91], v[182:185], v[210:213], v[88:91]
	s_waitcnt lgkmcnt(1)
	v_mfma_f32_16x16x32_bf16 v[106:109], v[182:185], v[214:217], v[106:109]
	s_waitcnt lgkmcnt(0)
	v_mfma_f32_16x16x32_bf16 v[24:27], v[182:185], v[218:221], v[24:27]
	global_load_dwordx4 v[182:185], v[8:9], off offset:768
	global_load_dwordx4 v[222:225], v[10:11], off offset:768
	global_load_dwordx4 v[226:229], v[12:13], off offset:768
	global_load_dwordx4 v[230:233], v[14:15], off offset:768
	global_load_dwordx4 v[234:237], v[16:17], off offset:768
	global_load_dwordx4 v[238:241], v[18:19], off offset:768
	global_load_dwordx4 v[242:245], v[20:21], off offset:768
	v_mfma_f32_16x16x32_bf16 v[52:55], v[186:189], v[198:201], v[52:55]
	v_mfma_f32_16x16x32_bf16 v[68:71], v[186:189], v[202:205], v[68:71]
	v_mfma_f32_16x16x32_bf16 v[92:95], v[186:189], v[206:209], v[92:95]
	v_mfma_f32_16x16x32_bf16 v[110:113], v[186:189], v[210:213], v[110:113]
	v_mfma_f32_16x16x32_bf16 v[156:159], v[186:189], v[214:217], v[156:159]
	v_mfma_f32_16x16x32_bf16 v[32:35], v[186:189], v[218:221], v[32:35]
	v_mfma_f32_16x16x32_bf16 v[56:59], v[190:193], v[198:201], v[56:59]
	v_mfma_f32_16x16x32_bf16 v[72:75], v[190:193], v[202:205], v[72:75]
	v_mfma_f32_16x16x32_bf16 v[102:105], v[190:193], v[206:209], v[102:105]
	v_mfma_f32_16x16x32_bf16 v[174:177], v[190:193], v[210:213], v[174:177]
	v_mfma_f32_16x16x32_bf16 v[178:181], v[190:193], v[214:217], v[178:181]
	v_mfma_f32_16x16x32_bf16 v[60:63], v[190:193], v[218:221], v[60:63]
	v_mfma_f32_16x16x32_bf16 v[28:31], v[194:197], v[198:201], v[28:31]
	v_mfma_f32_16x16x32_bf16 v[36:39], v[194:197], v[202:205], v[36:39]
	v_mfma_f32_16x16x32_bf16 v[48:51], v[194:197], v[206:209], v[48:51]
	v_mfma_f32_16x16x32_bf16 v[76:79], v[194:197], v[210:213], v[76:79]
	v_mfma_f32_16x16x32_bf16 v[80:83], v[194:197], v[214:217], v[80:83]
	v_mfma_f32_16x16x32_bf16 v[64:67], v[194:197], v[218:221], v[64:67]
	s_barrier
; __device__ __forceinline__ void gemm_gates6(f32x4 (&acc)[4][6], const bf16_t* __restrict__ A, int lda,
;                                             const bf16_t* __restrict__ Bt, int ldb, int bstr, bf16_t* sA0, bf16_t* sB0,
;                                             const int tidx) {
;     ...
; #pragma unroll
;   for (int ks = 0; ks < 16; ks++) {
;     const bf16_t* sA_ = sA0 + (ks & 1) * BUFE;
;     const bf16_t* sB_ = sB0 + (ks & 1) * BUFE;
; #pragma unroll
;     for (int kk = 0; kk < 64; kk += 32) {
;       bf16x8 a[4], b[6];
; #pragma unroll
;       for (int i = 0; i < 4; i++) a[i] = *(const bf16x8*)(sA_ + (wm * 64 + i * 16 + l15) * GSTR + kk + quad * 8);
; #pragma unroll
;       for (int j = 0; j < 6; j++) b[j] = *(const bf16x8*)(sB_ + (wn * 96 + j * 16 + l15) * GSTR + kk + quad * 8);
;       bf16_t* dA_ = sA0 + ((ks + 1) & 1) * BUFE;
;       bf16_t* dB_ = sB0 + ((ks + 1) & 1) * BUFE;
; #pragma unroll
;       for (int i = 0; i < 4; i++) {
; #pragma unroll
;         for (int j = 0; j < 6; j++) acc[i][j] = __builtin_amdgcn_mfma_f32_16x16x32_bf16(a[i], b[j], acc[i][j], 0, 0, 0);
;         if (kk == 32 && i == 0 && ks + 2 < 16) {
;           W_LOAD((ks + 2) * 64);
;           __builtin_amdgcn_sched_barrier(0);
;         }
;         if (kk == 0 && ks + 1 < 16) {
;           *(u32x4*)(dA_ + (cr + 64 * i) * GSTR + ck * 8) = ra[i];
;           if (i < 3) *(u32x4*)(dB_ + (brow + i * 32) * GSTR + ck * 8) = rb[i];
;           __builtin_amdgcn_sched_barrier(0);
;         }
;       }
;       __builtin_amdgcn_sched_barrier(0);
;     }
;     if (ks + 1 < 16) __syncthreads();
;   }
	ds_read_b128 v[186:189], v141
	ds_read_b128 v[190:193], v142
	ds_read_b128 v[194:197], v141 offset:2560
	ds_read_b128 v[198:201], v142 offset:2560
	ds_read_b128 v[202:205], v142 offset:5120
	ds_read_b128 v[206:209], v142 offset:7680
	ds_read_b128 v[210:213], v142 offset:10240
	ds_read_b128 v[214:217], v142 offset:12800
	ds_read_b128 v[218:221], v141 offset:5120
	ds_read_b128 v[246:249], v141 offset:7680
	s_waitcnt lgkmcnt(8)
	v_mfma_f32_16x16x32_bf16 v[40:43], v[186:189], v[190:193], v[40:43]
	s_waitcnt vmcnt(6)
	ds_write_b128 v125, v[182:185]
	s_waitcnt vmcnt(2)
	ds_write_b128 v23, v[234:237] offset:40960
	s_waitcnt lgkmcnt(8)
	v_mfma_f32_16x16x32_bf16 v[44:47], v[186:189], v[198:201], v[44:47]
	s_waitcnt lgkmcnt(7)
	v_mfma_f32_16x16x32_bf16 v[84:87], v[186:189], v[202:205], v[84:87]
	s_waitcnt lgkmcnt(6)
	v_mfma_f32_16x16x32_bf16 v[88:91], v[186:189], v[206:209], v[88:91]
	s_waitcnt lgkmcnt(5)
	v_mfma_f32_16x16x32_bf16 v[106:109], v[186:189], v[210:213], v[106:109]
	s_waitcnt lgkmcnt(4)
	v_mfma_f32_16x16x32_bf16 v[24:27], v[186:189], v[214:217], v[24:27]
	v_mfma_f32_16x16x32_bf16 v[52:55], v[194:197], v[190:193], v[52:55]
	ds_write_b128 v125, v[222:225] offset:10240
	s_waitcnt vmcnt(1)
	ds_write_b128 v23, v[238:241] offset:46080
	v_mfma_f32_16x16x32_bf16 v[68:71], v[194:197], v[198:201], v[68:71]
	v_mfma_f32_16x16x32_bf16 v[92:95], v[194:197], v[202:205], v[92:95]
	v_mfma_f32_16x16x32_bf16 v[110:113], v[194:197], v[206:209], v[110:113]
	v_mfma_f32_16x16x32_bf16 v[156:159], v[194:197], v[210:213], v[156:159]
	v_mfma_f32_16x16x32_bf16 v[32:35], v[194:197], v[214:217], v[32:35]
	s_waitcnt lgkmcnt(5)
	v_mfma_f32_16x16x32_bf16 v[56:59], v[218:221], v[190:193], v[56:59]
	ds_write_b128 v125, v[226:229] offset:20480
	s_waitcnt vmcnt(0)
	ds_write_b128 v23, v[242:245] offset:51200
	v_mfma_f32_16x16x32_bf16 v[72:75], v[218:221], v[198:201], v[72:75]
	v_mfma_f32_16x16x32_bf16 v[102:105], v[218:221], v[202:205], v[102:105]
	v_mfma_f32_16x16x32_bf16 v[174:177], v[218:221], v[206:209], v[174:177]
	v_mfma_f32_16x16x32_bf16 v[178:181], v[218:221], v[210:213], v[178:181]
	v_mfma_f32_16x16x32_bf16 v[60:63], v[218:221], v[214:217], v[60:63]
	s_waitcnt lgkmcnt(6)
	v_mfma_f32_16x16x32_bf16 v[28:31], v[246:249], v[190:193], v[28:31]
	ds_write_b128 v125, v[230:233] offset:30720
	v_mfma_f32_16x16x32_bf16 v[36:39], v[246:249], v[198:201], v[36:39]
	v_mfma_f32_16x16x32_bf16 v[48:51], v[246:249], v[202:205], v[48:51]
	v_mfma_f32_16x16x32_bf16 v[76:79], v[246:249], v[206:209], v[76:79]
	v_mfma_f32_16x16x32_bf16 v[80:83], v[246:249], v[210:213], v[80:83]
	v_mfma_f32_16x16x32_bf16 v[64:67], v[246:249], v[214:217], v[64:67]
	ds_read_b128 v[182:185], v143
	ds_read_b128 v[186:189], v143 offset:2560
	ds_read_b128 v[190:193], v143 offset:5120
	ds_read_b128 v[194:197], v143 offset:7680
	ds_read_b128 v[198:201], v144
	ds_read_b128 v[202:205], v144 offset:2560
	ds_read_b128 v[206:209], v144 offset:5120
	ds_read_b128 v[210:213], v144 offset:7680
	ds_read_b128 v[214:217], v144 offset:10240
	ds_read_b128 v[218:221], v144 offset:12800
	s_waitcnt lgkmcnt(5)
	v_mfma_f32_16x16x32_bf16 v[40:43], v[182:185], v[198:201], v[40:43]
	s_waitcnt lgkmcnt(4)
	v_mfma_f32_16x16x32_bf16 v[44:47], v[182:185], v[202:205], v[44:47]
	s_waitcnt lgkmcnt(3)
	v_mfma_f32_16x16x32_bf16 v[84:87], v[182:185], v[206:209], v[84:87]
	s_waitcnt lgkmcnt(2)
	v_mfma_f32_16x16x32_bf16 v[88:91], v[182:185], v[210:213], v[88:91]
	s_waitcnt lgkmcnt(1)
	v_mfma_f32_16x16x32_bf16 v[106:109], v[182:185], v[214:217], v[106:109]
	s_waitcnt lgkmcnt(0)
	v_mfma_f32_16x16x32_bf16 v[24:27], v[182:185], v[218:221], v[24:27]
	global_load_dwordx4 v[182:185], v[8:9], off offset:896
	global_load_dwordx4 v[222:225], v[10:11], off offset:896
	global_load_dwordx4 v[226:229], v[12:13], off offset:896
	global_load_dwordx4 v[230:233], v[14:15], off offset:896
	global_load_dwordx4 v[234:237], v[16:17], off offset:896
	global_load_dwordx4 v[238:241], v[18:19], off offset:896
	global_load_dwordx4 v[242:245], v[20:21], off offset:896
	v_mfma_f32_16x16x32_bf16 v[52:55], v[186:189], v[198:201], v[52:55]
	v_mfma_f32_16x16x32_bf16 v[68:71], v[186:189], v[202:205], v[68:71]
	v_mfma_f32_16x16x32_bf16 v[92:95], v[186:189], v[206:209], v[92:95]
	v_mfma_f32_16x16x32_bf16 v[110:113], v[186:189], v[210:213], v[110:113]
	v_mfma_f32_16x16x32_bf16 v[156:159], v[186:189], v[214:217], v[156:159]
	v_mfma_f32_16x16x32_bf16 v[32:35], v[186:189], v[218:221], v[32:35]
	v_mfma_f32_16x16x32_bf16 v[56:59], v[190:193], v[198:201], v[56:59]
	v_mfma_f32_16x16x32_bf16 v[72:75], v[190:193], v[202:205], v[72:75]
	v_mfma_f32_16x16x32_bf16 v[102:105], v[190:193], v[206:209], v[102:105]
	v_mfma_f32_16x16x32_bf16 v[174:177], v[190:193], v[210:213], v[174:177]
	v_mfma_f32_16x16x32_bf16 v[178:181], v[190:193], v[214:217], v[178:181]
	v_mfma_f32_16x16x32_bf16 v[60:63], v[190:193], v[218:221], v[60:63]
	v_mfma_f32_16x16x32_bf16 v[28:31], v[194:197], v[198:201], v[28:31]
	v_mfma_f32_16x16x32_bf16 v[36:39], v[194:197], v[202:205], v[36:39]
	v_mfma_f32_16x16x32_bf16 v[48:51], v[194:197], v[206:209], v[48:51]
	v_mfma_f32_16x16x32_bf16 v[76:79], v[194:197], v[210:213], v[76:79]
	v_mfma_f32_16x16x32_bf16 v[80:83], v[194:197], v[214:217], v[80:83]
	v_mfma_f32_16x16x32_bf16 v[64:67], v[194:197], v[218:221], v[64:67]
	s_barrier
; __device__ __forceinline__ void gemm_gates6(f32x4 (&acc)[4][6], const bf16_t* __restrict__ A, int lda,
;                                             const bf16_t* __restrict__ Bt, int ldb, int bstr, bf16_t* sA0, bf16_t* sB0,
;                                             const int tidx) {
;     ...
; #pragma unroll
;   for (int ks = 0; ks < 16; ks++) {
;     const bf16_t* sA_ = sA0 + (ks & 1) * BUFE;
;     const bf16_t* sB_ = sB0 + (ks & 1) * BUFE;
; #pragma unroll
;     for (int kk = 0; kk < 64; kk += 32) {
;       bf16x8 a[4], b[6];
; #pragma unroll
;       for (int i = 0; i < 4; i++) a[i] = *(const bf16x8*)(sA_ + (wm * 64 + i * 16 + l15) * GSTR + kk + quad * 8);
; #pragma unroll
;       for (int j = 0; j < 6; j++) b[j] = *(const bf16x8*)(sB_ + (wn * 96 + j * 16 + l15) * GSTR + kk + quad * 8);
;       bf16_t* dA_ = sA0 + ((ks + 1) & 1) * BUFE;
;       bf16_t* dB_ = sB0 + ((ks + 1) & 1) * BUFE;
; #pragma unroll
;       for (int i = 0; i < 4; i++) {
; #pragma unroll
;         for (int j = 0; j < 6; j++) acc[i][j] = __builtin_amdgcn_mfma_f32_16x16x32_bf16(a[i], b[j], acc[i][j], 0, 0, 0);
;         if (kk == 32 && i == 0 && ks + 2 < 16) {
;           W_LOAD((ks + 2) * 64);
;           __builtin_amdgcn_sched_barrier(0);
;         }
;         if (kk == 0 && ks + 1 < 16) {
;           *(u32x4*)(dA_ + (cr + 64 * i) * GSTR + ck * 8) = ra[i];
;           if (i < 3) *(u32x4*)(dB_ + (brow + i * 32) * GSTR + ck * 8) = rb[i];
;           __builtin_amdgcn_sched_barrier(0);
;         }
;       }
;       __builtin_amdgcn_sched_barrier(0);
;     }
;     if (ks + 1 < 16) __syncthreads();
;   }
	ds_read_b128 v[186:189], v124
	ds_read_b128 v[190:193], v22 offset:40960
	ds_read_b128 v[194:197], v124 offset:2560
	ds_read_b128 v[198:201], v22 offset:43520
	ds_read_b128 v[202:205], v22 offset:46080
	ds_read_b128 v[206:209], v22 offset:48640
	ds_read_b128 v[210:213], v22 offset:51200
	ds_read_b128 v[214:217], v22 offset:53760
	ds_read_b128 v[218:221], v124 offset:5120
	ds_read_b128 v[246:249], v124 offset:7680
	s_waitcnt lgkmcnt(8)
	v_mfma_f32_16x16x32_bf16 v[40:43], v[186:189], v[190:193], v[40:43]
	s_waitcnt vmcnt(6)
	ds_write_b128 v139, v[182:185]
	s_waitcnt vmcnt(2)
	ds_write_b128 v140, v[234:237]
	s_waitcnt lgkmcnt(8)
	v_mfma_f32_16x16x32_bf16 v[44:47], v[186:189], v[198:201], v[44:47]
	s_waitcnt lgkmcnt(7)
	v_mfma_f32_16x16x32_bf16 v[84:87], v[186:189], v[202:205], v[84:87]
	s_waitcnt lgkmcnt(6)
	v_mfma_f32_16x16x32_bf16 v[88:91], v[186:189], v[206:209], v[88:91]
	s_waitcnt lgkmcnt(5)
	v_mfma_f32_16x16x32_bf16 v[106:109], v[186:189], v[210:213], v[106:109]
	s_waitcnt lgkmcnt(4)
	v_mfma_f32_16x16x32_bf16 v[24:27], v[186:189], v[214:217], v[24:27]
	v_mfma_f32_16x16x32_bf16 v[52:55], v[194:197], v[190:193], v[52:55]
	ds_write_b128 v139, v[222:225] offset:10240
	s_waitcnt vmcnt(1)
	ds_write_b128 v140, v[238:241] offset:5120
	v_mfma_f32_16x16x32_bf16 v[68:71], v[194:197], v[198:201], v[68:71]
	v_mfma_f32_16x16x32_bf16 v[92:95], v[194:197], v[202:205], v[92:95]
	v_mfma_f32_16x16x32_bf16 v[110:113], v[194:197], v[206:209], v[110:113]
	v_mfma_f32_16x16x32_bf16 v[156:159], v[194:197], v[210:213], v[156:159]
	v_mfma_f32_16x16x32_bf16 v[32:35], v[194:197], v[214:217], v[32:35]
	s_waitcnt lgkmcnt(5)
	v_mfma_f32_16x16x32_bf16 v[56:59], v[218:221], v[190:193], v[56:59]
	ds_write_b128 v139, v[226:229] offset:20480
	s_waitcnt vmcnt(0)
	ds_write_b128 v140, v[242:245] offset:10240
	v_mfma_f32_16x16x32_bf16 v[72:75], v[218:221], v[198:201], v[72:75]
	v_mfma_f32_16x16x32_bf16 v[102:105], v[218:221], v[202:205], v[102:105]
	v_mfma_f32_16x16x32_bf16 v[174:177], v[218:221], v[206:209], v[174:177]
	v_mfma_f32_16x16x32_bf16 v[178:181], v[218:221], v[210:213], v[178:181]
	v_mfma_f32_16x16x32_bf16 v[60:63], v[218:221], v[214:217], v[60:63]
	s_waitcnt lgkmcnt(6)
	v_mfma_f32_16x16x32_bf16 v[28:31], v[246:249], v[190:193], v[28:31]
	ds_write_b128 v139, v[230:233] offset:30720
	v_mfma_f32_16x16x32_bf16 v[36:39], v[246:249], v[198:201], v[36:39]
	v_mfma_f32_16x16x32_bf16 v[48:51], v[246:249], v[202:205], v[48:51]
	v_mfma_f32_16x16x32_bf16 v[76:79], v[246:249], v[206:209], v[76:79]
	v_mfma_f32_16x16x32_bf16 v[80:83], v[246:249], v[210:213], v[80:83]
	v_mfma_f32_16x16x32_bf16 v[64:67], v[246:249], v[214:217], v[64:67]
	ds_read_b128 v[182:185], v124 offset:64
	ds_read_b128 v[186:189], v124 offset:2624
	ds_read_b128 v[190:193], v124 offset:5184
	ds_read_b128 v[194:197], v124 offset:7744
	ds_read_b128 v[198:201], v22 offset:41024
	ds_read_b128 v[202:205], v22 offset:43584
	ds_read_b128 v[206:209], v22 offset:46144
	ds_read_b128 v[210:213], v22 offset:48704
	ds_read_b128 v[214:217], v22 offset:51264
	ds_read_b128 v[218:221], v22 offset:53824
	s_waitcnt lgkmcnt(5)
	v_mfma_f32_16x16x32_bf16 v[40:43], v[182:185], v[198:201], v[40:43]
	s_waitcnt lgkmcnt(4)
	v_mfma_f32_16x16x32_bf16 v[44:47], v[182:185], v[202:205], v[44:47]
	s_waitcnt lgkmcnt(3)
	v_mfma_f32_16x16x32_bf16 v[84:87], v[182:185], v[206:209], v[84:87]
	s_waitcnt lgkmcnt(2)
	v_mfma_f32_16x16x32_bf16 v[88:91], v[182:185], v[210:213], v[88:91]
	s_waitcnt lgkmcnt(1)
	v_mfma_f32_16x16x32_bf16 v[106:109], v[182:185], v[214:217], v[106:109]
	s_waitcnt lgkmcnt(0)
	v_mfma_f32_16x16x32_bf16 v[24:27], v[182:185], v[218:221], v[24:27]
	global_load_dwordx4 v[182:185], v[8:9], off offset:1024
	global_load_dwordx4 v[222:225], v[10:11], off offset:1024
	global_load_dwordx4 v[226:229], v[12:13], off offset:1024
	global_load_dwordx4 v[230:233], v[14:15], off offset:1024
	global_load_dwordx4 v[234:237], v[16:17], off offset:1024
	global_load_dwordx4 v[238:241], v[18:19], off offset:1024
	global_load_dwordx4 v[242:245], v[20:21], off offset:1024
	v_mfma_f32_16x16x32_bf16 v[52:55], v[186:189], v[198:201], v[52:55]
	v_mfma_f32_16x16x32_bf16 v[68:71], v[186:189], v[202:205], v[68:71]
	v_mfma_f32_16x16x32_bf16 v[92:95], v[186:189], v[206:209], v[92:95]
	v_mfma_f32_16x16x32_bf16 v[110:113], v[186:189], v[210:213], v[110:113]
	v_mfma_f32_16x16x32_bf16 v[156:159], v[186:189], v[214:217], v[156:159]
	v_mfma_f32_16x16x32_bf16 v[32:35], v[186:189], v[218:221], v[32:35]
	v_mfma_f32_16x16x32_bf16 v[56:59], v[190:193], v[198:201], v[56:59]
	v_mfma_f32_16x16x32_bf16 v[72:75], v[190:193], v[202:205], v[72:75]
	v_mfma_f32_16x16x32_bf16 v[102:105], v[190:193], v[206:209], v[102:105]
	v_mfma_f32_16x16x32_bf16 v[174:177], v[190:193], v[210:213], v[174:177]
	v_mfma_f32_16x16x32_bf16 v[178:181], v[190:193], v[214:217], v[178:181]
	v_mfma_f32_16x16x32_bf16 v[60:63], v[190:193], v[218:221], v[60:63]
	v_mfma_f32_16x16x32_bf16 v[28:31], v[194:197], v[198:201], v[28:31]
	v_mfma_f32_16x16x32_bf16 v[36:39], v[194:197], v[202:205], v[36:39]
	v_mfma_f32_16x16x32_bf16 v[48:51], v[194:197], v[206:209], v[48:51]
	v_mfma_f32_16x16x32_bf16 v[76:79], v[194:197], v[210:213], v[76:79]
	v_mfma_f32_16x16x32_bf16 v[80:83], v[194:197], v[214:217], v[80:83]
	v_mfma_f32_16x16x32_bf16 v[64:67], v[194:197], v[218:221], v[64:67]
	s_barrier
; __device__ __forceinline__ void gemm_gates6(f32x4 (&acc)[4][6], const bf16_t* __restrict__ A, int lda,
;                                             const bf16_t* __restrict__ Bt, int ldb, int bstr, bf16_t* sA0, bf16_t* sB0,
;                                             const int tidx) {
;     ...
; #pragma unroll
;   for (int ks = 0; ks < 16; ks++) {
;     const bf16_t* sA_ = sA0 + (ks & 1) * BUFE;
;     const bf16_t* sB_ = sB0 + (ks & 1) * BUFE;
; #pragma unroll
;     for (int kk = 0; kk < 64; kk += 32) {
;       bf16x8 a[4], b[6];
; #pragma unroll
;       for (int i = 0; i < 4; i++) a[i] = *(const bf16x8*)(sA_ + (wm * 64 + i * 16 + l15) * GSTR + kk + quad * 8);
; #pragma unroll
;       for (int j = 0; j < 6; j++) b[j] = *(const bf16x8*)(sB_ + (wn * 96 + j * 16 + l15) * GSTR + kk + quad * 8);
;       bf16_t* dA_ = sA0 + ((ks + 1) & 1) * BUFE;
;       bf16_t* dB_ = sB0 + ((ks + 1) & 1) * BUFE;
; #pragma unroll
;       for (int i = 0; i < 4; i++) {
; #pragma unroll
;         for (int j = 0; j < 6; j++) acc[i][j] = __builtin_amdgcn_mfma_f32_16x16x32_bf16(a[i], b[j], acc[i][j], 0, 0, 0);
;         if (kk == 32 && i == 0 && ks + 2 < 16) {
;           W_LOAD((ks + 2) * 64);
;           __builtin_amdgcn_sched_barrier(0);
;         }
;         if (kk == 0 && ks + 1 < 16) {
;           *(u32x4*)(dA_ + (cr + 64 * i) * GSTR + ck * 8) = ra[i];
;           if (i < 3) *(u32x4*)(dB_ + (brow + i * 32) * GSTR + ck * 8) = rb[i];
;           __builtin_amdgcn_sched_barrier(0);
;         }
;       }
;       __builtin_amdgcn_sched_barrier(0);
;     }
;     if (ks + 1 < 16) __syncthreads();
;   }
	ds_read_b128 v[186:189], v141
	ds_read_b128 v[190:193], v142
	ds_read_b128 v[194:197], v141 offset:2560
	ds_read_b128 v[198:201], v142 offset:2560
	ds_read_b128 v[202:205], v142 offset:5120
	ds_read_b128 v[206:209], v142 offset:7680
	ds_read_b128 v[210:213], v142 offset:10240
	ds_read_b128 v[214:217], v142 offset:12800
	ds_read_b128 v[218:221], v141 offset:5120
	ds_read_b128 v[246:249], v141 offset:7680
	s_waitcnt lgkmcnt(8)
	v_mfma_f32_16x16x32_bf16 v[40:43], v[186:189], v[190:193], v[40:43]
	s_waitcnt vmcnt(6)
	ds_write_b128 v125, v[182:185]
	s_waitcnt vmcnt(2)
	ds_write_b128 v23, v[234:237] offset:40960
	s_waitcnt lgkmcnt(8)
	v_mfma_f32_16x16x32_bf16 v[44:47], v[186:189], v[198:201], v[44:47]
	s_waitcnt lgkmcnt(7)
	v_mfma_f32_16x16x32_bf16 v[84:87], v[186:189], v[202:205], v[84:87]
	s_waitcnt lgkmcnt(6)
	v_mfma_f32_16x16x32_bf16 v[88:91], v[186:189], v[206:209], v[88:91]
	s_waitcnt lgkmcnt(5)
	v_mfma_f32_16x16x32_bf16 v[106:109], v[186:189], v[210:213], v[106:109]
	s_waitcnt lgkmcnt(4)
	v_mfma_f32_16x16x32_bf16 v[24:27], v[186:189], v[214:217], v[24:27]
	v_mfma_f32_16x16x32_bf16 v[52:55], v[194:197], v[190:193], v[52:55]
	ds_write_b128 v125, v[222:225] offset:10240
	s_waitcnt vmcnt(1)
	ds_write_b128 v23, v[238:241] offset:46080
	v_mfma_f32_16x16x32_bf16 v[68:71], v[194:197], v[198:201], v[68:71]
	v_mfma_f32_16x16x32_bf16 v[92:95], v[194:197], v[202:205], v[92:95]
	v_mfma_f32_16x16x32_bf16 v[110:113], v[194:197], v[206:209], v[110:113]
	v_mfma_f32_16x16x32_bf16 v[156:159], v[194:197], v[210:213], v[156:159]
	v_mfma_f32_16x16x32_bf16 v[32:35], v[194:197], v[214:217], v[32:35]
	s_waitcnt lgkmcnt(5)
	v_mfma_f32_16x16x32_bf16 v[56:59], v[218:221], v[190:193], v[56:59]
	ds_write_b128 v125, v[226:229] offset:20480
	s_waitcnt vmcnt(0)
	ds_write_b128 v23, v[242:245] offset:51200
	v_mfma_f32_16x16x32_bf16 v[72:75], v[218:221], v[198:201], v[72:75]
	v_mfma_f32_16x16x32_bf16 v[102:105], v[218:221], v[202:205], v[102:105]
	v_mfma_f32_16x16x32_bf16 v[174:177], v[218:221], v[206:209], v[174:177]
	v_mfma_f32_16x16x32_bf16 v[178:181], v[218:221], v[210:213], v[178:181]
	v_mfma_f32_16x16x32_bf16 v[60:63], v[218:221], v[214:217], v[60:63]
	s_waitcnt lgkmcnt(6)
	v_mfma_f32_16x16x32_bf16 v[28:31], v[246:249], v[190:193], v[28:31]
	ds_write_b128 v125, v[230:233] offset:30720
	v_mfma_f32_16x16x32_bf16 v[36:39], v[246:249], v[198:201], v[36:39]
	v_mfma_f32_16x16x32_bf16 v[48:51], v[246:249], v[202:205], v[48:51]
	v_mfma_f32_16x16x32_bf16 v[76:79], v[246:249], v[206:209], v[76:79]
	v_mfma_f32_16x16x32_bf16 v[80:83], v[246:249], v[210:213], v[80:83]
	v_mfma_f32_16x16x32_bf16 v[64:67], v[246:249], v[214:217], v[64:67]
	ds_read_b128 v[182:185], v143
	ds_read_b128 v[186:189], v143 offset:2560
	ds_read_b128 v[190:193], v143 offset:5120
	ds_read_b128 v[194:197], v143 offset:7680
	ds_read_b128 v[198:201], v144
	ds_read_b128 v[202:205], v144 offset:2560
	ds_read_b128 v[206:209], v144 offset:5120
	ds_read_b128 v[210:213], v144 offset:7680
	ds_read_b128 v[214:217], v144 offset:10240
	ds_read_b128 v[218:221], v144 offset:12800
	s_waitcnt lgkmcnt(5)
	v_mfma_f32_16x16x32_bf16 v[40:43], v[182:185], v[198:201], v[40:43]
	s_waitcnt lgkmcnt(4)
	v_mfma_f32_16x16x32_bf16 v[44:47], v[182:185], v[202:205], v[44:47]
	s_waitcnt lgkmcnt(3)
	v_mfma_f32_16x16x32_bf16 v[84:87], v[182:185], v[206:209], v[84:87]
	s_waitcnt lgkmcnt(2)
	v_mfma_f32_16x16x32_bf16 v[88:91], v[182:185], v[210:213], v[88:91]
	s_waitcnt lgkmcnt(1)
	v_mfma_f32_16x16x32_bf16 v[106:109], v[182:185], v[214:217], v[106:109]
	s_waitcnt lgkmcnt(0)
	v_mfma_f32_16x16x32_bf16 v[24:27], v[182:185], v[218:221], v[24:27]
	global_load_dwordx4 v[182:185], v[8:9], off offset:1152
	global_load_dwordx4 v[222:225], v[10:11], off offset:1152
	global_load_dwordx4 v[226:229], v[12:13], off offset:1152
	global_load_dwordx4 v[230:233], v[14:15], off offset:1152
	global_load_dwordx4 v[234:237], v[16:17], off offset:1152
	global_load_dwordx4 v[238:241], v[18:19], off offset:1152
	global_load_dwordx4 v[242:245], v[20:21], off offset:1152
	v_mfma_f32_16x16x32_bf16 v[52:55], v[186:189], v[198:201], v[52:55]
	v_mfma_f32_16x16x32_bf16 v[68:71], v[186:189], v[202:205], v[68:71]
	v_mfma_f32_16x16x32_bf16 v[92:95], v[186:189], v[206:209], v[92:95]
	v_mfma_f32_16x16x32_bf16 v[110:113], v[186:189], v[210:213], v[110:113]
	v_mfma_f32_16x16x32_bf16 v[156:159], v[186:189], v[214:217], v[156:159]
	v_mfma_f32_16x16x32_bf16 v[32:35], v[186:189], v[218:221], v[32:35]
	v_mfma_f32_16x16x32_bf16 v[56:59], v[190:193], v[198:201], v[56:59]
	v_mfma_f32_16x16x32_bf16 v[72:75], v[190:193], v[202:205], v[72:75]
	v_mfma_f32_16x16x32_bf16 v[102:105], v[190:193], v[206:209], v[102:105]
	v_mfma_f32_16x16x32_bf16 v[174:177], v[190:193], v[210:213], v[174:177]
	v_mfma_f32_16x16x32_bf16 v[178:181], v[190:193], v[214:217], v[178:181]
	v_mfma_f32_16x16x32_bf16 v[60:63], v[190:193], v[218:221], v[60:63]
	v_mfma_f32_16x16x32_bf16 v[28:31], v[194:197], v[198:201], v[28:31]
	v_mfma_f32_16x16x32_bf16 v[36:39], v[194:197], v[202:205], v[36:39]
	v_mfma_f32_16x16x32_bf16 v[48:51], v[194:197], v[206:209], v[48:51]
	v_mfma_f32_16x16x32_bf16 v[76:79], v[194:197], v[210:213], v[76:79]
	v_mfma_f32_16x16x32_bf16 v[80:83], v[194:197], v[214:217], v[80:83]
	v_mfma_f32_16x16x32_bf16 v[64:67], v[194:197], v[218:221], v[64:67]
	s_barrier
; __device__ __forceinline__ void gemm_gates6(f32x4 (&acc)[4][6], const bf16_t* __restrict__ A, int lda,
;                                             const bf16_t* __restrict__ Bt, int ldb, int bstr, bf16_t* sA0, bf16_t* sB0,
;                                             const int tidx) {
;     ...
; #pragma unroll
;   for (int ks = 0; ks < 16; ks++) {
;     const bf16_t* sA_ = sA0 + (ks & 1) * BUFE;
;     const bf16_t* sB_ = sB0 + (ks & 1) * BUFE;
; #pragma unroll
;     for (int kk = 0; kk < 64; kk += 32) {
;       bf16x8 a[4], b[6];
; #pragma unroll
;       for (int i = 0; i < 4; i++) a[i] = *(const bf16x8*)(sA_ + (wm * 64 + i * 16 + l15) * GSTR + kk + quad * 8);
; #pragma unroll
;       for (int j = 0; j < 6; j++) b[j] = *(const bf16x8*)(sB_ + (wn * 96 + j * 16 + l15) * GSTR + kk + quad * 8);
;       bf16_t* dA_ = sA0 + ((ks + 1) & 1) * BUFE;
;       bf16_t* dB_ = sB0 + ((ks + 1) & 1) * BUFE;
; #pragma unroll
;       for (int i = 0; i < 4; i++) {
; #pragma unroll
;         for (int j = 0; j < 6; j++) acc[i][j] = __builtin_amdgcn_mfma_f32_16x16x32_bf16(a[i], b[j], acc[i][j], 0, 0, 0);
;         if (kk == 32 && i == 0 && ks + 2 < 16) {
;           W_LOAD((ks + 2) * 64);
;           __builtin_amdgcn_sched_barrier(0);
;         }
;         if (kk == 0 && ks + 1 < 16) {
;           *(u32x4*)(dA_ + (cr + 64 * i) * GSTR + ck * 8) = ra[i];
;           if (i < 3) *(u32x4*)(dB_ + (brow + i * 32) * GSTR + ck * 8) = rb[i];
;           __builtin_amdgcn_sched_barrier(0);
;         }
;       }
;       __builtin_amdgcn_sched_barrier(0);
;     }
;     if (ks + 1 < 16) __syncthreads();
;   }
	ds_read_b128 v[186:189], v124
	ds_read_b128 v[190:193], v22 offset:40960
	ds_read_b128 v[194:197], v124 offset:2560
	ds_read_b128 v[198:201], v22 offset:43520
	ds_read_b128 v[202:205], v22 offset:46080
	ds_read_b128 v[206:209], v22 offset:48640
	ds_read_b128 v[210:213], v22 offset:51200
	ds_read_b128 v[214:217], v22 offset:53760
	ds_read_b128 v[218:221], v124 offset:5120
	ds_read_b128 v[246:249], v124 offset:7680
	s_waitcnt lgkmcnt(8)
	v_mfma_f32_16x16x32_bf16 v[40:43], v[186:189], v[190:193], v[40:43]
	s_waitcnt vmcnt(6)
	ds_write_b128 v139, v[182:185]
	s_waitcnt vmcnt(2)
	ds_write_b128 v140, v[234:237]
	s_waitcnt lgkmcnt(8)
	v_mfma_f32_16x16x32_bf16 v[44:47], v[186:189], v[198:201], v[44:47]
	s_waitcnt lgkmcnt(7)
	v_mfma_f32_16x16x32_bf16 v[84:87], v[186:189], v[202:205], v[84:87]
	s_waitcnt lgkmcnt(6)
	v_mfma_f32_16x16x32_bf16 v[88:91], v[186:189], v[206:209], v[88:91]
	s_waitcnt lgkmcnt(5)
	v_mfma_f32_16x16x32_bf16 v[106:109], v[186:189], v[210:213], v[106:109]
	s_waitcnt lgkmcnt(4)
	v_mfma_f32_16x16x32_bf16 v[24:27], v[186:189], v[214:217], v[24:27]
	v_mfma_f32_16x16x32_bf16 v[52:55], v[194:197], v[190:193], v[52:55]
	ds_write_b128 v139, v[222:225] offset:10240
	s_waitcnt vmcnt(1)
	ds_write_b128 v140, v[238:241] offset:5120
	v_mfma_f32_16x16x32_bf16 v[68:71], v[194:197], v[198:201], v[68:71]
	v_mfma_f32_16x16x32_bf16 v[92:95], v[194:197], v[202:205], v[92:95]
	v_mfma_f32_16x16x32_bf16 v[110:113], v[194:197], v[206:209], v[110:113]
	v_mfma_f32_16x16x32_bf16 v[156:159], v[194:197], v[210:213], v[156:159]
	v_mfma_f32_16x16x32_bf16 v[32:35], v[194:197], v[214:217], v[32:35]
	s_waitcnt lgkmcnt(5)
	v_mfma_f32_16x16x32_bf16 v[56:59], v[218:221], v[190:193], v[56:59]
	ds_write_b128 v139, v[226:229] offset:20480
	s_waitcnt vmcnt(0)
	ds_write_b128 v140, v[242:245] offset:10240
	v_mfma_f32_16x16x32_bf16 v[72:75], v[218:221], v[198:201], v[72:75]
	v_mfma_f32_16x16x32_bf16 v[102:105], v[218:221], v[202:205], v[102:105]
	v_mfma_f32_16x16x32_bf16 v[174:177], v[218:221], v[206:209], v[174:177]
	v_mfma_f32_16x16x32_bf16 v[178:181], v[218:221], v[210:213], v[178:181]
	v_mfma_f32_16x16x32_bf16 v[60:63], v[218:221], v[214:217], v[60:63]
	s_waitcnt lgkmcnt(6)
	v_mfma_f32_16x16x32_bf16 v[28:31], v[246:249], v[190:193], v[28:31]
	ds_write_b128 v139, v[230:233] offset:30720
	v_mfma_f32_16x16x32_bf16 v[36:39], v[246:249], v[198:201], v[36:39]
	v_mfma_f32_16x16x32_bf16 v[48:51], v[246:249], v[202:205], v[48:51]
	v_mfma_f32_16x16x32_bf16 v[76:79], v[246:249], v[206:209], v[76:79]
	v_mfma_f32_16x16x32_bf16 v[80:83], v[246:249], v[210:213], v[80:83]
	v_mfma_f32_16x16x32_bf16 v[64:67], v[246:249], v[214:217], v[64:67]
	ds_read_b128 v[182:185], v124 offset:64
	ds_read_b128 v[186:189], v124 offset:2624
	ds_read_b128 v[190:193], v124 offset:5184
	ds_read_b128 v[194:197], v124 offset:7744
	ds_read_b128 v[198:201], v22 offset:41024
	ds_read_b128 v[202:205], v22 offset:43584
	ds_read_b128 v[206:209], v22 offset:46144
	ds_read_b128 v[210:213], v22 offset:48704
	ds_read_b128 v[214:217], v22 offset:51264
	ds_read_b128 v[218:221], v22 offset:53824
	s_waitcnt lgkmcnt(5)
	v_mfma_f32_16x16x32_bf16 v[40:43], v[182:185], v[198:201], v[40:43]
	s_waitcnt lgkmcnt(4)
	v_mfma_f32_16x16x32_bf16 v[44:47], v[182:185], v[202:205], v[44:47]
	s_waitcnt lgkmcnt(3)
	v_mfma_f32_16x16x32_bf16 v[84:87], v[182:185], v[206:209], v[84:87]
	s_waitcnt lgkmcnt(2)
	v_mfma_f32_16x16x32_bf16 v[88:91], v[182:185], v[210:213], v[88:91]
	s_waitcnt lgkmcnt(1)
	v_mfma_f32_16x16x32_bf16 v[106:109], v[182:185], v[214:217], v[106:109]
	s_waitcnt lgkmcnt(0)
	v_mfma_f32_16x16x32_bf16 v[24:27], v[182:185], v[218:221], v[24:27]
	global_load_dwordx4 v[182:185], v[8:9], off offset:1280
	global_load_dwordx4 v[222:225], v[10:11], off offset:1280
	global_load_dwordx4 v[226:229], v[12:13], off offset:1280
	global_load_dwordx4 v[230:233], v[14:15], off offset:1280
	global_load_dwordx4 v[234:237], v[16:17], off offset:1280
	global_load_dwordx4 v[238:241], v[18:19], off offset:1280
	global_load_dwordx4 v[242:245], v[20:21], off offset:1280
	v_mfma_f32_16x16x32_bf16 v[52:55], v[186:189], v[198:201], v[52:55]
	v_mfma_f32_16x16x32_bf16 v[68:71], v[186:189], v[202:205], v[68:71]
	v_mfma_f32_16x16x32_bf16 v[92:95], v[186:189], v[206:209], v[92:95]
	v_mfma_f32_16x16x32_bf16 v[110:113], v[186:189], v[210:213], v[110:113]
	v_mfma_f32_16x16x32_bf16 v[156:159], v[186:189], v[214:217], v[156:159]
	v_mfma_f32_16x16x32_bf16 v[32:35], v[186:189], v[218:221], v[32:35]
	v_mfma_f32_16x16x32_bf16 v[56:59], v[190:193], v[198:201], v[56:59]
	v_mfma_f32_16x16x32_bf16 v[72:75], v[190:193], v[202:205], v[72:75]
	v_mfma_f32_16x16x32_bf16 v[102:105], v[190:193], v[206:209], v[102:105]
	v_mfma_f32_16x16x32_bf16 v[174:177], v[190:193], v[210:213], v[174:177]
	v_mfma_f32_16x16x32_bf16 v[178:181], v[190:193], v[214:217], v[178:181]
	v_mfma_f32_16x16x32_bf16 v[60:63], v[190:193], v[218:221], v[60:63]
	v_mfma_f32_16x16x32_bf16 v[28:31], v[194:197], v[198:201], v[28:31]
	v_mfma_f32_16x16x32_bf16 v[36:39], v[194:197], v[202:205], v[36:39]
	v_mfma_f32_16x16x32_bf16 v[48:51], v[194:197], v[206:209], v[48:51]
	v_mfma_f32_16x16x32_bf16 v[76:79], v[194:197], v[210:213], v[76:79]
	v_mfma_f32_16x16x32_bf16 v[80:83], v[194:197], v[214:217], v[80:83]
	v_mfma_f32_16x16x32_bf16 v[64:67], v[194:197], v[218:221], v[64:67]
	s_barrier
; __device__ __forceinline__ void gemm_gates6(f32x4 (&acc)[4][6], const bf16_t* __restrict__ A, int lda,
;                                             const bf16_t* __restrict__ Bt, int ldb, int bstr, bf16_t* sA0, bf16_t* sB0,
;                                             const int tidx) {
;     ...
; #pragma unroll
;   for (int ks = 0; ks < 16; ks++) {
;     const bf16_t* sA_ = sA0 + (ks & 1) * BUFE;
;     const bf16_t* sB_ = sB0 + (ks & 1) * BUFE;
; #pragma unroll
;     for (int kk = 0; kk < 64; kk += 32) {
;       bf16x8 a[4], b[6];
; #pragma unroll
;       for (int i = 0; i < 4; i++) a[i] = *(const bf16x8*)(sA_ + (wm * 64 + i * 16 + l15) * GSTR + kk + quad * 8);
; #pragma unroll
;       for (int j = 0; j < 6; j++) b[j] = *(const bf16x8*)(sB_ + (wn * 96 + j * 16 + l15) * GSTR + kk + quad * 8);
;       bf16_t* dA_ = sA0 + ((ks + 1) & 1) * BUFE;
;       bf16_t* dB_ = sB0 + ((ks + 1) & 1) * BUFE;
; #pragma unroll
;       for (int i = 0; i < 4; i++) {
; #pragma unroll
;         for (int j = 0; j < 6; j++) acc[i][j] = __builtin_amdgcn_mfma_f32_16x16x32_bf16(a[i], b[j], acc[i][j], 0, 0, 0);
;         if (kk == 32 && i == 0 && ks + 2 < 16) {
;           W_LOAD((ks + 2) * 64);
;           __builtin_amdgcn_sched_barrier(0);
;         }
;         if (kk == 0 && ks + 1 < 16) {
;           *(u32x4*)(dA_ + (cr + 64 * i) * GSTR + ck * 8) = ra[i];
;           if (i < 3) *(u32x4*)(dB_ + (brow + i * 32) * GSTR + ck * 8) = rb[i];
;           __builtin_amdgcn_sched_barrier(0);
;         }
;       }
;       __builtin_amdgcn_sched_barrier(0);
;     }
;     if (ks + 1 < 16) __syncthreads();
;   }
	ds_read_b128 v[186:189], v141
	ds_read_b128 v[190:193], v142
	ds_read_b128 v[194:197], v141 offset:2560
	ds_read_b128 v[198:201], v142 offset:2560
	ds_read_b128 v[202:205], v142 offset:5120
	ds_read_b128 v[206:209], v142 offset:7680
	ds_read_b128 v[210:213], v142 offset:10240
	ds_read_b128 v[214:217], v142 offset:12800
	ds_read_b128 v[218:221], v141 offset:5120
	ds_read_b128 v[246:249], v141 offset:7680
	s_waitcnt lgkmcnt(8)
	v_mfma_f32_16x16x32_bf16 v[40:43], v[186:189], v[190:193], v[40:43]
	s_waitcnt vmcnt(6)
	ds_write_b128 v125, v[182:185]
	s_waitcnt vmcnt(2)
	ds_write_b128 v23, v[234:237] offset:40960
	s_waitcnt lgkmcnt(8)
	v_mfma_f32_16x16x32_bf16 v[44:47], v[186:189], v[198:201], v[44:47]
	s_waitcnt lgkmcnt(7)
	v_mfma_f32_16x16x32_bf16 v[84:87], v[186:189], v[202:205], v[84:87]
	s_waitcnt lgkmcnt(6)
	v_mfma_f32_16x16x32_bf16 v[88:91], v[186:189], v[206:209], v[88:91]
	s_waitcnt lgkmcnt(5)
	v_mfma_f32_16x16x32_bf16 v[106:109], v[186:189], v[210:213], v[106:109]
	s_waitcnt lgkmcnt(4)
	v_mfma_f32_16x16x32_bf16 v[24:27], v[186:189], v[214:217], v[24:27]
	v_mfma_f32_16x16x32_bf16 v[52:55], v[194:197], v[190:193], v[52:55]
	ds_write_b128 v125, v[222:225] offset:10240
	s_waitcnt vmcnt(1)
	ds_write_b128 v23, v[238:241] offset:46080
	v_mfma_f32_16x16x32_bf16 v[68:71], v[194:197], v[198:201], v[68:71]
	v_mfma_f32_16x16x32_bf16 v[92:95], v[194:197], v[202:205], v[92:95]
	v_mfma_f32_16x16x32_bf16 v[110:113], v[194:197], v[206:209], v[110:113]
	v_mfma_f32_16x16x32_bf16 v[156:159], v[194:197], v[210:213], v[156:159]
	v_mfma_f32_16x16x32_bf16 v[32:35], v[194:197], v[214:217], v[32:35]
	s_waitcnt lgkmcnt(5)
	v_mfma_f32_16x16x32_bf16 v[56:59], v[218:221], v[190:193], v[56:59]
	ds_write_b128 v125, v[226:229] offset:20480
	s_waitcnt vmcnt(0)
	ds_write_b128 v23, v[242:245] offset:51200
	v_mfma_f32_16x16x32_bf16 v[72:75], v[218:221], v[198:201], v[72:75]
	v_mfma_f32_16x16x32_bf16 v[102:105], v[218:221], v[202:205], v[102:105]
	v_mfma_f32_16x16x32_bf16 v[174:177], v[218:221], v[206:209], v[174:177]
	v_mfma_f32_16x16x32_bf16 v[178:181], v[218:221], v[210:213], v[178:181]
	v_mfma_f32_16x16x32_bf16 v[60:63], v[218:221], v[214:217], v[60:63]
	s_waitcnt lgkmcnt(6)
	v_mfma_f32_16x16x32_bf16 v[28:31], v[246:249], v[190:193], v[28:31]
	ds_write_b128 v125, v[230:233] offset:30720
	v_mfma_f32_16x16x32_bf16 v[36:39], v[246:249], v[198:201], v[36:39]
	v_mfma_f32_16x16x32_bf16 v[48:51], v[246:249], v[202:205], v[48:51]
	v_mfma_f32_16x16x32_bf16 v[76:79], v[246:249], v[206:209], v[76:79]
	v_mfma_f32_16x16x32_bf16 v[80:83], v[246:249], v[210:213], v[80:83]
	v_mfma_f32_16x16x32_bf16 v[64:67], v[246:249], v[214:217], v[64:67]
	ds_read_b128 v[182:185], v143
	ds_read_b128 v[186:189], v143 offset:2560
	ds_read_b128 v[190:193], v143 offset:5120
	ds_read_b128 v[194:197], v143 offset:7680
	ds_read_b128 v[198:201], v144
	ds_read_b128 v[202:205], v144 offset:2560
	ds_read_b128 v[206:209], v144 offset:5120
	ds_read_b128 v[210:213], v144 offset:7680
	ds_read_b128 v[214:217], v144 offset:10240
	ds_read_b128 v[218:221], v144 offset:12800
	s_waitcnt lgkmcnt(5)
	v_mfma_f32_16x16x32_bf16 v[40:43], v[182:185], v[198:201], v[40:43]
	s_waitcnt lgkmcnt(4)
	v_mfma_f32_16x16x32_bf16 v[44:47], v[182:185], v[202:205], v[44:47]
	s_waitcnt lgkmcnt(3)
	v_mfma_f32_16x16x32_bf16 v[84:87], v[182:185], v[206:209], v[84:87]
	s_waitcnt lgkmcnt(2)
	v_mfma_f32_16x16x32_bf16 v[88:91], v[182:185], v[210:213], v[88:91]
	s_waitcnt lgkmcnt(1)
	v_mfma_f32_16x16x32_bf16 v[106:109], v[182:185], v[214:217], v[106:109]
	s_waitcnt lgkmcnt(0)
	v_mfma_f32_16x16x32_bf16 v[24:27], v[182:185], v[218:221], v[24:27]
	global_load_dwordx4 v[182:185], v[8:9], off offset:1408
	global_load_dwordx4 v[222:225], v[10:11], off offset:1408
	global_load_dwordx4 v[226:229], v[12:13], off offset:1408
	global_load_dwordx4 v[230:233], v[14:15], off offset:1408
	global_load_dwordx4 v[234:237], v[16:17], off offset:1408
	global_load_dwordx4 v[238:241], v[18:19], off offset:1408
	global_load_dwordx4 v[242:245], v[20:21], off offset:1408
	v_mfma_f32_16x16x32_bf16 v[52:55], v[186:189], v[198:201], v[52:55]
	v_mfma_f32_16x16x32_bf16 v[68:71], v[186:189], v[202:205], v[68:71]
	v_mfma_f32_16x16x32_bf16 v[92:95], v[186:189], v[206:209], v[92:95]
	v_mfma_f32_16x16x32_bf16 v[110:113], v[186:189], v[210:213], v[110:113]
	v_mfma_f32_16x16x32_bf16 v[156:159], v[186:189], v[214:217], v[156:159]
	v_mfma_f32_16x16x32_bf16 v[32:35], v[186:189], v[218:221], v[32:35]
	v_mfma_f32_16x16x32_bf16 v[56:59], v[190:193], v[198:201], v[56:59]
	v_mfma_f32_16x16x32_bf16 v[72:75], v[190:193], v[202:205], v[72:75]
	v_mfma_f32_16x16x32_bf16 v[102:105], v[190:193], v[206:209], v[102:105]
	v_mfma_f32_16x16x32_bf16 v[174:177], v[190:193], v[210:213], v[174:177]
	v_mfma_f32_16x16x32_bf16 v[178:181], v[190:193], v[214:217], v[178:181]
	v_mfma_f32_16x16x32_bf16 v[60:63], v[190:193], v[218:221], v[60:63]
	v_mfma_f32_16x16x32_bf16 v[28:31], v[194:197], v[198:201], v[28:31]
	v_mfma_f32_16x16x32_bf16 v[36:39], v[194:197], v[202:205], v[36:39]
	v_mfma_f32_16x16x32_bf16 v[48:51], v[194:197], v[206:209], v[48:51]
	v_mfma_f32_16x16x32_bf16 v[76:79], v[194:197], v[210:213], v[76:79]
	v_mfma_f32_16x16x32_bf16 v[80:83], v[194:197], v[214:217], v[80:83]
	v_mfma_f32_16x16x32_bf16 v[64:67], v[194:197], v[218:221], v[64:67]
	s_barrier
; __device__ __forceinline__ void gemm_gates6(f32x4 (&acc)[4][6], const bf16_t* __restrict__ A, int lda,
;                                             const bf16_t* __restrict__ Bt, int ldb, int bstr, bf16_t* sA0, bf16_t* sB0,
;                                             const int tidx) {
;     ...
; #pragma unroll
;   for (int ks = 0; ks < 16; ks++) {
;     const bf16_t* sA_ = sA0 + (ks & 1) * BUFE;
;     const bf16_t* sB_ = sB0 + (ks & 1) * BUFE;
; #pragma unroll
;     for (int kk = 0; kk < 64; kk += 32) {
;       bf16x8 a[4], b[6];
; #pragma unroll
;       for (int i = 0; i < 4; i++) a[i] = *(const bf16x8*)(sA_ + (wm * 64 + i * 16 + l15) * GSTR + kk + quad * 8);
; #pragma unroll
;       for (int j = 0; j < 6; j++) b[j] = *(const bf16x8*)(sB_ + (wn * 96 + j * 16 + l15) * GSTR + kk + quad * 8);
;       bf16_t* dA_ = sA0 + ((ks + 1) & 1) * BUFE;
;       bf16_t* dB_ = sB0 + ((ks + 1) & 1) * BUFE;
; #pragma unroll
;       for (int i = 0; i < 4; i++) {
; #pragma unroll
;         for (int j = 0; j < 6; j++) acc[i][j] = __builtin_amdgcn_mfma_f32_16x16x32_bf16(a[i], b[j], acc[i][j], 0, 0, 0);
;         if (kk == 32 && i == 0 && ks + 2 < 16) {
;           W_LOAD((ks + 2) * 64);
;           __builtin_amdgcn_sched_barrier(0);
;         }
;         if (kk == 0 && ks + 1 < 16) {
;           *(u32x4*)(dA_ + (cr + 64 * i) * GSTR + ck * 8) = ra[i];
;           if (i < 3) *(u32x4*)(dB_ + (brow + i * 32) * GSTR + ck * 8) = rb[i];
;           __builtin_amdgcn_sched_barrier(0);
;         }
;       }
;       __builtin_amdgcn_sched_barrier(0);
;     }
;     if (ks + 1 < 16) __syncthreads();
;   }
	ds_read_b128 v[186:189], v124
	ds_read_b128 v[190:193], v22 offset:40960
	ds_read_b128 v[194:197], v124 offset:2560
	ds_read_b128 v[198:201], v22 offset:43520
	ds_read_b128 v[202:205], v22 offset:46080
	ds_read_b128 v[206:209], v22 offset:48640
	ds_read_b128 v[210:213], v22 offset:51200
	ds_read_b128 v[214:217], v22 offset:53760
	ds_read_b128 v[218:221], v124 offset:5120
	ds_read_b128 v[246:249], v124 offset:7680
	s_waitcnt lgkmcnt(8)
	v_mfma_f32_16x16x32_bf16 v[40:43], v[186:189], v[190:193], v[40:43]
	s_waitcnt vmcnt(6)
	ds_write_b128 v139, v[182:185]
	s_waitcnt vmcnt(2)
	ds_write_b128 v140, v[234:237]
	s_waitcnt lgkmcnt(8)
	v_mfma_f32_16x16x32_bf16 v[44:47], v[186:189], v[198:201], v[44:47]
	s_waitcnt lgkmcnt(7)
	v_mfma_f32_16x16x32_bf16 v[84:87], v[186:189], v[202:205], v[84:87]
	s_waitcnt lgkmcnt(6)
	v_mfma_f32_16x16x32_bf16 v[88:91], v[186:189], v[206:209], v[88:91]
	s_waitcnt lgkmcnt(5)
	v_mfma_f32_16x16x32_bf16 v[106:109], v[186:189], v[210:213], v[106:109]
	s_waitcnt lgkmcnt(4)
	v_mfma_f32_16x16x32_bf16 v[24:27], v[186:189], v[214:217], v[24:27]
	v_mfma_f32_16x16x32_bf16 v[52:55], v[194:197], v[190:193], v[52:55]
	ds_write_b128 v139, v[222:225] offset:10240
	s_waitcnt vmcnt(1)
	ds_write_b128 v140, v[238:241] offset:5120
	v_mfma_f32_16x16x32_bf16 v[68:71], v[194:197], v[198:201], v[68:71]
	v_mfma_f32_16x16x32_bf16 v[92:95], v[194:197], v[202:205], v[92:95]
	v_mfma_f32_16x16x32_bf16 v[110:113], v[194:197], v[206:209], v[110:113]
	v_mfma_f32_16x16x32_bf16 v[156:159], v[194:197], v[210:213], v[156:159]
	v_mfma_f32_16x16x32_bf16 v[32:35], v[194:197], v[214:217], v[32:35]
	s_waitcnt lgkmcnt(5)
	v_mfma_f32_16x16x32_bf16 v[56:59], v[218:221], v[190:193], v[56:59]
	ds_write_b128 v139, v[226:229] offset:20480
	s_waitcnt vmcnt(0)
	ds_write_b128 v140, v[242:245] offset:10240
	v_mfma_f32_16x16x32_bf16 v[72:75], v[218:221], v[198:201], v[72:75]
	v_mfma_f32_16x16x32_bf16 v[102:105], v[218:221], v[202:205], v[102:105]
	v_mfma_f32_16x16x32_bf16 v[174:177], v[218:221], v[206:209], v[174:177]
	v_mfma_f32_16x16x32_bf16 v[178:181], v[218:221], v[210:213], v[178:181]
	v_mfma_f32_16x16x32_bf16 v[60:63], v[218:221], v[214:217], v[60:63]
	s_waitcnt lgkmcnt(6)
	v_mfma_f32_16x16x32_bf16 v[28:31], v[246:249], v[190:193], v[28:31]
	ds_write_b128 v139, v[230:233] offset:30720
	v_mfma_f32_16x16x32_bf16 v[36:39], v[246:249], v[198:201], v[36:39]
	v_mfma_f32_16x16x32_bf16 v[48:51], v[246:249], v[202:205], v[48:51]
	v_mfma_f32_16x16x32_bf16 v[76:79], v[246:249], v[206:209], v[76:79]
	v_mfma_f32_16x16x32_bf16 v[80:83], v[246:249], v[210:213], v[80:83]
	v_mfma_f32_16x16x32_bf16 v[64:67], v[246:249], v[214:217], v[64:67]
	ds_read_b128 v[182:185], v124 offset:64
	ds_read_b128 v[186:189], v124 offset:2624
	ds_read_b128 v[190:193], v124 offset:5184
	ds_read_b128 v[194:197], v124 offset:7744
	ds_read_b128 v[198:201], v22 offset:41024
	ds_read_b128 v[202:205], v22 offset:43584
	ds_read_b128 v[206:209], v22 offset:46144
	ds_read_b128 v[210:213], v22 offset:48704
	ds_read_b128 v[214:217], v22 offset:51264
	ds_read_b128 v[218:221], v22 offset:53824
	s_waitcnt lgkmcnt(5)
	v_mfma_f32_16x16x32_bf16 v[40:43], v[182:185], v[198:201], v[40:43]
	s_waitcnt lgkmcnt(4)
	v_mfma_f32_16x16x32_bf16 v[44:47], v[182:185], v[202:205], v[44:47]
	s_waitcnt lgkmcnt(3)
	v_mfma_f32_16x16x32_bf16 v[84:87], v[182:185], v[206:209], v[84:87]
	s_waitcnt lgkmcnt(2)
	v_mfma_f32_16x16x32_bf16 v[88:91], v[182:185], v[210:213], v[88:91]
	s_waitcnt lgkmcnt(1)
	v_mfma_f32_16x16x32_bf16 v[106:109], v[182:185], v[214:217], v[106:109]
	s_waitcnt lgkmcnt(0)
	v_mfma_f32_16x16x32_bf16 v[24:27], v[182:185], v[218:221], v[24:27]
	global_load_dwordx4 v[182:185], v[8:9], off offset:1536
	global_load_dwordx4 v[222:225], v[10:11], off offset:1536
	global_load_dwordx4 v[226:229], v[12:13], off offset:1536
	global_load_dwordx4 v[230:233], v[14:15], off offset:1536
	global_load_dwordx4 v[234:237], v[16:17], off offset:1536
	global_load_dwordx4 v[238:241], v[18:19], off offset:1536
	global_load_dwordx4 v[242:245], v[20:21], off offset:1536
	v_mfma_f32_16x16x32_bf16 v[52:55], v[186:189], v[198:201], v[52:55]
	v_mfma_f32_16x16x32_bf16 v[68:71], v[186:189], v[202:205], v[68:71]
	v_mfma_f32_16x16x32_bf16 v[92:95], v[186:189], v[206:209], v[92:95]
	v_mfma_f32_16x16x32_bf16 v[110:113], v[186:189], v[210:213], v[110:113]
	v_mfma_f32_16x16x32_bf16 v[156:159], v[186:189], v[214:217], v[156:159]
	v_mfma_f32_16x16x32_bf16 v[32:35], v[186:189], v[218:221], v[32:35]
	v_mfma_f32_16x16x32_bf16 v[56:59], v[190:193], v[198:201], v[56:59]
	v_mfma_f32_16x16x32_bf16 v[72:75], v[190:193], v[202:205], v[72:75]
	v_mfma_f32_16x16x32_bf16 v[102:105], v[190:193], v[206:209], v[102:105]
	v_mfma_f32_16x16x32_bf16 v[174:177], v[190:193], v[210:213], v[174:177]
	v_mfma_f32_16x16x32_bf16 v[178:181], v[190:193], v[214:217], v[178:181]
	v_mfma_f32_16x16x32_bf16 v[60:63], v[190:193], v[218:221], v[60:63]
	v_mfma_f32_16x16x32_bf16 v[28:31], v[194:197], v[198:201], v[28:31]
	v_mfma_f32_16x16x32_bf16 v[36:39], v[194:197], v[202:205], v[36:39]
	v_mfma_f32_16x16x32_bf16 v[48:51], v[194:197], v[206:209], v[48:51]
	v_mfma_f32_16x16x32_bf16 v[76:79], v[194:197], v[210:213], v[76:79]
	v_mfma_f32_16x16x32_bf16 v[80:83], v[194:197], v[214:217], v[80:83]
	v_mfma_f32_16x16x32_bf16 v[64:67], v[194:197], v[218:221], v[64:67]
	s_barrier
; __device__ __forceinline__ void gemm_gates6(f32x4 (&acc)[4][6], const bf16_t* __restrict__ A, int lda,
;                                             const bf16_t* __restrict__ Bt, int ldb, int bstr, bf16_t* sA0, bf16_t* sB0,
;                                             const int tidx) {
;     ...
; #pragma unroll
;   for (int ks = 0; ks < 16; ks++) {
;     const bf16_t* sA_ = sA0 + (ks & 1) * BUFE;
;     const bf16_t* sB_ = sB0 + (ks & 1) * BUFE;
; #pragma unroll
;     for (int kk = 0; kk < 64; kk += 32) {
;       bf16x8 a[4], b[6];
; #pragma unroll
;       for (int i = 0; i < 4; i++) a[i] = *(const bf16x8*)(sA_ + (wm * 64 + i * 16 + l15) * GSTR + kk + quad * 8);
; #pragma unroll
;       for (int j = 0; j < 6; j++) b[j] = *(const bf16x8*)(sB_ + (wn * 96 + j * 16 + l15) * GSTR + kk + quad * 8);
;       bf16_t* dA_ = sA0 + ((ks + 1) & 1) * BUFE;
;       bf16_t* dB_ = sB0 + ((ks + 1) & 1) * BUFE;
; #pragma unroll
;       for (int i = 0; i < 4; i++) {
; #pragma unroll
;         for (int j = 0; j < 6; j++) acc[i][j] = __builtin_amdgcn_mfma_f32_16x16x32_bf16(a[i], b[j], acc[i][j], 0, 0, 0);
;         if (kk == 32 && i == 0 && ks + 2 < 16) {
;           W_LOAD((ks + 2) * 64);
;           __builtin_amdgcn_sched_barrier(0);
;         }
;         if (kk == 0 && ks + 1 < 16) {
;           *(u32x4*)(dA_ + (cr + 64 * i) * GSTR + ck * 8) = ra[i];
;           if (i < 3) *(u32x4*)(dB_ + (brow + i * 32) * GSTR + ck * 8) = rb[i];
;           __builtin_amdgcn_sched_barrier(0);
;         }
;       }
;       __builtin_amdgcn_sched_barrier(0);
;     }
;     if (ks + 1 < 16) __syncthreads();
;   }
	ds_read_b128 v[186:189], v141
	ds_read_b128 v[190:193], v142
	ds_read_b128 v[194:197], v141 offset:2560
	ds_read_b128 v[198:201], v142 offset:2560
	ds_read_b128 v[202:205], v142 offset:5120
	ds_read_b128 v[206:209], v142 offset:7680
	ds_read_b128 v[210:213], v142 offset:10240
	ds_read_b128 v[214:217], v142 offset:12800
	ds_read_b128 v[218:221], v141 offset:5120
	ds_read_b128 v[246:249], v141 offset:7680
	s_waitcnt lgkmcnt(8)
	v_mfma_f32_16x16x32_bf16 v[40:43], v[186:189], v[190:193], v[40:43]
	s_waitcnt vmcnt(6)
	ds_write_b128 v125, v[182:185]
	s_waitcnt vmcnt(2)
	ds_write_b128 v23, v[234:237] offset:40960
	s_waitcnt lgkmcnt(8)
	v_mfma_f32_16x16x32_bf16 v[44:47], v[186:189], v[198:201], v[44:47]
	s_waitcnt lgkmcnt(7)
	v_mfma_f32_16x16x32_bf16 v[84:87], v[186:189], v[202:205], v[84:87]
	s_waitcnt lgkmcnt(6)
	v_mfma_f32_16x16x32_bf16 v[88:91], v[186:189], v[206:209], v[88:91]
	s_waitcnt lgkmcnt(5)
	v_mfma_f32_16x16x32_bf16 v[106:109], v[186:189], v[210:213], v[106:109]
	s_waitcnt lgkmcnt(4)
	v_mfma_f32_16x16x32_bf16 v[24:27], v[186:189], v[214:217], v[24:27]
	v_mfma_f32_16x16x32_bf16 v[52:55], v[194:197], v[190:193], v[52:55]
	ds_write_b128 v125, v[222:225] offset:10240
	s_waitcnt vmcnt(1)
	ds_write_b128 v23, v[238:241] offset:46080
	v_mfma_f32_16x16x32_bf16 v[68:71], v[194:197], v[198:201], v[68:71]
	v_mfma_f32_16x16x32_bf16 v[92:95], v[194:197], v[202:205], v[92:95]
	v_mfma_f32_16x16x32_bf16 v[110:113], v[194:197], v[206:209], v[110:113]
	v_mfma_f32_16x16x32_bf16 v[156:159], v[194:197], v[210:213], v[156:159]
	v_mfma_f32_16x16x32_bf16 v[32:35], v[194:197], v[214:217], v[32:35]
	s_waitcnt lgkmcnt(5)
	v_mfma_f32_16x16x32_bf16 v[56:59], v[218:221], v[190:193], v[56:59]
	ds_write_b128 v125, v[226:229] offset:20480
	s_waitcnt vmcnt(0)
	ds_write_b128 v23, v[242:245] offset:51200
	v_mfma_f32_16x16x32_bf16 v[72:75], v[218:221], v[198:201], v[72:75]
	v_mfma_f32_16x16x32_bf16 v[102:105], v[218:221], v[202:205], v[102:105]
	v_mfma_f32_16x16x32_bf16 v[174:177], v[218:221], v[206:209], v[174:177]
	v_mfma_f32_16x16x32_bf16 v[178:181], v[218:221], v[210:213], v[178:181]
	v_mfma_f32_16x16x32_bf16 v[60:63], v[218:221], v[214:217], v[60:63]
	s_waitcnt lgkmcnt(6)
	v_mfma_f32_16x16x32_bf16 v[28:31], v[246:249], v[190:193], v[28:31]
	ds_write_b128 v125, v[230:233] offset:30720
	v_mfma_f32_16x16x32_bf16 v[36:39], v[246:249], v[198:201], v[36:39]
	v_mfma_f32_16x16x32_bf16 v[48:51], v[246:249], v[202:205], v[48:51]
	v_mfma_f32_16x16x32_bf16 v[76:79], v[246:249], v[206:209], v[76:79]
	v_mfma_f32_16x16x32_bf16 v[80:83], v[246:249], v[210:213], v[80:83]
	v_mfma_f32_16x16x32_bf16 v[64:67], v[246:249], v[214:217], v[64:67]
	ds_read_b128 v[182:185], v143
	ds_read_b128 v[186:189], v143 offset:2560
	ds_read_b128 v[190:193], v143 offset:5120
	ds_read_b128 v[194:197], v143 offset:7680
	ds_read_b128 v[198:201], v144
	ds_read_b128 v[202:205], v144 offset:2560
	ds_read_b128 v[206:209], v144 offset:5120
	ds_read_b128 v[210:213], v144 offset:7680
	ds_read_b128 v[214:217], v144 offset:10240
	ds_read_b128 v[218:221], v144 offset:12800
	s_waitcnt lgkmcnt(5)
	v_mfma_f32_16x16x32_bf16 v[40:43], v[182:185], v[198:201], v[40:43]
	s_waitcnt lgkmcnt(4)
	v_mfma_f32_16x16x32_bf16 v[44:47], v[182:185], v[202:205], v[44:47]
	s_waitcnt lgkmcnt(3)
	v_mfma_f32_16x16x32_bf16 v[84:87], v[182:185], v[206:209], v[84:87]
	s_waitcnt lgkmcnt(2)
	v_mfma_f32_16x16x32_bf16 v[88:91], v[182:185], v[210:213], v[88:91]
	s_waitcnt lgkmcnt(1)
	v_mfma_f32_16x16x32_bf16 v[106:109], v[182:185], v[214:217], v[106:109]
	s_waitcnt lgkmcnt(0)
	v_mfma_f32_16x16x32_bf16 v[24:27], v[182:185], v[218:221], v[24:27]
	global_load_dwordx4 v[182:185], v[8:9], off offset:1664
	global_load_dwordx4 v[222:225], v[10:11], off offset:1664
	global_load_dwordx4 v[226:229], v[12:13], off offset:1664
	global_load_dwordx4 v[230:233], v[14:15], off offset:1664
	global_load_dwordx4 v[234:237], v[16:17], off offset:1664
	global_load_dwordx4 v[238:241], v[18:19], off offset:1664
	global_load_dwordx4 v[242:245], v[20:21], off offset:1664
	v_mfma_f32_16x16x32_bf16 v[52:55], v[186:189], v[198:201], v[52:55]
	v_mfma_f32_16x16x32_bf16 v[68:71], v[186:189], v[202:205], v[68:71]
	v_mfma_f32_16x16x32_bf16 v[92:95], v[186:189], v[206:209], v[92:95]
	v_mfma_f32_16x16x32_bf16 v[110:113], v[186:189], v[210:213], v[110:113]
	v_mfma_f32_16x16x32_bf16 v[156:159], v[186:189], v[214:217], v[156:159]
	v_mfma_f32_16x16x32_bf16 v[32:35], v[186:189], v[218:221], v[32:35]
	v_mfma_f32_16x16x32_bf16 v[56:59], v[190:193], v[198:201], v[56:59]
	v_mfma_f32_16x16x32_bf16 v[72:75], v[190:193], v[202:205], v[72:75]
	v_mfma_f32_16x16x32_bf16 v[102:105], v[190:193], v[206:209], v[102:105]
	v_mfma_f32_16x16x32_bf16 v[174:177], v[190:193], v[210:213], v[174:177]
	v_mfma_f32_16x16x32_bf16 v[178:181], v[190:193], v[214:217], v[178:181]
	v_mfma_f32_16x16x32_bf16 v[60:63], v[190:193], v[218:221], v[60:63]
	v_mfma_f32_16x16x32_bf16 v[28:31], v[194:197], v[198:201], v[28:31]
	v_mfma_f32_16x16x32_bf16 v[36:39], v[194:197], v[202:205], v[36:39]
	v_mfma_f32_16x16x32_bf16 v[48:51], v[194:197], v[206:209], v[48:51]
	v_mfma_f32_16x16x32_bf16 v[76:79], v[194:197], v[210:213], v[76:79]
	v_mfma_f32_16x16x32_bf16 v[80:83], v[194:197], v[214:217], v[80:83]
	v_mfma_f32_16x16x32_bf16 v[64:67], v[194:197], v[218:221], v[64:67]
	s_barrier
; __device__ __forceinline__ void gemm_gates6(f32x4 (&acc)[4][6], const bf16_t* __restrict__ A, int lda,
;                                             const bf16_t* __restrict__ Bt, int ldb, int bstr, bf16_t* sA0, bf16_t* sB0,
;                                             const int tidx) {
;     ...
; #pragma unroll
;   for (int ks = 0; ks < 16; ks++) {
;     const bf16_t* sA_ = sA0 + (ks & 1) * BUFE;
;     const bf16_t* sB_ = sB0 + (ks & 1) * BUFE;
; #pragma unroll
;     for (int kk = 0; kk < 64; kk += 32) {
;       bf16x8 a[4], b[6];
; #pragma unroll
;       for (int i = 0; i < 4; i++) a[i] = *(const bf16x8*)(sA_ + (wm * 64 + i * 16 + l15) * GSTR + kk + quad * 8);
; #pragma unroll
;       for (int j = 0; j < 6; j++) b[j] = *(const bf16x8*)(sB_ + (wn * 96 + j * 16 + l15) * GSTR + kk + quad * 8);
;       bf16_t* dA_ = sA0 + ((ks + 1) & 1) * BUFE;
;       bf16_t* dB_ = sB0 + ((ks + 1) & 1) * BUFE;
; #pragma unroll
;       for (int i = 0; i < 4; i++) {
; #pragma unroll
;         for (int j = 0; j < 6; j++) acc[i][j] = __builtin_amdgcn_mfma_f32_16x16x32_bf16(a[i], b[j], acc[i][j], 0, 0, 0);
;         if (kk == 32 && i == 0 && ks + 2 < 16) {
;           W_LOAD((ks + 2) * 64);
;           __builtin_amdgcn_sched_barrier(0);
;         }
;         if (kk == 0 && ks + 1 < 16) {
;           *(u32x4*)(dA_ + (cr + 64 * i) * GSTR + ck * 8) = ra[i];
;           if (i < 3) *(u32x4*)(dB_ + (brow + i * 32) * GSTR + ck * 8) = rb[i];
;           __builtin_amdgcn_sched_barrier(0);
;         }
;       }
;       __builtin_amdgcn_sched_barrier(0);
;     }
;     if (ks + 1 < 16) __syncthreads();
;   }
	ds_read_b128 v[186:189], v124
	ds_read_b128 v[190:193], v22 offset:40960
	ds_read_b128 v[194:197], v124 offset:2560
	ds_read_b128 v[198:201], v22 offset:43520
	ds_read_b128 v[202:205], v22 offset:46080
	ds_read_b128 v[206:209], v22 offset:48640
	ds_read_b128 v[210:213], v22 offset:51200
	ds_read_b128 v[214:217], v22 offset:53760
	ds_read_b128 v[218:221], v124 offset:5120
	ds_read_b128 v[246:249], v124 offset:7680
	s_waitcnt lgkmcnt(8)
	v_mfma_f32_16x16x32_bf16 v[40:43], v[186:189], v[190:193], v[40:43]
	s_waitcnt vmcnt(6)
	ds_write_b128 v139, v[182:185]
	s_waitcnt vmcnt(2)
	ds_write_b128 v140, v[234:237]
	s_waitcnt lgkmcnt(8)
	v_mfma_f32_16x16x32_bf16 v[44:47], v[186:189], v[198:201], v[44:47]
	s_waitcnt lgkmcnt(7)
	v_mfma_f32_16x16x32_bf16 v[84:87], v[186:189], v[202:205], v[84:87]
	s_waitcnt lgkmcnt(6)
	v_mfma_f32_16x16x32_bf16 v[88:91], v[186:189], v[206:209], v[88:91]
	s_waitcnt lgkmcnt(5)
	v_mfma_f32_16x16x32_bf16 v[106:109], v[186:189], v[210:213], v[106:109]
	s_waitcnt lgkmcnt(4)
	v_mfma_f32_16x16x32_bf16 v[24:27], v[186:189], v[214:217], v[24:27]
	v_mfma_f32_16x16x32_bf16 v[52:55], v[194:197], v[190:193], v[52:55]
	ds_write_b128 v139, v[222:225] offset:10240
	s_waitcnt vmcnt(1)
	ds_write_b128 v140, v[238:241] offset:5120
	v_mfma_f32_16x16x32_bf16 v[68:71], v[194:197], v[198:201], v[68:71]
	v_mfma_f32_16x16x32_bf16 v[92:95], v[194:197], v[202:205], v[92:95]
	v_mfma_f32_16x16x32_bf16 v[110:113], v[194:197], v[206:209], v[110:113]
	v_mfma_f32_16x16x32_bf16 v[156:159], v[194:197], v[210:213], v[156:159]
	v_mfma_f32_16x16x32_bf16 v[32:35], v[194:197], v[214:217], v[32:35]
	s_waitcnt lgkmcnt(5)
	v_mfma_f32_16x16x32_bf16 v[56:59], v[218:221], v[190:193], v[56:59]
	ds_write_b128 v139, v[226:229] offset:20480
	s_waitcnt vmcnt(0)
	ds_write_b128 v140, v[242:245] offset:10240
	v_mfma_f32_16x16x32_bf16 v[72:75], v[218:221], v[198:201], v[72:75]
	v_mfma_f32_16x16x32_bf16 v[102:105], v[218:221], v[202:205], v[102:105]
	v_mfma_f32_16x16x32_bf16 v[174:177], v[218:221], v[206:209], v[174:177]
	v_mfma_f32_16x16x32_bf16 v[178:181], v[218:221], v[210:213], v[178:181]
	v_mfma_f32_16x16x32_bf16 v[60:63], v[218:221], v[214:217], v[60:63]
	s_waitcnt lgkmcnt(6)
	v_mfma_f32_16x16x32_bf16 v[28:31], v[246:249], v[190:193], v[28:31]
	ds_write_b128 v139, v[230:233] offset:30720
	v_mfma_f32_16x16x32_bf16 v[36:39], v[246:249], v[198:201], v[36:39]
	v_mfma_f32_16x16x32_bf16 v[48:51], v[246:249], v[202:205], v[48:51]
	v_mfma_f32_16x16x32_bf16 v[76:79], v[246:249], v[206:209], v[76:79]
	v_mfma_f32_16x16x32_bf16 v[80:83], v[246:249], v[210:213], v[80:83]
	v_mfma_f32_16x16x32_bf16 v[64:67], v[246:249], v[214:217], v[64:67]
	ds_read_b128 v[182:185], v124 offset:64
	ds_read_b128 v[186:189], v124 offset:2624
	ds_read_b128 v[190:193], v124 offset:5184
	ds_read_b128 v[194:197], v124 offset:7744
	ds_read_b128 v[198:201], v22 offset:41024
	ds_read_b128 v[202:205], v22 offset:43584
	ds_read_b128 v[206:209], v22 offset:46144
	ds_read_b128 v[210:213], v22 offset:48704
	ds_read_b128 v[214:217], v22 offset:51264
	ds_read_b128 v[218:221], v22 offset:53824
	s_waitcnt lgkmcnt(5)
	v_mfma_f32_16x16x32_bf16 v[40:43], v[182:185], v[198:201], v[40:43]
	s_waitcnt lgkmcnt(4)
	v_mfma_f32_16x16x32_bf16 v[44:47], v[182:185], v[202:205], v[44:47]
	s_waitcnt lgkmcnt(3)
	v_mfma_f32_16x16x32_bf16 v[84:87], v[182:185], v[206:209], v[84:87]
	s_waitcnt lgkmcnt(2)
	v_mfma_f32_16x16x32_bf16 v[88:91], v[182:185], v[210:213], v[88:91]
	s_waitcnt lgkmcnt(1)
	v_mfma_f32_16x16x32_bf16 v[106:109], v[182:185], v[214:217], v[106:109]
	s_waitcnt lgkmcnt(0)
	v_mfma_f32_16x16x32_bf16 v[24:27], v[182:185], v[218:221], v[24:27]
	global_load_dwordx4 v[182:185], v[8:9], off offset:1792
	global_load_dwordx4 v[222:225], v[10:11], off offset:1792
	global_load_dwordx4 v[226:229], v[12:13], off offset:1792
	global_load_dwordx4 v[230:233], v[14:15], off offset:1792
	global_load_dwordx4 v[234:237], v[16:17], off offset:1792
	global_load_dwordx4 v[238:241], v[18:19], off offset:1792
	global_load_dwordx4 v[242:245], v[20:21], off offset:1792
	v_mfma_f32_16x16x32_bf16 v[52:55], v[186:189], v[198:201], v[52:55]
	v_mfma_f32_16x16x32_bf16 v[68:71], v[186:189], v[202:205], v[68:71]
	v_mfma_f32_16x16x32_bf16 v[92:95], v[186:189], v[206:209], v[92:95]
	v_mfma_f32_16x16x32_bf16 v[110:113], v[186:189], v[210:213], v[110:113]
	v_mfma_f32_16x16x32_bf16 v[156:159], v[186:189], v[214:217], v[156:159]
	v_mfma_f32_16x16x32_bf16 v[32:35], v[186:189], v[218:221], v[32:35]
	v_mfma_f32_16x16x32_bf16 v[56:59], v[190:193], v[198:201], v[56:59]
	v_mfma_f32_16x16x32_bf16 v[72:75], v[190:193], v[202:205], v[72:75]
	v_mfma_f32_16x16x32_bf16 v[102:105], v[190:193], v[206:209], v[102:105]
	v_mfma_f32_16x16x32_bf16 v[174:177], v[190:193], v[210:213], v[174:177]
	v_mfma_f32_16x16x32_bf16 v[178:181], v[190:193], v[214:217], v[178:181]
	v_mfma_f32_16x16x32_bf16 v[60:63], v[190:193], v[218:221], v[60:63]
	v_mfma_f32_16x16x32_bf16 v[28:31], v[194:197], v[198:201], v[28:31]
	v_mfma_f32_16x16x32_bf16 v[36:39], v[194:197], v[202:205], v[36:39]
	v_mfma_f32_16x16x32_bf16 v[48:51], v[194:197], v[206:209], v[48:51]
	v_mfma_f32_16x16x32_bf16 v[76:79], v[194:197], v[210:213], v[76:79]
	v_mfma_f32_16x16x32_bf16 v[80:83], v[194:197], v[214:217], v[80:83]
	v_mfma_f32_16x16x32_bf16 v[64:67], v[194:197], v[218:221], v[64:67]
	s_barrier
; __device__ __forceinline__ void gemm_gates6(f32x4 (&acc)[4][6], const bf16_t* __restrict__ A, int lda,
;                                             const bf16_t* __restrict__ Bt, int ldb, int bstr, bf16_t* sA0, bf16_t* sB0,
;                                             const int tidx) {
;     ...
; #pragma unroll
;   for (int ks = 0; ks < 16; ks++) {
;     const bf16_t* sA_ = sA0 + (ks & 1) * BUFE;
;     const bf16_t* sB_ = sB0 + (ks & 1) * BUFE;
; #pragma unroll
;     for (int kk = 0; kk < 64; kk += 32) {
;       bf16x8 a[4], b[6];
; #pragma unroll
;       for (int i = 0; i < 4; i++) a[i] = *(const bf16x8*)(sA_ + (wm * 64 + i * 16 + l15) * GSTR + kk + quad * 8);
; #pragma unroll
;       for (int j = 0; j < 6; j++) b[j] = *(const bf16x8*)(sB_ + (wn * 96 + j * 16 + l15) * GSTR + kk + quad * 8);
;       bf16_t* dA_ = sA0 + ((ks + 1) & 1) * BUFE;
;       bf16_t* dB_ = sB0 + ((ks + 1) & 1) * BUFE;
; #pragma unroll
;       for (int i = 0; i < 4; i++) {
; #pragma unroll
;         for (int j = 0; j < 6; j++) acc[i][j] = __builtin_amdgcn_mfma_f32_16x16x32_bf16(a[i], b[j], acc[i][j], 0, 0, 0);
;         if (kk == 32 && i == 0 && ks + 2 < 16) {
;           W_LOAD((ks + 2) * 64);
;           __builtin_amdgcn_sched_barrier(0);
;         }
;         if (kk == 0 && ks + 1 < 16) {
;           *(u32x4*)(dA_ + (cr + 64 * i) * GSTR + ck * 8) = ra[i];
;           if (i < 3) *(u32x4*)(dB_ + (brow + i * 32) * GSTR + ck * 8) = rb[i];
;           __builtin_amdgcn_sched_barrier(0);
;         }
;       }
;       __builtin_amdgcn_sched_barrier(0);
;     }
;     if (ks + 1 < 16) __syncthreads();
;   }
	ds_read_b128 v[186:189], v141
	ds_read_b128 v[190:193], v142
	ds_read_b128 v[194:197], v141 offset:2560
	ds_read_b128 v[198:201], v142 offset:2560
	ds_read_b128 v[202:205], v142 offset:5120
	ds_read_b128 v[206:209], v142 offset:7680
	ds_read_b128 v[210:213], v142 offset:10240
	ds_read_b128 v[214:217], v142 offset:12800
	ds_read_b128 v[218:221], v141 offset:5120
	ds_read_b128 v[246:249], v141 offset:7680
	s_waitcnt lgkmcnt(8)
	v_mfma_f32_16x16x32_bf16 v[40:43], v[186:189], v[190:193], v[40:43]
	s_waitcnt vmcnt(6)
	ds_write_b128 v125, v[182:185]
	s_waitcnt vmcnt(2)
	ds_write_b128 v23, v[234:237] offset:40960
	s_waitcnt lgkmcnt(8)
	v_mfma_f32_16x16x32_bf16 v[44:47], v[186:189], v[198:201], v[44:47]
	s_waitcnt lgkmcnt(7)
	v_mfma_f32_16x16x32_bf16 v[84:87], v[186:189], v[202:205], v[84:87]
	s_waitcnt lgkmcnt(6)
	v_mfma_f32_16x16x32_bf16 v[88:91], v[186:189], v[206:209], v[88:91]
	s_waitcnt lgkmcnt(5)
	v_mfma_f32_16x16x32_bf16 v[106:109], v[186:189], v[210:213], v[106:109]
	s_waitcnt lgkmcnt(4)
	v_mfma_f32_16x16x32_bf16 v[24:27], v[186:189], v[214:217], v[24:27]
	v_mfma_f32_16x16x32_bf16 v[52:55], v[194:197], v[190:193], v[52:55]
	ds_write_b128 v125, v[222:225] offset:10240
	s_waitcnt vmcnt(1)
	ds_write_b128 v23, v[238:241] offset:46080
	v_mfma_f32_16x16x32_bf16 v[68:71], v[194:197], v[198:201], v[68:71]
	v_mfma_f32_16x16x32_bf16 v[92:95], v[194:197], v[202:205], v[92:95]
	v_mfma_f32_16x16x32_bf16 v[110:113], v[194:197], v[206:209], v[110:113]
	v_mfma_f32_16x16x32_bf16 v[156:159], v[194:197], v[210:213], v[156:159]
	v_mfma_f32_16x16x32_bf16 v[32:35], v[194:197], v[214:217], v[32:35]
	s_waitcnt lgkmcnt(5)
	v_mfma_f32_16x16x32_bf16 v[56:59], v[218:221], v[190:193], v[56:59]
	ds_write_b128 v125, v[226:229] offset:20480
	s_waitcnt vmcnt(0)
	ds_write_b128 v23, v[242:245] offset:51200
	v_mfma_f32_16x16x32_bf16 v[72:75], v[218:221], v[198:201], v[72:75]
	v_mfma_f32_16x16x32_bf16 v[102:105], v[218:221], v[202:205], v[102:105]
	v_mfma_f32_16x16x32_bf16 v[174:177], v[218:221], v[206:209], v[174:177]
	v_mfma_f32_16x16x32_bf16 v[178:181], v[218:221], v[210:213], v[178:181]
	v_mfma_f32_16x16x32_bf16 v[60:63], v[218:221], v[214:217], v[60:63]
	s_waitcnt lgkmcnt(6)
	v_mfma_f32_16x16x32_bf16 v[28:31], v[246:249], v[190:193], v[28:31]
	ds_write_b128 v125, v[230:233] offset:30720
	v_mfma_f32_16x16x32_bf16 v[36:39], v[246:249], v[198:201], v[36:39]
	v_mfma_f32_16x16x32_bf16 v[48:51], v[246:249], v[202:205], v[48:51]
	v_mfma_f32_16x16x32_bf16 v[76:79], v[246:249], v[206:209], v[76:79]
	v_mfma_f32_16x16x32_bf16 v[80:83], v[246:249], v[210:213], v[80:83]
	v_mfma_f32_16x16x32_bf16 v[64:67], v[246:249], v[214:217], v[64:67]
	ds_read_b128 v[182:185], v143
	ds_read_b128 v[186:189], v143 offset:2560
	ds_read_b128 v[190:193], v143 offset:5120
	ds_read_b128 v[194:197], v143 offset:7680
	ds_read_b128 v[198:201], v144
	ds_read_b128 v[202:205], v144 offset:2560
	ds_read_b128 v[206:209], v144 offset:5120
	ds_read_b128 v[210:213], v144 offset:7680
	ds_read_b128 v[214:217], v144 offset:10240
	ds_read_b128 v[218:221], v144 offset:12800
	s_waitcnt lgkmcnt(5)
	v_mfma_f32_16x16x32_bf16 v[40:43], v[182:185], v[198:201], v[40:43]
	s_waitcnt lgkmcnt(4)
	v_mfma_f32_16x16x32_bf16 v[44:47], v[182:185], v[202:205], v[44:47]
	s_waitcnt lgkmcnt(3)
	v_mfma_f32_16x16x32_bf16 v[84:87], v[182:185], v[206:209], v[84:87]
	s_waitcnt lgkmcnt(2)
	v_mfma_f32_16x16x32_bf16 v[88:91], v[182:185], v[210:213], v[88:91]
	s_waitcnt lgkmcnt(1)
	v_mfma_f32_16x16x32_bf16 v[106:109], v[182:185], v[214:217], v[106:109]
	s_waitcnt lgkmcnt(0)
	v_mfma_f32_16x16x32_bf16 v[24:27], v[182:185], v[218:221], v[24:27]
	global_load_dwordx4 v[182:185], v[8:9], off offset:1920
	s_nop 0
	global_load_dwordx4 v[8:11], v[10:11], off offset:1920
	s_nop 0
	global_load_dwordx4 v[222:225], v[12:13], off offset:1920
	s_nop 0
	global_load_dwordx4 v[12:15], v[14:15], off offset:1920
	s_nop 0
	global_load_dwordx4 v[226:229], v[16:17], off offset:1920
	s_nop 0
	global_load_dwordx4 v[16:19], v[18:19], off offset:1920
	s_nop 0
	global_load_dwordx4 v[230:233], v[20:21], off offset:1920
	v_mfma_f32_16x16x32_bf16 v[52:55], v[186:189], v[198:201], v[52:55]
	v_mfma_f32_16x16x32_bf16 v[68:71], v[186:189], v[202:205], v[68:71]
	v_mfma_f32_16x16x32_bf16 v[92:95], v[186:189], v[206:209], v[92:95]
	v_mfma_f32_16x16x32_bf16 v[110:113], v[186:189], v[210:213], v[110:113]
	v_mfma_f32_16x16x32_bf16 v[156:159], v[186:189], v[214:217], v[156:159]
	v_mfma_f32_16x16x32_bf16 v[32:35], v[186:189], v[218:221], v[32:35]
	v_mfma_f32_16x16x32_bf16 v[56:59], v[190:193], v[198:201], v[56:59]
	v_mfma_f32_16x16x32_bf16 v[72:75], v[190:193], v[202:205], v[72:75]
	v_mfma_f32_16x16x32_bf16 v[102:105], v[190:193], v[206:209], v[102:105]
	v_mfma_f32_16x16x32_bf16 v[174:177], v[190:193], v[210:213], v[174:177]
	v_mfma_f32_16x16x32_bf16 v[178:181], v[190:193], v[214:217], v[178:181]
	v_mfma_f32_16x16x32_bf16 v[60:63], v[190:193], v[218:221], v[60:63]
	v_mfma_f32_16x16x32_bf16 v[28:31], v[194:197], v[198:201], v[28:31]
	v_mfma_f32_16x16x32_bf16 v[36:39], v[194:197], v[202:205], v[36:39]
	v_mfma_f32_16x16x32_bf16 v[48:51], v[194:197], v[206:209], v[48:51]
	v_mfma_f32_16x16x32_bf16 v[76:79], v[194:197], v[210:213], v[76:79]
	v_mfma_f32_16x16x32_bf16 v[80:83], v[194:197], v[214:217], v[80:83]
	v_mfma_f32_16x16x32_bf16 v[64:67], v[194:197], v[218:221], v[64:67]
	s_barrier
; __device__ __forceinline__ void gemm_gates6(f32x4 (&acc)[4][6], const bf16_t* __restrict__ A, int lda,
;                                             const bf16_t* __restrict__ Bt, int ldb, int bstr, bf16_t* sA0, bf16_t* sB0,
;                                             const int tidx) {
;     ...
; #pragma unroll
;   for (int ks = 0; ks < 16; ks++) {
;     const bf16_t* sA_ = sA0 + (ks & 1) * BUFE;
;     const bf16_t* sB_ = sB0 + (ks & 1) * BUFE;
; #pragma unroll
;     for (int kk = 0; kk < 64; kk += 32) {
;       bf16x8 a[4], b[6];
; #pragma unroll
;       for (int i = 0; i < 4; i++) a[i] = *(const bf16x8*)(sA_ + (wm * 64 + i * 16 + l15) * GSTR + kk + quad * 8);
; #pragma unroll
;       for (int j = 0; j < 6; j++) b[j] = *(const bf16x8*)(sB_ + (wn * 96 + j * 16 + l15) * GSTR + kk + quad * 8);
;       bf16_t* dA_ = sA0 + ((ks + 1) & 1) * BUFE;
;       bf16_t* dB_ = sB0 + ((ks + 1) & 1) * BUFE;
; #pragma unroll
;       for (int i = 0; i < 4; i++) {
; #pragma unroll
;         for (int j = 0; j < 6; j++) acc[i][j] = __builtin_amdgcn_mfma_f32_16x16x32_bf16(a[i], b[j], acc[i][j], 0, 0, 0);
;         if (kk == 32 && i == 0 && ks + 2 < 16) {
;           W_LOAD((ks + 2) * 64);
;           __builtin_amdgcn_sched_barrier(0);
;         }
;         if (kk == 0 && ks + 1 < 16) {
;           *(u32x4*)(dA_ + (cr + 64 * i) * GSTR + ck * 8) = ra[i];
;           if (i < 3) *(u32x4*)(dB_ + (brow + i * 32) * GSTR + ck * 8) = rb[i];
;           __builtin_amdgcn_sched_barrier(0);
;         }
;       }
;       __builtin_amdgcn_sched_barrier(0);
;     }
;     if (ks + 1 < 16) __syncthreads();
;   }
	ds_read_b128 v[186:189], v124
	ds_read_b128 v[190:193], v22 offset:40960
	ds_read_b128 v[194:197], v124 offset:2560
	ds_read_b128 v[198:201], v22 offset:43520
	ds_read_b128 v[202:205], v22 offset:46080
	ds_read_b128 v[206:209], v22 offset:48640
	ds_read_b128 v[210:213], v22 offset:51200
	ds_read_b128 v[214:217], v22 offset:53760
	ds_read_b128 v[218:221], v124 offset:5120
	ds_read_b128 v[234:237], v124 offset:7680
	s_waitcnt lgkmcnt(8)
	v_mfma_f32_16x16x32_bf16 v[40:43], v[186:189], v[190:193], v[40:43]
	s_waitcnt vmcnt(6)
	ds_write_b128 v139, v[182:185]
	s_waitcnt vmcnt(2)
	ds_write_b128 v140, v[226:229]
	s_waitcnt lgkmcnt(8)
	v_mfma_f32_16x16x32_bf16 v[44:47], v[186:189], v[198:201], v[44:47]
	s_waitcnt lgkmcnt(7)
	v_mfma_f32_16x16x32_bf16 v[84:87], v[186:189], v[202:205], v[84:87]
	s_waitcnt lgkmcnt(6)
	v_mfma_f32_16x16x32_bf16 v[88:91], v[186:189], v[206:209], v[88:91]
	s_waitcnt lgkmcnt(5)
	v_mfma_f32_16x16x32_bf16 v[106:109], v[186:189], v[210:213], v[106:109]
	s_waitcnt lgkmcnt(4)
	v_mfma_f32_16x16x32_bf16 v[24:27], v[186:189], v[214:217], v[24:27]
	v_mfma_f32_16x16x32_bf16 v[52:55], v[194:197], v[190:193], v[52:55]
	ds_write_b128 v139, v[8:11] offset:10240
	s_waitcnt vmcnt(1)
	ds_write_b128 v140, v[16:19] offset:5120
	v_mfma_f32_16x16x32_bf16 v[68:71], v[194:197], v[198:201], v[68:71]
	v_mfma_f32_16x16x32_bf16 v[92:95], v[194:197], v[202:205], v[92:95]
	v_mfma_f32_16x16x32_bf16 v[110:113], v[194:197], v[206:209], v[110:113]
	v_mfma_f32_16x16x32_bf16 v[156:159], v[194:197], v[210:213], v[156:159]
	v_mfma_f32_16x16x32_bf16 v[8:11], v[194:197], v[214:217], v[32:35]
	s_waitcnt lgkmcnt(5)
	v_mfma_f32_16x16x32_bf16 v[16:19], v[218:221], v[190:193], v[56:59]
	ds_write_b128 v139, v[222:225] offset:20480
	s_waitcnt vmcnt(0)
	ds_write_b128 v140, v[230:233] offset:10240
	v_mfma_f32_16x16x32_bf16 v[32:35], v[218:221], v[198:201], v[72:75]
	v_mfma_f32_16x16x32_bf16 v[56:59], v[218:221], v[202:205], v[102:105]
	v_mfma_f32_16x16x32_bf16 v[72:75], v[218:221], v[206:209], v[174:177]
	v_mfma_f32_16x16x32_bf16 v[102:105], v[218:221], v[210:213], v[178:181]
	v_mfma_f32_16x16x32_bf16 v[60:63], v[218:221], v[214:217], v[60:63]
	s_waitcnt lgkmcnt(6)
	v_mfma_f32_16x16x32_bf16 v[28:31], v[234:237], v[190:193], v[28:31]
	ds_write_b128 v139, v[12:15] offset:30720
	v_mfma_f32_16x16x32_bf16 v[36:39], v[234:237], v[198:201], v[36:39]
	v_mfma_f32_16x16x32_bf16 v[48:51], v[234:237], v[202:205], v[48:51]
	v_mfma_f32_16x16x32_bf16 v[76:79], v[234:237], v[206:209], v[76:79]
	v_mfma_f32_16x16x32_bf16 v[80:83], v[234:237], v[210:213], v[80:83]
	v_mfma_f32_16x16x32_bf16 v[12:15], v[234:237], v[214:217], v[64:67]
	s_nop 2
	ds_read_b128 v[64:67], v124 offset:64
	ds_read_b128 v[174:177], v22 offset:41024
	ds_read_b128 v[178:181], v22 offset:43584
	ds_read_b128 v[182:185], v22 offset:46144
	ds_read_b128 v[186:189], v22 offset:48704
	ds_read_b128 v[190:193], v22 offset:51264
	ds_read_b128 v[20:23], v22 offset:53824
	s_waitcnt lgkmcnt(5)
	v_mfma_f32_16x16x32_bf16 v[40:43], v[64:67], v[174:177], v[40:43]
	s_waitcnt lgkmcnt(4)
	v_mfma_f32_16x16x32_bf16 v[44:47], v[64:67], v[178:181], v[44:47]
	s_waitcnt lgkmcnt(3)
	v_mfma_f32_16x16x32_bf16 v[84:87], v[64:67], v[182:185], v[84:87]
	s_waitcnt lgkmcnt(2)
	v_mfma_f32_16x16x32_bf16 v[88:91], v[64:67], v[186:189], v[88:91]
	s_waitcnt lgkmcnt(1)
	v_mfma_f32_16x16x32_bf16 v[106:109], v[64:67], v[190:193], v[106:109]
	s_waitcnt lgkmcnt(0)
	v_mfma_f32_16x16x32_bf16 v[24:27], v[64:67], v[20:23], v[24:27]
	ds_read_b128 v[64:67], v124 offset:2624
	s_waitcnt lgkmcnt(0)
	v_mfma_f32_16x16x32_bf16 v[52:55], v[64:67], v[174:177], v[52:55]
	v_mfma_f32_16x16x32_bf16 v[68:71], v[64:67], v[178:181], v[68:71]
	v_mfma_f32_16x16x32_bf16 v[92:95], v[64:67], v[182:185], v[92:95]
	v_mfma_f32_16x16x32_bf16 v[110:113], v[64:67], v[186:189], v[110:113]
	v_mfma_f32_16x16x32_bf16 v[156:159], v[64:67], v[190:193], v[156:159]
	v_mfma_f32_16x16x32_bf16 v[8:11], v[64:67], v[20:23], v[8:11]
	ds_read_b128 v[64:67], v124 offset:5184
	s_waitcnt lgkmcnt(0)
	v_mfma_f32_16x16x32_bf16 v[16:19], v[64:67], v[174:177], v[16:19]
	v_mfma_f32_16x16x32_bf16 v[32:35], v[64:67], v[178:181], v[32:35]
	v_mfma_f32_16x16x32_bf16 v[56:59], v[64:67], v[182:185], v[56:59]
	v_mfma_f32_16x16x32_bf16 v[72:75], v[64:67], v[186:189], v[72:75]
	v_mfma_f32_16x16x32_bf16 v[102:105], v[64:67], v[190:193], v[102:105]
	v_mfma_f32_16x16x32_bf16 v[60:63], v[64:67], v[20:23], v[60:63]
	ds_read_b128 v[64:67], v124 offset:7744
	s_waitcnt lgkmcnt(0)
	v_mfma_f32_16x16x32_bf16 v[28:31], v[64:67], v[174:177], v[28:31]
	v_mfma_f32_16x16x32_bf16 v[36:39], v[64:67], v[178:181], v[36:39]
	v_mfma_f32_16x16x32_bf16 v[48:51], v[64:67], v[182:185], v[48:51]
	v_mfma_f32_16x16x32_bf16 v[76:79], v[64:67], v[186:189], v[76:79]
	v_mfma_f32_16x16x32_bf16 v[80:83], v[64:67], v[190:193], v[80:83]
	v_mfma_f32_16x16x32_bf16 v[12:15], v[64:67], v[20:23], v[12:15]
	s_barrier
; __device__ __forceinline__ float sigmoidf_(float x) { return __builtin_amdgcn_rcpf(1.f + __expf(-x)); }
; __device__ __forceinline__ void gemm_gates6(f32x4 (&acc)[4][6], const bf16_t* __restrict__ A, int lda,
;                                             const bf16_t* __restrict__ Bt, int ldb, int bstr, bf16_t* sA0, bf16_t* sB0,
;                                             const int tidx) {
;     ...
; #pragma unroll
;   for (int ks = 0; ks < 16; ks++) {
;     const bf16_t* sA_ = sA0 + (ks & 1) * BUFE;
;     const bf16_t* sB_ = sB0 + (ks & 1) * BUFE;
; #pragma unroll
;     for (int kk = 0; kk < 64; kk += 32) {
;       bf16x8 a[4], b[6];
; #pragma unroll
;       for (int i = 0; i < 4; i++) a[i] = *(const bf16x8*)(sA_ + (wm * 64 + i * 16 + l15) * GSTR + kk + quad * 8);
; #pragma unroll
;       for (int j = 0; j < 6; j++) b[j] = *(const bf16x8*)(sB_ + (wn * 96 + j * 16 + l15) * GSTR + kk + quad * 8);
;       bf16_t* dA_ = sA0 + ((ks + 1) & 1) * BUFE;
;       bf16_t* dB_ = sB0 + ((ks + 1) & 1) * BUFE;
; #pragma unroll
;       for (int i = 0; i < 4; i++) {
; #pragma unroll
;         for (int j = 0; j < 6; j++) acc[i][j] = __builtin_amdgcn_mfma_f32_16x16x32_bf16(a[i], b[j], acc[i][j], 0, 0, 0);
;         if (kk == 32 && i == 0 && ks + 2 < 16) {
;           W_LOAD((ks + 2) * 64);
;           __builtin_amdgcn_sched_barrier(0);
;         }
;         if (kk == 0 && ks + 1 < 16) {
;           *(u32x4*)(dA_ + (cr + 64 * i) * GSTR + ck * 8) = ra[i];
;           if (i < 3) *(u32x4*)(dB_ + (brow + i * 32) * GSTR + ck * 8) = rb[i];
;           __builtin_amdgcn_sched_barrier(0);
;         }
;       }
;       __builtin_amdgcn_sched_barrier(0);
;     }
;     if (ks + 1 < 16) __syncthreads();
;   }
; __device__ __forceinline__ void phase_merge(const Params& p, const int tidx) {
;     ...
; #pragma unroll
;       for (int br = 0; br < 2; br++)
; #pragma unroll
;         for (int i = 0; i < 4; i++)
; #pragma unroll
;           for (int j = 0; j < 2; j++) {
;             gp[br][i][j][0] = pack2(sigmoidf_(g6[i][2 * br + j][0]), sigmoidf_(g6[i][2 * br + j][1]));
;             gp[br][i][j][1] = pack2(sigmoidf_(g6[i][2 * br + j][2]), sigmoidf_(g6[i][2 * br + j][3]));
;           }
	ds_read_b128 v[20:23], v141
	ds_read_b128 v[64:67], v142
	ds_read_b128 v[174:177], v142 offset:2560
	ds_read_b128 v[178:181], v142 offset:5120
	ds_read_b128 v[182:185], v142 offset:7680
	ds_read_b128 v[186:189], v142 offset:10240
	ds_read_b128 v[190:193], v142 offset:12800
	s_waitcnt lgkmcnt(5)
	v_mfma_f32_16x16x32_bf16 v[40:43], v[20:23], v[64:67], v[40:43]
	s_waitcnt lgkmcnt(4)
	v_mfma_f32_16x16x32_bf16 v[44:47], v[20:23], v[174:177], v[44:47]
	s_waitcnt lgkmcnt(3)
	v_mfma_f32_16x16x32_bf16 v[84:87], v[20:23], v[178:181], v[84:87]
	s_waitcnt lgkmcnt(2)
	v_mfma_f32_16x16x32_bf16 v[88:91], v[20:23], v[182:185], v[88:91]
	s_waitcnt lgkmcnt(1)
	v_mfma_f32_16x16x32_bf16 v[106:109], v[20:23], v[186:189], v[106:109]
	s_waitcnt lgkmcnt(0)
	v_mfma_f32_16x16x32_bf16 v[20:23], v[20:23], v[190:193], v[24:27]
	s_nop 2
	ds_read_b128 v[24:27], v141 offset:2560
	s_waitcnt lgkmcnt(0)
	v_mfma_f32_16x16x32_bf16 v[194:197], v[24:27], v[64:67], v[52:55]
	s_nop 2
	ds_read_b128 v[52:55], v141 offset:7680
	v_mfma_f32_16x16x32_bf16 v[68:71], v[24:27], v[174:177], v[68:71]
	v_mfma_f32_16x16x32_bf16 v[92:95], v[24:27], v[178:181], v[92:95]
	v_mfma_f32_16x16x32_bf16 v[110:113], v[24:27], v[182:185], v[110:113]
	v_mfma_f32_16x16x32_bf16 v[156:159], v[24:27], v[186:189], v[156:159]
	v_mfma_f32_16x16x32_bf16 v[8:11], v[24:27], v[190:193], v[8:11]
	ds_read_b128 v[24:27], v141 offset:5120
	s_waitcnt lgkmcnt(0)
	v_mfma_f32_16x16x32_bf16 v[16:19], v[24:27], v[64:67], v[16:19]
	v_mfma_f32_16x16x32_bf16 v[32:35], v[24:27], v[174:177], v[32:35]
	v_mfma_f32_16x16x32_bf16 v[198:201], v[24:27], v[178:181], v[56:59]
	v_mfma_f32_16x16x32_bf16 v[72:75], v[24:27], v[182:185], v[72:75]
	v_mfma_f32_16x16x32_bf16 v[102:105], v[24:27], v[186:189], v[102:105]
	v_mfma_f32_16x16x32_bf16 v[24:27], v[24:27], v[190:193], v[60:63]
	v_mfma_f32_16x16x32_bf16 v[202:205], v[52:55], v[64:67], v[28:31]
	v_mfma_f32_16x16x32_bf16 v[174:177], v[52:55], v[174:177], v[36:39]
	v_mfma_f32_16x16x32_bf16 v[178:181], v[52:55], v[178:181], v[48:51]
	v_mfma_f32_16x16x32_bf16 v[76:79], v[52:55], v[182:185], v[76:79]
	v_mfma_f32_16x16x32_bf16 v[80:83], v[52:55], v[186:189], v[80:83]
	v_mfma_f32_16x16x32_bf16 v[182:185], v[52:55], v[190:193], v[12:15]
	s_nop 2
	ds_read_b128 v[12:15], v143
	ds_read_b128 v[186:189], v144
	ds_read_b128 v[206:209], v144 offset:2560
	ds_read_b128 v[214:217], v144 offset:5120
	s_waitcnt lgkmcnt(0)
	v_mfma_f32_16x16x32_bf16 v[64:67], v[12:15], v[214:217], v[84:87]
	s_nop 2
	ds_read_b128 v[84:87], v144 offset:7680
	s_waitcnt lgkmcnt(0)
	v_mfma_f32_16x16x32_bf16 v[56:59], v[12:15], v[84:87], v[88:91]
	s_nop 2
	ds_read_b128 v[88:91], v144 offset:10240
	s_waitcnt lgkmcnt(0)
	v_mfma_f32_16x16x32_bf16 v[52:55], v[12:15], v[88:91], v[106:109]
	s_nop 2
	ds_read_b128 v[106:109], v144 offset:12800
	v_mfma_f32_16x16x32_bf16 v[190:193], v[12:15], v[186:189], v[40:43]
	v_mfma_f32_16x16x32_bf16 v[210:213], v[12:15], v[206:209], v[44:47]
	s_waitcnt lgkmcnt(0)
	v_mfma_f32_16x16x32_bf16 v[44:47], v[12:15], v[106:109], v[20:23]
	ds_read_b128 v[12:15], v143 offset:2560
	s_waitcnt lgkmcnt(0)
	v_mfma_f32_16x16x32_bf16 v[40:43], v[12:15], v[106:109], v[8:11]
	s_nop 2
	ds_read_b128 v[8:11], v143 offset:5120
	s_waitcnt lgkmcnt(0)
	v_mfma_f32_16x16x32_bf16 v[28:31], v[8:11], v[106:109], v[24:27]
	s_nop 2
	ds_read_b128 v[24:27], v143 offset:7680
	v_mfma_f32_16x16x32_bf16 v[194:197], v[12:15], v[186:189], v[194:197]
	v_mfma_f32_16x16x32_bf16 v[218:221], v[12:15], v[206:209], v[68:71]
	v_mfma_f32_16x16x32_bf16 v[68:71], v[12:15], v[214:217], v[92:95]
	v_mfma_f32_16x16x32_bf16 v[60:63], v[12:15], v[84:87], v[110:113]
	v_mfma_f32_16x16x32_bf16 v[48:51], v[12:15], v[88:91], v[156:159]
	v_mfma_f32_16x16x32_bf16 v[92:95], v[8:11], v[186:189], v[16:19]
	v_mfma_f32_16x16x32_bf16 v[110:113], v[8:11], v[206:209], v[32:35]
	v_mfma_f32_16x16x32_bf16 v[20:23], v[8:11], v[214:217], v[198:201]
	v_mfma_f32_16x16x32_bf16 v[12:15], v[8:11], v[84:87], v[72:75]
	v_mfma_f32_16x16x32_bf16 v[36:39], v[8:11], v[88:91], v[102:105]
	s_waitcnt lgkmcnt(0)
	v_mfma_f32_16x16x32_bf16 v[102:105], v[24:27], v[186:189], v[202:205]
	v_mfma_f32_16x16x32_bf16 v[156:159], v[24:27], v[206:209], v[174:177]
	v_mfma_f32_16x16x32_bf16 v[16:19], v[24:27], v[214:217], v[178:181]
	v_mfma_f32_16x16x32_bf16 v[8:11], v[24:27], v[84:87], v[76:79]
	v_mfma_f32_16x16x32_bf16 v[32:35], v[24:27], v[88:91], v[80:83]
	v_mfma_f32_16x16x32_bf16 v[24:27], v[24:27], v[106:109], v[182:185]
	v_mul_f32_e32 v72, 0xbfb8aa3b, v190
	v_mul_f32_e32 v73, 0xbfb8aa3b, v191
	v_exp_f32_e32 v72, v72
	v_exp_f32_e32 v73, v73
	v_mul_f32_e32 v74, 0xbfb8aa3b, v192
	v_mul_f32_e32 v75, 0xbfb8aa3b, v193
	v_add_f32_e32 v72, 1.0, v72
	v_add_f32_e32 v73, 1.0, v73
	v_rcp_f32_e32 v72, v72
	v_rcp_f32_e32 v73, v73
	v_exp_f32_e32 v74, v74
	v_exp_f32_e32 v75, v75
	v_mul_f32_e32 v76, 0xbfb8aa3b, v211
	v_cvt_pk_bf16_f32 v72, v72, v73
	v_add_f32_e32 v73, 1.0, v74
	v_add_f32_e32 v74, 1.0, v75
	v_mul_f32_e32 v75, 0xbfb8aa3b, v210
	v_rcp_f32_e32 v73, v73
	v_rcp_f32_e32 v74, v74
	v_exp_f32_e32 v75, v75
	v_exp_f32_e32 v76, v76
	v_mul_f32_e32 v77, 0xbfb8aa3b, v213
	v_cvt_pk_bf16_f32 v73, v73, v74
	v_add_f32_e32 v74, 1.0, v75
	v_add_f32_e32 v75, 1.0, v76
	v_mul_f32_e32 v76, 0xbfb8aa3b, v212
	v_rcp_f32_e32 v74, v74
	v_rcp_f32_e32 v75, v75
	v_exp_f32_e32 v76, v76
	v_exp_f32_e32 v77, v77
	v_mul_f32_e32 v78, 0xbfb8aa3b, v195
	v_cvt_pk_bf16_f32 v74, v74, v75
	v_add_f32_e32 v75, 1.0, v76
	v_add_f32_e32 v76, 1.0, v77
	v_mul_f32_e32 v77, 0xbfb8aa3b, v194
	v_rcp_f32_e32 v75, v75
	v_rcp_f32_e32 v76, v76
	v_exp_f32_e32 v77, v77
	v_exp_f32_e32 v78, v78
	v_mul_f32_e32 v79, 0xbfb8aa3b, v197
	v_cvt_pk_bf16_f32 v75, v75, v76
; __device__ __forceinline__ float sigmoidf_(float x) { return __builtin_amdgcn_rcpf(1.f + __expf(-x)); }
; __device__ __forceinline__ void phase_merge(const Params& p, const int tidx) {
;     ...
; #pragma unroll
;       for (int br = 0; br < 2; br++)
; #pragma unroll
;         for (int i = 0; i < 4; i++)
; #pragma unroll
;           for (int j = 0; j < 2; j++) {
;             gp[br][i][j][0] = pack2(sigmoidf_(g6[i][2 * br + j][0]), sigmoidf_(g6[i][2 * br + j][1]));
;             gp[br][i][j][1] = pack2(sigmoidf_(g6[i][2 * br + j][2]), sigmoidf_(g6[i][2 * br + j][3]));
;           }
;       __syncthreads();
	v_add_f32_e32 v76, 1.0, v77
	v_add_f32_e32 v77, 1.0, v78
	v_mul_f32_e32 v78, 0xbfb8aa3b, v196
	v_rcp_f32_e32 v76, v76
	v_rcp_f32_e32 v77, v77
	v_exp_f32_e32 v78, v78
	v_exp_f32_e32 v79, v79
	v_mul_f32_e32 v56, 0xbfb8aa3b, v56
	v_mul_f32_e32 v57, 0xbfb8aa3b, v57
	v_cvt_pk_bf16_f32 v76, v76, v77
	v_add_f32_e32 v77, 1.0, v78
	v_add_f32_e32 v78, 1.0, v79
	v_mul_f32_e32 v79, 0xbfb8aa3b, v218
	v_mul_f32_e32 v80, 0xbfb8aa3b, v219
	v_exp_f32_e32 v56, v56
	v_exp_f32_e32 v57, v57
	v_rcp_f32_e32 v77, v77
	v_rcp_f32_e32 v78, v78
	v_exp_f32_e32 v79, v79
	v_exp_f32_e32 v80, v80
	v_add_f32_e32 v56, 1.0, v56
	v_add_f32_e32 v57, 1.0, v57
	v_mul_f32_e32 v58, 0xbfb8aa3b, v58
	v_mul_f32_e32 v59, 0xbfb8aa3b, v59
	v_cvt_pk_bf16_f32 v77, v77, v78
	v_add_f32_e32 v78, 1.0, v79
	v_add_f32_e32 v79, 1.0, v80
	v_mul_f32_e32 v80, 0xbfb8aa3b, v220
	v_mul_f32_e32 v81, 0xbfb8aa3b, v221
	v_rcp_f32_e32 v56, v56
	v_rcp_f32_e32 v57, v57
	v_exp_f32_e32 v58, v58
	v_exp_f32_e32 v59, v59
	v_rcp_f32_e32 v78, v78
	v_rcp_f32_e32 v79, v79
	v_exp_f32_e32 v80, v80
	v_exp_f32_e32 v81, v81
	v_cvt_pk_bf16_f32 v206, v56, v57
	v_add_f32_e32 v56, 1.0, v58
	v_add_f32_e32 v57, 1.0, v59
	v_mul_f32_e32 v58, 0xbfb8aa3b, v68
	v_mul_f32_e32 v59, 0xbfb8aa3b, v69
	v_cvt_pk_bf16_f32 v78, v78, v79
	v_add_f32_e32 v79, 1.0, v80
	v_add_f32_e32 v80, 1.0, v81
	v_mul_f32_e32 v81, 0xbfb8aa3b, v92
	v_mul_f32_e32 v82, 0xbfb8aa3b, v93
	v_rcp_f32_e32 v56, v56
	v_rcp_f32_e32 v57, v57
	v_exp_f32_e32 v58, v58
	v_exp_f32_e32 v59, v59
	v_rcp_f32_e32 v79, v79
	v_rcp_f32_e32 v80, v80
	v_exp_f32_e32 v81, v81
	v_exp_f32_e32 v82, v82
	v_cvt_pk_bf16_f32 v207, v56, v57
	v_add_f32_e32 v56, 1.0, v58
	v_add_f32_e32 v57, 1.0, v59
	v_mul_f32_e32 v58, 0xbfb8aa3b, v70
	v_mul_f32_e32 v59, 0xbfb8aa3b, v71
	v_cvt_pk_bf16_f32 v79, v79, v80
	v_add_f32_e32 v80, 1.0, v81
	v_add_f32_e32 v81, 1.0, v82
	v_mul_f32_e32 v82, 0xbfb8aa3b, v94
	v_mul_f32_e32 v83, 0xbfb8aa3b, v95
	v_rcp_f32_e32 v56, v56
	v_rcp_f32_e32 v57, v57
	v_exp_f32_e32 v58, v58
	v_exp_f32_e32 v59, v59
	v_rcp_f32_e32 v80, v80
	v_rcp_f32_e32 v81, v81
	v_exp_f32_e32 v82, v82
	v_exp_f32_e32 v83, v83
	v_mul_f32_e32 v20, 0xbfb8aa3b, v20
	v_cvt_pk_bf16_f32 v208, v56, v57
	v_add_f32_e32 v56, 1.0, v58
	v_add_f32_e32 v57, 1.0, v59
	v_mul_f32_e32 v58, 0xbfb8aa3b, v60
	v_exp_f32_e32 v20, v20
	v_mul_f32_e32 v21, 0xbfb8aa3b, v21
	v_cvt_pk_bf16_f32 v80, v80, v81
	v_add_f32_e32 v81, 1.0, v82
	v_add_f32_e32 v82, 1.0, v83
	v_mul_f32_e32 v83, 0xbfb8aa3b, v110
	v_mul_f32_e32 v84, 0xbfb8aa3b, v111
	v_rcp_f32_e32 v56, v56
	v_rcp_f32_e32 v57, v57
	v_exp_f32_e32 v58, v58
	v_mul_f32_e32 v59, 0xbfb8aa3b, v61
	v_exp_f32_e32 v21, v21
	v_rcp_f32_e32 v81, v81
	v_rcp_f32_e32 v82, v82
	v_exp_f32_e32 v83, v83
	v_exp_f32_e32 v84, v84
	v_exp_f32_e32 v59, v59
	v_add_f32_e32 v20, 1.0, v20
	v_cvt_pk_bf16_f32 v209, v56, v57
	v_add_f32_e32 v56, 1.0, v58
	v_mul_f32_e32 v58, 0xbfb8aa3b, v62
	v_rcp_f32_e32 v62, v20
	v_add_f32_e32 v20, 1.0, v21
	v_cvt_pk_bf16_f32 v81, v81, v82
	v_add_f32_e32 v82, 1.0, v83
	v_add_f32_e32 v83, 1.0, v84
	v_mul_f32_e32 v84, 0xbfb8aa3b, v112
	v_mul_f32_e32 v85, 0xbfb8aa3b, v113
	v_add_f32_e32 v57, 1.0, v59
	v_mul_f32_e32 v59, 0xbfb8aa3b, v63
	v_rcp_f32_e32 v63, v20
	v_mul_f32_e32 v20, 0xbfb8aa3b, v52
	v_mul_f32_e32 v21, 0xbfb8aa3b, v53
	v_rcp_f32_e32 v82, v82
	v_rcp_f32_e32 v83, v83
	v_exp_f32_e32 v84, v84
	v_exp_f32_e32 v85, v85
	v_exp_f32_e32 v20, v20
	v_exp_f32_e32 v21, v21
	v_cvt_pk_bf16_f32 v82, v82, v83
	v_add_f32_e32 v83, 1.0, v84
	v_add_f32_e32 v84, 1.0, v85
	v_mul_f32_e32 v85, 0xbfb8aa3b, v102
	v_mul_f32_e32 v86, 0xbfb8aa3b, v103
	v_add_f32_e32 v20, 1.0, v20
	v_add_f32_e32 v21, 1.0, v21
	v_mul_f32_e32 v52, 0xbfb8aa3b, v54
	v_mul_f32_e32 v53, 0xbfb8aa3b, v55
	v_rcp_f32_e32 v83, v83
	v_rcp_f32_e32 v84, v84
	v_exp_f32_e32 v85, v85
	v_exp_f32_e32 v86, v86
	v_rcp_f32_e32 v20, v20
	v_rcp_f32_e32 v21, v21
	v_exp_f32_e32 v52, v52
	v_exp_f32_e32 v53, v53
	v_mul_f32_e32 v44, 0xbfb8aa3b, v44
	v_mul_f32_e32 v45, 0xbfb8aa3b, v45
	v_exp_f32_e32 v44, v44
	v_exp_f32_e32 v45, v45
	v_cvt_pk_bf16_f32 v83, v83, v84
	v_add_f32_e32 v84, 1.0, v85
	v_add_f32_e32 v85, 1.0, v86
	v_mul_f32_e32 v86, 0xbfb8aa3b, v104
	v_mul_f32_e32 v87, 0xbfb8aa3b, v105
	v_cvt_pk_bf16_f32 v20, v20, v21
	v_add_f32_e32 v21, 1.0, v52
	v_add_f32_e32 v52, 1.0, v53
	v_rcp_f32_e32 v84, v84
	v_rcp_f32_e32 v85, v85
	v_exp_f32_e32 v86, v86
	v_exp_f32_e32 v87, v87
	v_rcp_f32_e32 v21, v21
	v_rcp_f32_e32 v52, v52
	v_add_f32_e32 v44, 1.0, v44
	v_add_f32_e32 v45, 1.0, v45
	v_mul_f32_e32 v46, 0xbfb8aa3b, v46
	v_mul_f32_e32 v47, 0xbfb8aa3b, v47
	v_rcp_f32_e32 v44, v44
	v_exp_f32_e32 v46, v46
	v_exp_f32_e32 v47, v47
	v_rcp_f32_e32 v45, v45
	v_cvt_pk_bf16_f32 v84, v84, v85
	v_add_f32_e32 v85, 1.0, v86
	v_add_f32_e32 v86, 1.0, v87
	v_mul_f32_e32 v87, 0xbfb8aa3b, v156
	v_mul_f32_e32 v88, 0xbfb8aa3b, v157
	v_cvt_pk_bf16_f32 v21, v21, v52
	v_rcp_f32_e32 v85, v85
	v_rcp_f32_e32 v86, v86
	v_exp_f32_e32 v87, v87
	v_exp_f32_e32 v88, v88
	s_barrier
; __device__ __forceinline__ float sigmoidf_(float x) { return __builtin_amdgcn_rcpf(1.f + __expf(-x)); }
;     ...
;   G_LOAD(ra0, rb0, 0);
;   G_LOAD(ra1, rb1, 64);
;   __syncthreads();
;   G_STORE(ra0, rb0, 0);
;   __syncthreads();
; __device__ __forceinline__ void phase_merge(const Params& p, const int tidx) {
;     ...
;       __syncthreads();
; #pragma unroll
;       for (int i = 0; i < 4; i++)
; #pragma unroll
;         for (int j = 0; j < 2; j++) {
;           sGate[((i * 2 + j) * 2 + 0) * NT + tidx] = pack2(sigmoidf_(g6[i][4 + j][0]), sigmoidf_(g6[i][4 + j][1]));
;           sGate[((i * 2 + j) * 2 + 1) * NT + tidx] = pack2(sigmoidf_(g6[i][4 + j][2]), sigmoidf_(g6[i][4 + j][3]));
;         }
;     }
;     f32x4 mg[4][2];
;     zero_acc<2>(mg);
; #pragma unroll
;     for (int br = 0; br < 3; br++) {
;       f32x4 t[4][2];
;       zero_acc<2>(t);
;       if (br == 0)
;         gemm_main<2, 512>(t, P + (size_t)mt * 256 * NP + OFF_AZ, NP, (const bf16_t*)(p.ws + WS_WAT) + (size_t)nt * 64 * 512, 512, sA, sB, tidx);
	v_add_f32_e32 v46, 1.0, v46
	v_add_f32_e32 v47, 1.0, v47
	ds_write_b32 v131, v21
	v_cvt_pk_bf16_f32 v21, v44, v45
	v_rcp_f32_e32 v46, v46
	v_rcp_f32_e32 v47, v47
	ds_write2st64_b32 v122, v20, v21 offset1:16
	v_mul_f32_e32 v21, 0xbfb8aa3b, v48
	v_mul_f32_e32 v44, 0xbfb8aa3b, v49
	v_exp_f32_e32 v21, v21
	v_exp_f32_e32 v44, v44
	v_cvt_pk_bf16_f32 v85, v85, v86
	v_add_f32_e32 v86, 1.0, v87
	v_add_f32_e32 v87, 1.0, v88
	v_mul_f32_e32 v88, 0xbfb8aa3b, v158
	v_mul_f32_e32 v89, 0xbfb8aa3b, v159
	v_rcp_f32_e32 v86, v86
	v_rcp_f32_e32 v87, v87
	v_exp_f32_e32 v88, v88
	v_exp_f32_e32 v89, v89
	v_cvt_pk_bf16_f32 v20, v46, v47
	ds_write_b32 v132, v20
	v_add_f32_e32 v20, 1.0, v21
	v_add_f32_e32 v21, 1.0, v44
	v_mul_f32_e32 v44, 0xbfb8aa3b, v50
	v_mul_f32_e32 v45, 0xbfb8aa3b, v51
	v_rcp_f32_e32 v20, v20
	v_rcp_f32_e32 v21, v21
	v_exp_f32_e32 v44, v44
	v_exp_f32_e32 v45, v45
	v_mul_f32_e32 v40, 0xbfb8aa3b, v40
	v_mul_f32_e32 v41, 0xbfb8aa3b, v41
	v_mul_f32_e32 v64, 0xbfb8aa3b, v64
	v_exp_f32_e32 v40, v40
	v_exp_f32_e32 v41, v41
	v_cvt_pk_bf16_f32 v86, v86, v87
	v_add_f32_e32 v87, 1.0, v88
	v_add_f32_e32 v88, 1.0, v89
	v_exp_f32_e32 v89, v64
	v_mul_f32_e32 v64, 0xbfb8aa3b, v65
	v_rcp_f32_e32 v87, v87
	v_rcp_f32_e32 v88, v88
	v_exp_f32_e32 v65, v64
	v_cvt_pk_bf16_f32 v20, v20, v21
	v_add_f32_e32 v21, 1.0, v44
	v_add_f32_e32 v44, 1.0, v45
	v_rcp_f32_e32 v21, v21
	v_rcp_f32_e32 v44, v44
	v_add_f32_e32 v40, 1.0, v40
	v_add_f32_e32 v41, 1.0, v41
	v_mul_f32_e32 v42, 0xbfb8aa3b, v42
	v_mul_f32_e32 v43, 0xbfb8aa3b, v43
	v_rcp_f32_e32 v40, v40
	v_exp_f32_e32 v42, v42
	v_exp_f32_e32 v43, v43
	v_rcp_f32_e32 v41, v41
	v_cvt_pk_bf16_f32 v64, v87, v88
	v_add_f32_e32 v87, 1.0, v89
	v_add_f32_e32 v65, 1.0, v65
	v_mul_f32_e32 v66, 0xbfb8aa3b, v66
	v_mul_f32_e32 v67, 0xbfb8aa3b, v67
	v_rcp_f32_e32 v87, v87
	v_rcp_f32_e32 v65, v65
	v_exp_f32_e32 v66, v66
	v_exp_f32_e32 v67, v67
	v_cvt_pk_bf16_f32 v21, v21, v44
	v_add_f32_e32 v42, 1.0, v42
	v_add_f32_e32 v43, 1.0, v43
	ds_write_b32 v133, v21
	v_cvt_pk_bf16_f32 v21, v40, v41
	v_rcp_f32_e32 v42, v42
	v_rcp_f32_e32 v43, v43
	ds_write2st64_b32 v122, v20, v21 offset0:32 offset1:48
	v_mul_f32_e32 v21, 0xbfb8aa3b, v36
	v_cvt_pk_bf16_f32 v204, v87, v65
	v_add_f32_e32 v65, 1.0, v66
	v_add_f32_e32 v66, 1.0, v67
	v_exp_f32_e32 v21, v21
	v_mul_f32_e32 v36, 0xbfb8aa3b, v37
	v_rcp_f32_e32 v65, v65
	v_rcp_f32_e32 v66, v66
	v_exp_f32_e32 v36, v36
	v_cvt_pk_bf16_f32 v20, v42, v43
	s_mul_i32 s10, s14, 0x3a0000
	v_rcp_f32_e32 v56, v56
	v_rcp_f32_e32 v57, v57
	v_exp_f32_e32 v58, v58
	v_exp_f32_e32 v59, v59
	ds_write_b32 v134, v20
	v_add_f32_e32 v20, 1.0, v21
	s_mul_hi_i32 s0, s14, 0x3a0000
	s_add_u32 s14, s94, s10
	v_cvt_pk_bf16_f32 v205, v65, v66
	v_rcp_f32_e32 v65, v20
	v_add_f32_e32 v20, 1.0, v36
	s_addc_u32 s15, s95, s0
	v_rcp_f32_e32 v66, v20
	v_mul_f32_e32 v20, 0xbfb8aa3b, v38
	v_lshl_add_u64 v[104:105], s[14:15], 0, v[2:3]
	s_mov_b32 s0, 0xe8000
	v_exp_f32_e32 v67, v20
	v_add_co_u32_e64 v20, s[10:11], s0, v104
	v_cvt_pk_bf16_f32 v210, v56, v57
	v_add_f32_e32 v56, 1.0, v58
	v_add_f32_e32 v57, 1.0, v59
	v_addc_co_u32_e64 v21, s[10:11], 0, v105, s[10:11]
	s_mov_b32 s0, 0x1d0000
	v_rcp_f32_e32 v56, v56
	v_rcp_f32_e32 v57, v57
	v_add_co_u32_e64 v36, s[10:11], s0, v104
	global_load_dwordx4 v[42:45], v[104:105], off offset:1024
	s_nop 0
	v_addc_co_u32_e64 v37, s[10:11], 0, v105, s[10:11]
	s_mov_b32 s0, 0x2b8000
	s_ashr_i32 s17, s16, 31
	global_load_dwordx4 v[46:49], v[20:21], off offset:1024
	global_load_dwordx4 v[50:53], v[36:37], off offset:1024
	v_add_co_u32_e64 v38, s[10:11], s0, v104
	v_mul_f32_e32 v68, 0xbfb8aa3b, v39
	s_lshl_b64 s[18:19], s[16:17], 16
	v_addc_co_u32_e64 v39, s[10:11], 0, v105, s[10:11]
	v_cvt_pk_bf16_f32 v211, v56, v57
	global_load_dwordx4 v[54:57], v[38:39], off offset:1024
	v_lshl_add_u64 v[40:41], v[96:97], 0, s[18:19]
	global_load_dwordx4 v[58:61], v[40:41], off
	v_mul_f32_e32 v28, 0xbfb8aa3b, v28
	v_mul_f32_e32 v29, 0xbfb8aa3b, v29
	v_exp_f32_e32 v28, v28
	v_exp_f32_e32 v29, v29
	v_mul_f32_e32 v30, 0xbfb8aa3b, v30
	v_mul_f32_e32 v31, 0xbfb8aa3b, v31
	v_exp_f32_e32 v30, v30
	v_exp_f32_e32 v31, v31
	v_add_f32_e32 v28, 1.0, v28
	v_add_f32_e32 v29, 1.0, v29
	v_rcp_f32_e32 v28, v28
	v_rcp_f32_e32 v29, v29
	v_add_f32_e32 v30, 1.0, v30
	v_add_f32_e32 v31, 1.0, v31
	v_rcp_f32_e32 v30, v30
	v_rcp_f32_e32 v31, v31
	v_cvt_pk_bf16_f32 v65, v65, v66
	v_cvt_pk_bf16_f32 v28, v28, v29
	ds_write2st64_b32 v122, v65, v28 offset0:64 offset1:80
	v_cvt_pk_bf16_f32 v28, v30, v31
	v_mul_f32_e32 v29, 0xbfb8aa3b, v32
	v_mul_f32_e32 v30, 0xbfb8aa3b, v33
	v_exp_f32_e32 v29, v29
	v_exp_f32_e32 v30, v30
	v_mul_f32_e32 v24, 0xbfb8aa3b, v24
	v_mul_f32_e32 v25, 0xbfb8aa3b, v25
	ds_write_b32 v136, v28
	v_add_f32_e32 v28, 1.0, v29
	v_add_f32_e32 v29, 1.0, v30
	v_mul_f32_e32 v30, 0xbfb8aa3b, v34
	v_mul_f32_e32 v31, 0xbfb8aa3b, v35
	v_exp_f32_e32 v24, v24
	v_exp_f32_e32 v25, v25
	v_mul_f32_e32 v26, 0xbfb8aa3b, v26
	v_mul_f32_e32 v27, 0xbfb8aa3b, v27
	v_exp_f32_e32 v68, v68
	v_rcp_f32_e32 v28, v28
	v_rcp_f32_e32 v29, v29
	v_exp_f32_e32 v30, v30
	v_exp_f32_e32 v31, v31
	v_exp_f32_e32 v26, v26
	v_exp_f32_e32 v27, v27
	v_add_f32_e32 v24, 1.0, v24
	v_add_f32_e32 v25, 1.0, v25
	v_add_f32_e32 v66, 1.0, v67
	v_add_f32_e32 v67, 1.0, v68
	v_cvt_pk_bf16_f32 v28, v28, v29
	v_add_f32_e32 v29, 1.0, v30
	v_add_f32_e32 v30, 1.0, v31
	v_rcp_f32_e32 v24, v24
	v_rcp_f32_e32 v25, v25
	v_add_f32_e32 v26, 1.0, v26
	v_add_f32_e32 v27, 1.0, v27
	v_rcp_f32_e32 v66, v66
	v_rcp_f32_e32 v67, v67
	v_rcp_f32_e32 v29, v29
	v_rcp_f32_e32 v30, v30
	v_rcp_f32_e32 v26, v26
	v_rcp_f32_e32 v27, v27
	v_cvt_pk_bf16_f32 v24, v24, v25
	v_cvt_pk_bf16_f32 v66, v66, v67
	v_cvt_pk_bf16_f32 v29, v29, v30
	ds_write2st64_b32 v122, v28, v24 offset0:96 offset1:112
	v_cvt_pk_bf16_f32 v24, v26, v27
	ds_write_b32 v135, v66
	ds_write_b32 v137, v29
	ds_write_b32 v138, v24
	global_load_dwordx4 v[24:27], v[104:105], off offset:1152
	global_load_dwordx4 v[28:31], v[20:21], off offset:1152
	global_load_dwordx4 v[32:35], v[36:37], off offset:1152
	global_load_dwordx4 v[66:69], v[38:39], off offset:1152
	global_load_dwordx4 v[88:91], v[40:41], off offset:128
	s_waitcnt lgkmcnt(0)
	s_barrier
; __device__ __forceinline__ float sigmoidf_(float x) { return __builtin_amdgcn_rcpf(1.f + __expf(-x)); }
;     ...
;   G_LOAD(ra0, rb0, 0);
;   G_LOAD(ra1, rb1, 64);
;   __syncthreads();
;   G_STORE(ra0, rb0, 0);
;   __syncthreads();
;   G_READ(fa0, fb0, 0, 0);
; #pragma unroll
;   for (int k0 = 0; k0 < K; k0 += 128) {
;     G_READ(fa1, fb1, 0, 32);
;     if (k0 + 128 < K) G_LOAD(ra0, rb0, k0 + 128);
;     __builtin_amdgcn_sched_barrier(0);
;     G_MFMA_ST(fa0, fb0, ra1, rb1, 1);
;     __syncthreads();
;     G_READ(fa0, fb0, 1, 0);
;     __builtin_amdgcn_sched_barrier(0);
;     G_MFMA(fa1, fb1);
;     __builtin_amdgcn_sched_barrier(0);
;     G_READ(fa1, fb1, 1, 32);
;     if (k0 + 192 < K) G_LOAD(ra1, rb1, k0 + 192);
;     __builtin_amdgcn_sched_barrier(0);
;     if (k0 + 128 < K) {
;       G_MFMA_ST(fa0, fb0, ra0, rb0, 0);
; __device__ __forceinline__ void phase_merge(const Params& p, const int tidx) {
;     ...
;       for (int br = 0; br < 2; br++)
; #pragma unroll
;         for (int i = 0; i < 4; i++)
; #pragma unroll
;           for (int j = 0; j < 2; j++) {
;             gp[br][i][j][0] = pack2(sigmoidf_(g6[i][2 * br + j][0]), sigmoidf_(g6[i][2 * br + j][1]));
;             gp[br][i][j][1] = pack2(sigmoidf_(g6[i][2 * br + j][2]), sigmoidf_(g6[i][2 * br + j][3]));
;           }
	s_waitcnt vmcnt(9)
	ds_write_b128 v125, v[42:45]
	s_waitcnt vmcnt(8)
	ds_write_b128 v145, v[46:49]
	s_waitcnt vmcnt(7)
	ds_write_b128 v145, v[50:53] offset:10240
	s_waitcnt vmcnt(6)
	ds_write_b128 v145, v[54:57] offset:20480
	s_waitcnt vmcnt(5)
	ds_write_b128 v125, v[58:61] offset:40960
	s_waitcnt lgkmcnt(0)
	s_barrier
	global_load_dwordx4 v[42:45], v[104:105], off offset:1280
	global_load_dwordx4 v[46:49], v[20:21], off offset:1280
	global_load_dwordx4 v[50:53], v[36:37], off offset:1280
	global_load_dwordx4 v[54:57], v[38:39], off offset:1280
	global_load_dwordx4 v[58:61], v[40:41], off offset:256
	v_mul_f32_e32 v12, 0xbfb8aa3b, v12
	v_mul_f32_e32 v13, 0xbfb8aa3b, v13
	v_exp_f32_e32 v12, v12
	v_exp_f32_e32 v13, v13
	v_mul_f32_e32 v14, 0xbfb8aa3b, v14
	v_mul_f32_e32 v15, 0xbfb8aa3b, v15
	v_add_f32_e32 v12, 1.0, v12
	v_add_f32_e32 v13, 1.0, v13
	v_rcp_f32_e32 v12, v12
	v_rcp_f32_e32 v13, v13
	v_exp_f32_e32 v14, v14
	v_exp_f32_e32 v15, v15
	v_mul_f32_e32 v8, 0xbfb8aa3b, v8
	v_cvt_pk_bf16_f32 v214, v12, v13
	v_add_f32_e32 v12, 1.0, v14
	v_add_f32_e32 v13, 1.0, v15
	v_mul_f32_e32 v14, 0xbfb8aa3b, v16
	v_mul_f32_e32 v15, 0xbfb8aa3b, v17
	v_rcp_f32_e32 v12, v12
	v_rcp_f32_e32 v13, v13
	v_exp_f32_e32 v14, v14
	v_exp_f32_e32 v15, v15
	v_mul_f32_e32 v9, 0xbfb8aa3b, v9
	v_mul_f32_e32 v22, 0xbfb8aa3b, v22
	v_mul_f32_e32 v23, 0xbfb8aa3b, v23
	v_exp_f32_e32 v8, v8
	v_exp_f32_e32 v9, v9
	v_exp_f32_e32 v22, v22
	v_exp_f32_e32 v23, v23
	v_cvt_pk_bf16_f32 v215, v12, v13
	v_add_f32_e32 v12, 1.0, v14
	v_add_f32_e32 v13, 1.0, v15
	v_mul_f32_e32 v14, 0xbfb8aa3b, v18
	v_mul_f32_e32 v15, 0xbfb8aa3b, v19
	v_rcp_f32_e32 v12, v12
	v_rcp_f32_e32 v13, v13
	v_exp_f32_e32 v14, v14
	v_exp_f32_e32 v15, v15
	v_add_f32_e32 v8, 1.0, v8
	v_add_f32_e32 v9, 1.0, v9
	v_mul_f32_e32 v10, 0xbfb8aa3b, v10
	v_add_f32_e32 v22, 1.0, v22
	v_add_f32_e32 v23, 1.0, v23
	v_rcp_f32_e32 v8, v8
	v_rcp_f32_e32 v9, v9
	v_exp_f32_e32 v10, v10
	v_mul_f32_e32 v11, 0xbfb8aa3b, v11
	v_rcp_f32_e32 v22, v22
	v_rcp_f32_e32 v23, v23
	v_cvt_pk_bf16_f32 v216, v12, v13
	v_add_f32_e32 v12, 1.0, v14
	v_add_f32_e32 v13, 1.0, v15
	v_exp_f32_e32 v11, v11
	v_rcp_f32_e32 v12, v12
	v_rcp_f32_e32 v13, v13
	v_cvt_pk_bf16_f32 v218, v8, v9
	v_add_f32_e32 v8, 1.0, v10
	v_cvt_pk_bf16_f32 v213, v22, v23
	v_rcp_f32_e32 v22, v8
	v_add_f32_e32 v8, 1.0, v11
	v_add_u32_e32 v202, v120, v123
	v_cvt_pk_bf16_f32 v217, v12, v13
	v_rcp_f32_e32 v23, v8
	ds_read_b128 v[8:11], v202 offset:40960
	ds_read_b128 v[12:15], v202 offset:43520
	ds_read_b128 v[16:19], v124
	ds_read_b128 v[92:95], v124 offset:64
	ds_read_b128 v[108:111], v124 offset:2560
	ds_read_b128 v[112:115], v124 offset:2624
	ds_read_b128 v[156:159], v124 offset:5120
	ds_read_b128 v[174:177], v124 offset:5184
	ds_read_b128 v[178:181], v124 offset:7680
	ds_read_b128 v[182:185], v124 offset:7744
	ds_read_b128 v[186:189], v146 offset:41024
	ds_read_b128 v[190:193], v146 offset:43584
	s_mov_b64 s[10:11], 0x1400
	v_lshl_add_u64 v[106:107], v[104:105], 0, s[10:11]
	s_lshl_b64 s[16:17], s[16:17], 17
	s_mov_b64 s[10:11], 0x3200
	v_cvt_pk_bf16_f32 v212, v62, v63
	v_cvt_pk_bf16_f32 v219, v22, v23
	v_lshl_add_u64 v[102:103], v[104:105], 0, s[10:11]
	s_waitcnt lgkmcnt(9)
	v_mfma_f32_16x16x32_bf16 v[194:197], v[16:19], v[8:11], 0
	s_waitcnt vmcnt(9)
	ds_write_b128 v125, v[24:27] offset:61440
	s_waitcnt vmcnt(5)
	ds_write_b128 v126, v[88:91]
	v_mfma_f32_16x16x32_bf16 v[16:19], v[16:19], v[12:15], 0
	s_waitcnt lgkmcnt(9)
	v_mfma_f32_16x16x32_bf16 v[22:25], v[108:111], v[8:11], 0
	ds_write_b128 v127, v[28:31] offset:61440
	v_mfma_f32_16x16x32_bf16 v[26:29], v[108:111], v[12:15], 0
	s_waitcnt lgkmcnt(8)
	v_mfma_f32_16x16x32_bf16 v[88:91], v[156:159], v[8:11], 0
	ds_write_b128 v128, v[32:35] offset:61440
	v_mfma_f32_16x16x32_bf16 v[30:33], v[156:159], v[12:15], 0
	s_waitcnt lgkmcnt(7)
	v_mfma_f32_16x16x32_bf16 v[8:11], v[178:181], v[8:11], 0
	ds_write_b128 v129, v[66:69] offset:61440
	v_mfma_f32_16x16x32_bf16 v[12:15], v[178:181], v[12:15], 0
	s_waitcnt lgkmcnt(0)
	s_barrier
	ds_read_b128 v[66:69], v124 offset:61440
	ds_read_b128 v[108:111], v124 offset:64000
	ds_read_b128 v[156:159], v147 offset:5120
	ds_read_b128 v[178:181], v147 offset:7680
	ds_read_b128 v[198:201], v151
	ds_read_b128 v[220:223], v151 offset:2560
	v_mfma_f32_16x16x32_bf16 v[194:197], v[92:95], v[186:189], v[194:197]
	v_mfma_f32_16x16x32_bf16 v[16:19], v[92:95], v[190:193], v[16:19]
	v_mfma_f32_16x16x32_bf16 v[22:25], v[112:115], v[186:189], v[22:25]
	v_mfma_f32_16x16x32_bf16 v[26:29], v[112:115], v[190:193], v[26:29]
	v_mfma_f32_16x16x32_bf16 v[88:91], v[174:177], v[186:189], v[88:91]
	v_mfma_f32_16x16x32_bf16 v[30:33], v[174:177], v[190:193], v[30:33]
	v_mfma_f32_16x16x32_bf16 v[8:11], v[182:185], v[186:189], v[8:11]
	v_mfma_f32_16x16x32_bf16 v[12:15], v[182:185], v[190:193], v[12:15]
	global_load_dwordx4 v[92:95], v[104:105], off offset:1408
	global_load_dwordx4 v[112:115], v[20:21], off offset:1408
	global_load_dwordx4 v[174:177], v[36:37], off offset:1408
	global_load_dwordx4 v[182:185], v[38:39], off offset:1408
	global_load_dwordx4 v[186:189], v[40:41], off offset:384
	ds_read_b128 v[190:193], v124 offset:61504
	ds_read_b128 v[224:227], v124 offset:64064
	ds_read_b128 v[228:231], v152 offset:64
	ds_read_b128 v[232:235], v153 offset:64
	v_add_u32_e32 v203, v130, v117
	ds_read_b128 v[236:239], v203 offset:64
	ds_read_b128 v[240:243], v154 offset:64
	s_waitcnt lgkmcnt(7)
	v_mfma_f32_16x16x32_bf16 v[194:197], v[66:69], v[198:201], v[194:197]
	s_waitcnt vmcnt(9)
	ds_write_b128 v125, v[42:45]
	s_waitcnt vmcnt(5)
	ds_write_b128 v125, v[58:61] offset:40960
	s_waitcnt lgkmcnt(8)
	v_mfma_f32_16x16x32_bf16 v[16:19], v[66:69], v[220:223], v[16:19]
	v_mfma_f32_16x16x32_bf16 v[22:25], v[108:111], v[198:201], v[22:25]
	ds_write_b128 v125, v[46:49] offset:10240
	v_mfma_f32_16x16x32_bf16 v[26:29], v[108:111], v[220:223], v[26:29]
	v_mfma_f32_16x16x32_bf16 v[42:45], v[156:159], v[198:201], v[88:91]
	ds_write_b128 v125, v[50:53] offset:20480
	v_mfma_f32_16x16x32_bf16 v[30:33], v[156:159], v[220:223], v[30:33]
	v_mfma_f32_16x16x32_bf16 v[8:11], v[178:181], v[198:201], v[8:11]
	ds_write_b128 v125, v[54:57] offset:30720
	v_mfma_f32_16x16x32_bf16 v[12:15], v[178:181], v[220:223], v[12:15]
	s_waitcnt lgkmcnt(0)
	s_barrier
;     ...
;   for (int k0 = 0; k0 < K; k0 += 128) {
;     G_READ(fa1, fb1, 0, 32);
;     if (k0 + 128 < K) G_LOAD(ra0, rb0, k0 + 128);
;     __builtin_amdgcn_sched_barrier(0);
;     G_MFMA_ST(fa0, fb0, ra1, rb1, 1);
;     __syncthreads();
;     G_READ(fa0, fb0, 1, 0);
;     __builtin_amdgcn_sched_barrier(0);
;     G_MFMA(fa1, fb1);
;     __builtin_amdgcn_sched_barrier(0);
;     G_READ(fa1, fb1, 1, 32);
;     if (k0 + 192 < K) G_LOAD(ra1, rb1, k0 + 192);
;     __builtin_amdgcn_sched_barrier(0);
;     if (k0 + 128 < K) {
;       G_MFMA_ST(fa0, fb0, ra0, rb0, 0);
;       __syncthreads();
;       G_READ(fa0, fb0, 0, 0);
;     } else {
;       G_MFMA(fa0, fb0);
;     }
;     __builtin_amdgcn_sched_barrier(0);
;     G_MFMA(fa1, fb1);
;     __builtin_amdgcn_sched_barrier(0);
;   }
	ds_read_b128 v[46:49], v124
	ds_read_b128 v[50:53], v124 offset:2560
	ds_read_b128 v[54:57], v124 offset:5120
	ds_read_b128 v[58:61], v124 offset:7680
	ds_read_b128 v[66:69], v202 offset:40960
	ds_read_b128 v[88:91], v202 offset:43520
	v_mfma_f32_16x16x32_bf16 v[108:111], v[190:193], v[236:239], v[194:197]
	v_mfma_f32_16x16x32_bf16 v[16:19], v[190:193], v[240:243], v[16:19]
	v_mfma_f32_16x16x32_bf16 v[22:25], v[224:227], v[236:239], v[22:25]
	v_mfma_f32_16x16x32_bf16 v[26:29], v[224:227], v[240:243], v[26:29]
	v_mfma_f32_16x16x32_bf16 v[42:45], v[228:231], v[236:239], v[42:45]
	v_mfma_f32_16x16x32_bf16 v[30:33], v[228:231], v[240:243], v[30:33]
	v_mfma_f32_16x16x32_bf16 v[8:11], v[232:235], v[236:239], v[8:11]
	v_mfma_f32_16x16x32_bf16 v[12:15], v[232:235], v[240:243], v[12:15]
	global_load_dwordx4 v[156:159], v[104:105], off offset:1536
	global_load_dwordx4 v[178:181], v[20:21], off offset:1536
	global_load_dwordx4 v[190:193], v[36:37], off offset:1536
	global_load_dwordx4 v[194:197], v[38:39], off offset:1536
	global_load_dwordx4 v[198:201], v[40:41], off offset:512
	ds_read_b128 v[220:223], v124 offset:64
	ds_read_b128 v[224:227], v124 offset:2624
	ds_read_b128 v[228:231], v124 offset:5184
	ds_read_b128 v[232:235], v124 offset:7744
	ds_read_b128 v[236:239], v146 offset:41024
	ds_read_b128 v[240:243], v146 offset:43584
	s_waitcnt lgkmcnt(7)
	v_mfma_f32_16x16x32_bf16 v[108:111], v[46:49], v[66:69], v[108:111]
	s_waitcnt vmcnt(9)
	ds_write_b128 v125, v[92:95] offset:61440
	s_waitcnt vmcnt(5)
	ds_write_b128 v126, v[186:189]
	s_waitcnt lgkmcnt(8)
	v_mfma_f32_16x16x32_bf16 v[16:19], v[46:49], v[88:91], v[16:19]
	v_mfma_f32_16x16x32_bf16 v[22:25], v[50:53], v[66:69], v[22:25]
	ds_write_b128 v127, v[112:115] offset:61440
	v_mfma_f32_16x16x32_bf16 v[26:29], v[50:53], v[88:91], v[26:29]
	v_mfma_f32_16x16x32_bf16 v[42:45], v[54:57], v[66:69], v[42:45]
	ds_write_b128 v128, v[174:177] offset:61440
	v_mfma_f32_16x16x32_bf16 v[30:33], v[54:57], v[88:91], v[30:33]
	v_mfma_f32_16x16x32_bf16 v[8:11], v[58:61], v[66:69], v[8:11]
	ds_write_b128 v129, v[182:185] offset:61440
	v_mfma_f32_16x16x32_bf16 v[12:15], v[58:61], v[88:91], v[12:15]
	s_waitcnt lgkmcnt(0)
	s_barrier
	ds_read_b128 v[46:49], v124 offset:61440
	ds_read_b128 v[50:53], v124 offset:64000
	ds_read_b128 v[54:57], v147 offset:5120
	ds_read_b128 v[58:61], v147 offset:7680
	ds_read_b128 v[66:69], v151
	ds_read_b128 v[88:91], v151 offset:2560
	v_mfma_f32_16x16x32_bf16 v[92:95], v[220:223], v[236:239], v[108:111]
	v_mfma_f32_16x16x32_bf16 v[16:19], v[220:223], v[240:243], v[16:19]
	v_mfma_f32_16x16x32_bf16 v[22:25], v[224:227], v[236:239], v[22:25]
	v_mfma_f32_16x16x32_bf16 v[26:29], v[224:227], v[240:243], v[26:29]
	v_mfma_f32_16x16x32_bf16 v[42:45], v[228:231], v[236:239], v[42:45]
	v_mfma_f32_16x16x32_bf16 v[30:33], v[228:231], v[240:243], v[30:33]
	v_mfma_f32_16x16x32_bf16 v[8:11], v[232:235], v[236:239], v[8:11]
	v_mfma_f32_16x16x32_bf16 v[12:15], v[232:235], v[240:243], v[12:15]
	global_load_dwordx4 v[108:111], v[104:105], off offset:1664
	global_load_dwordx4 v[112:115], v[20:21], off offset:1664
	global_load_dwordx4 v[174:177], v[36:37], off offset:1664
	global_load_dwordx4 v[182:185], v[38:39], off offset:1664
	global_load_dwordx4 v[186:189], v[40:41], off offset:640
	ds_read_b128 v[220:223], v124 offset:61504
	ds_read_b128 v[224:227], v124 offset:64064
	ds_read_b128 v[228:231], v152 offset:64
	ds_read_b128 v[232:235], v153 offset:64
	ds_read_b128 v[236:239], v203 offset:64
	ds_read_b128 v[240:243], v154 offset:64
	s_waitcnt lgkmcnt(7)
	v_mfma_f32_16x16x32_bf16 v[92:95], v[46:49], v[66:69], v[92:95]
	s_waitcnt vmcnt(9)
	ds_write_b128 v125, v[156:159]
	s_waitcnt vmcnt(5)
	ds_write_b128 v125, v[198:201] offset:40960
	s_waitcnt lgkmcnt(8)
	v_mfma_f32_16x16x32_bf16 v[16:19], v[46:49], v[88:91], v[16:19]
	v_mfma_f32_16x16x32_bf16 v[22:25], v[50:53], v[66:69], v[22:25]
	ds_write_b128 v125, v[178:181] offset:10240
	v_mfma_f32_16x16x32_bf16 v[26:29], v[50:53], v[88:91], v[26:29]
	v_mfma_f32_16x16x32_bf16 v[42:45], v[54:57], v[66:69], v[42:45]
	ds_write_b128 v125, v[190:193] offset:20480
	v_mfma_f32_16x16x32_bf16 v[30:33], v[54:57], v[88:91], v[30:33]
	v_mfma_f32_16x16x32_bf16 v[8:11], v[58:61], v[66:69], v[8:11]
	ds_write_b128 v125, v[194:197] offset:30720
	v_mfma_f32_16x16x32_bf16 v[12:15], v[58:61], v[88:91], v[12:15]
	s_waitcnt lgkmcnt(0)
	s_barrier
	ds_read_b128 v[46:49], v124
	ds_read_b128 v[50:53], v124 offset:2560
	ds_read_b128 v[54:57], v124 offset:5120
	ds_read_b128 v[58:61], v124 offset:7680
	ds_read_b128 v[66:69], v202 offset:40960
	ds_read_b128 v[88:91], v202 offset:43520
	v_mfma_f32_16x16x32_bf16 v[92:95], v[220:223], v[236:239], v[92:95]
	v_mfma_f32_16x16x32_bf16 v[16:19], v[220:223], v[240:243], v[16:19]
	v_mfma_f32_16x16x32_bf16 v[22:25], v[224:227], v[236:239], v[22:25]
	v_mfma_f32_16x16x32_bf16 v[26:29], v[224:227], v[240:243], v[26:29]
	v_mfma_f32_16x16x32_bf16 v[42:45], v[228:231], v[236:239], v[42:45]
	v_mfma_f32_16x16x32_bf16 v[30:33], v[228:231], v[240:243], v[30:33]
	v_mfma_f32_16x16x32_bf16 v[8:11], v[232:235], v[236:239], v[8:11]
	v_mfma_f32_16x16x32_bf16 v[12:15], v[232:235], v[240:243], v[12:15]
	global_load_dwordx4 v[156:159], v[104:105], off offset:1792
	global_load_dwordx4 v[178:181], v[20:21], off offset:1792
	global_load_dwordx4 v[190:193], v[36:37], off offset:1792
	global_load_dwordx4 v[194:197], v[38:39], off offset:1792
	global_load_dwordx4 v[198:201], v[40:41], off offset:768
	ds_read_b128 v[220:223], v124 offset:64
	ds_read_b128 v[224:227], v124 offset:2624
	ds_read_b128 v[228:231], v124 offset:5184
	ds_read_b128 v[232:235], v124 offset:7744
	ds_read_b128 v[236:239], v146 offset:41024
	ds_read_b128 v[240:243], v146 offset:43584
	s_waitcnt lgkmcnt(7)
	v_mfma_f32_16x16x32_bf16 v[92:95], v[46:49], v[66:69], v[92:95]
	s_waitcnt vmcnt(9)
	ds_write_b128 v125, v[108:111] offset:61440
	s_waitcnt vmcnt(5)
	ds_write_b128 v126, v[186:189]
	s_waitcnt lgkmcnt(8)
	v_mfma_f32_16x16x32_bf16 v[16:19], v[46:49], v[88:91], v[16:19]
	v_mfma_f32_16x16x32_bf16 v[22:25], v[50:53], v[66:69], v[22:25]
	ds_write_b128 v127, v[112:115] offset:61440
	v_mfma_f32_16x16x32_bf16 v[26:29], v[50:53], v[88:91], v[26:29]
	v_mfma_f32_16x16x32_bf16 v[42:45], v[54:57], v[66:69], v[42:45]
	ds_write_b128 v128, v[174:177] offset:61440
	v_mfma_f32_16x16x32_bf16 v[30:33], v[54:57], v[88:91], v[30:33]
	v_mfma_f32_16x16x32_bf16 v[8:11], v[58:61], v[66:69], v[8:11]
	ds_write_b128 v129, v[182:185] offset:61440
	v_mfma_f32_16x16x32_bf16 v[12:15], v[58:61], v[88:91], v[12:15]
	s_waitcnt lgkmcnt(0)
	s_barrier
;     ...
;   for (int k0 = 0; k0 < K; k0 += 128) {
;     G_READ(fa1, fb1, 0, 32);
;     if (k0 + 128 < K) G_LOAD(ra0, rb0, k0 + 128);
;     __builtin_amdgcn_sched_barrier(0);
;     G_MFMA_ST(fa0, fb0, ra1, rb1, 1);
;     __syncthreads();
;     G_READ(fa0, fb0, 1, 0);
;     __builtin_amdgcn_sched_barrier(0);
;     G_MFMA(fa1, fb1);
;     __builtin_amdgcn_sched_barrier(0);
;     G_READ(fa1, fb1, 1, 32);
;     if (k0 + 192 < K) G_LOAD(ra1, rb1, k0 + 192);
;     __builtin_amdgcn_sched_barrier(0);
;     if (k0 + 128 < K) {
;       G_MFMA_ST(fa0, fb0, ra0, rb0, 0);
;       __syncthreads();
;       G_READ(fa0, fb0, 0, 0);
;     } else {
;       G_MFMA(fa0, fb0);
;     }
;     __builtin_amdgcn_sched_barrier(0);
;     G_MFMA(fa1, fb1);
;     __builtin_amdgcn_sched_barrier(0);
;   }
	ds_read_b128 v[46:49], v124 offset:61440
	ds_read_b128 v[50:53], v124 offset:64000
	ds_read_b128 v[54:57], v147 offset:5120
	ds_read_b128 v[58:61], v147 offset:7680
	ds_read_b128 v[66:69], v151
	ds_read_b128 v[88:91], v151 offset:2560
	v_mfma_f32_16x16x32_bf16 v[92:95], v[220:223], v[236:239], v[92:95]
	v_mfma_f32_16x16x32_bf16 v[16:19], v[220:223], v[240:243], v[16:19]
	v_mfma_f32_16x16x32_bf16 v[22:25], v[224:227], v[236:239], v[22:25]
	v_mfma_f32_16x16x32_bf16 v[26:29], v[224:227], v[240:243], v[26:29]
	v_mfma_f32_16x16x32_bf16 v[42:45], v[228:231], v[236:239], v[42:45]
	v_mfma_f32_16x16x32_bf16 v[30:33], v[228:231], v[240:243], v[30:33]
	v_mfma_f32_16x16x32_bf16 v[8:11], v[232:235], v[236:239], v[8:11]
	v_mfma_f32_16x16x32_bf16 v[12:15], v[232:235], v[240:243], v[12:15]
	global_load_dwordx4 v[108:111], v[104:105], off offset:1920
	global_load_dwordx4 v[112:115], v[20:21], off offset:1920
	s_nop 0
	global_load_dwordx4 v[34:37], v[36:37], off offset:1920
	s_nop 0
	global_load_dwordx4 v[174:177], v[38:39], off offset:1920
	s_nop 0
	global_load_dwordx4 v[38:41], v[40:41], off offset:896
	ds_read_b128 v[182:185], v124 offset:61504
	ds_read_b128 v[186:189], v124 offset:64064
	ds_read_b128 v[220:223], v152 offset:64
	ds_read_b128 v[224:227], v153 offset:64
	ds_read_b128 v[228:231], v203 offset:64
	ds_read_b128 v[232:235], v154 offset:64
	s_waitcnt lgkmcnt(7)
	v_mfma_f32_16x16x32_bf16 v[92:95], v[46:49], v[66:69], v[92:95]
	s_waitcnt vmcnt(9)
	ds_write_b128 v125, v[156:159]
	s_waitcnt vmcnt(5)
	ds_write_b128 v125, v[198:201] offset:40960
	s_waitcnt lgkmcnt(8)
	v_mfma_f32_16x16x32_bf16 v[16:19], v[46:49], v[88:91], v[16:19]
	v_mfma_f32_16x16x32_bf16 v[20:23], v[50:53], v[66:69], v[22:25]
	ds_write_b128 v125, v[178:181] offset:10240
	v_mfma_f32_16x16x32_bf16 v[24:27], v[50:53], v[88:91], v[26:29]
	v_mfma_f32_16x16x32_bf16 v[42:45], v[54:57], v[66:69], v[42:45]
	ds_write_b128 v125, v[190:193] offset:20480
	v_mfma_f32_16x16x32_bf16 v[28:31], v[54:57], v[88:91], v[30:33]
	v_mfma_f32_16x16x32_bf16 v[8:11], v[58:61], v[66:69], v[8:11]
	ds_write_b128 v125, v[194:197] offset:30720
	v_mfma_f32_16x16x32_bf16 v[12:15], v[58:61], v[88:91], v[12:15]
	s_waitcnt lgkmcnt(0)
	s_barrier
	ds_read_b128 v[46:49], v124
	ds_read_b128 v[50:53], v124 offset:2560
	ds_read_b128 v[54:57], v124 offset:5120
	ds_read_b128 v[58:61], v124 offset:7680
	ds_read_b128 v[66:69], v202 offset:40960
	ds_read_b128 v[88:91], v202 offset:43520
	v_mfma_f32_16x16x32_bf16 v[92:95], v[182:185], v[228:231], v[92:95]
	v_mfma_f32_16x16x32_bf16 v[16:19], v[182:185], v[232:235], v[16:19]
	v_mfma_f32_16x16x32_bf16 v[20:23], v[186:189], v[228:231], v[20:23]
	v_mfma_f32_16x16x32_bf16 v[24:27], v[186:189], v[232:235], v[24:27]
	v_mfma_f32_16x16x32_bf16 v[42:45], v[220:223], v[228:231], v[42:45]
	v_mfma_f32_16x16x32_bf16 v[28:31], v[220:223], v[232:235], v[28:31]
	v_mfma_f32_16x16x32_bf16 v[8:11], v[224:227], v[228:231], v[8:11]
	v_mfma_f32_16x16x32_bf16 v[12:15], v[224:227], v[232:235], v[12:15]
	ds_read_b128 v[156:159], v124 offset:64
	ds_read_b128 v[178:181], v124 offset:2624
	ds_read_b128 v[182:185], v124 offset:5184
	ds_read_b128 v[186:189], v124 offset:7744
	ds_read_b128 v[190:193], v146 offset:41024
	ds_read_b128 v[194:197], v146 offset:43584
	s_waitcnt lgkmcnt(7)
	v_mfma_f32_16x16x32_bf16 v[92:95], v[46:49], v[66:69], v[92:95]
	s_waitcnt vmcnt(4)
	ds_write_b128 v125, v[108:111] offset:61440
	s_waitcnt vmcnt(0)
	ds_write_b128 v126, v[38:41]
	s_waitcnt lgkmcnt(8)
	v_mfma_f32_16x16x32_bf16 v[16:19], v[46:49], v[88:91], v[16:19]
	v_mfma_f32_16x16x32_bf16 v[20:23], v[50:53], v[66:69], v[20:23]
	ds_write_b128 v127, v[112:115] offset:61440
	v_mfma_f32_16x16x32_bf16 v[24:27], v[50:53], v[88:91], v[24:27]
	v_mfma_f32_16x16x32_bf16 v[38:41], v[54:57], v[66:69], v[42:45]
	ds_write_b128 v128, v[34:37] offset:61440
	v_mfma_f32_16x16x32_bf16 v[28:31], v[54:57], v[88:91], v[28:31]
	v_mfma_f32_16x16x32_bf16 v[8:11], v[58:61], v[66:69], v[8:11]
	ds_write_b128 v129, v[174:177] offset:61440
	v_mfma_f32_16x16x32_bf16 v[12:15], v[58:61], v[88:91], v[12:15]
	s_waitcnt lgkmcnt(0)
	s_barrier
	ds_read_b128 v[32:35], v124 offset:61440
	ds_read_b128 v[42:45], v124 offset:64000
	ds_read_b128 v[46:49], v147 offset:5120
	ds_read_b128 v[50:53], v147 offset:7680
	ds_read_b128 v[54:57], v151
	ds_read_b128 v[58:61], v151 offset:2560
	v_mfma_f32_16x16x32_bf16 v[66:69], v[156:159], v[190:193], v[92:95]
	v_mfma_f32_16x16x32_bf16 v[16:19], v[156:159], v[194:197], v[16:19]
	v_mfma_f32_16x16x32_bf16 v[20:23], v[178:181], v[190:193], v[20:23]
	v_mfma_f32_16x16x32_bf16 v[24:27], v[178:181], v[194:197], v[24:27]
	v_mfma_f32_16x16x32_bf16 v[36:39], v[182:185], v[190:193], v[38:41]
	v_mfma_f32_16x16x32_bf16 v[28:31], v[182:185], v[194:197], v[28:31]
	v_mfma_f32_16x16x32_bf16 v[8:11], v[186:189], v[190:193], v[8:11]
	v_mfma_f32_16x16x32_bf16 v[12:15], v[186:189], v[194:197], v[12:15]
	ds_read_b128 v[88:91], v124 offset:61504
	ds_read_b128 v[92:95], v124 offset:64064
	ds_read_b128 v[108:111], v152 offset:64
	ds_read_b128 v[112:115], v153 offset:64
	ds_read_b128 v[156:159], v203 offset:64
	ds_read_b128 v[174:177], v154 offset:64
	s_waitcnt lgkmcnt(7)
	v_mfma_f32_16x16x32_bf16 v[66:69], v[32:35], v[54:57], v[66:69]
	s_waitcnt lgkmcnt(6)
	v_mfma_f32_16x16x32_bf16 v[16:19], v[32:35], v[58:61], v[16:19]
	v_mfma_f32_16x16x32_bf16 v[20:23], v[42:45], v[54:57], v[20:23]
	v_mfma_f32_16x16x32_bf16 v[24:27], v[42:45], v[58:61], v[24:27]
	v_mfma_f32_16x16x32_bf16 v[32:35], v[46:49], v[54:57], v[36:39]
	v_mfma_f32_16x16x32_bf16 v[28:31], v[46:49], v[58:61], v[28:31]
	v_mfma_f32_16x16x32_bf16 v[8:11], v[50:53], v[54:57], v[8:11]
	v_mfma_f32_16x16x32_bf16 v[12:15], v[50:53], v[58:61], v[12:15]
	s_waitcnt lgkmcnt(1)
; __device__ __forceinline__ float bflo(unsigned w) { return __uint_as_float(w << 16); }
; __device__ __forceinline__ float bfhi(unsigned w) { return __uint_as_float(w & 0xffff0000u); }
;     ...
;   G_LOAD(ra0, rb0, 0);
;   G_LOAD(ra1, rb1, 64);
;   __syncthreads();
;   G_STORE(ra0, rb0, 0);
;   __syncthreads();
;   G_READ(fa0, fb0, 0, 0);
; #pragma unroll
;   for (int k0 = 0; k0 < K; k0 += 128) {
;     G_READ(fa1, fb1, 0, 32);
;     if (k0 + 128 < K) G_LOAD(ra0, rb0, k0 + 128);
;     __builtin_amdgcn_sched_barrier(0);
;     G_MFMA_ST(fa0, fb0, ra1, rb1, 1);
;     __syncthreads();
;     G_READ(fa0, fb0, 1, 0);
; __device__ __forceinline__ void phase_merge(const Params& p, const int tidx) {
;     ...
; #pragma unroll
;       for (int i = 0; i < 4; i++)
; #pragma unroll
;         for (int j = 0; j < 2; j++) {
;           unsigned g0, g1;
;           if (br < 2) { g0 = gp[br < 2 ? br : 0][i][j][0]; g1 = gp[br < 2 ? br : 0][i][j][1]; }
;           else { g0 = sGate[((i * 2 + j) * 2 + 0) * NT + tidx]; g1 = sGate[((i * 2 + j) * 2 + 1) * NT + tidx]; }
;           mg[i][j][0] += bflo(g0) * t[i][j][0];
;           mg[i][j][1] += bfhi(g0) * t[i][j][1];
;           mg[i][j][2] += bflo(g1) * t[i][j][2];
;           mg[i][j][3] += bfhi(g1) * t[i][j][3];
;         }
	v_mfma_f32_16x16x32_bf16 v[36:39], v[88:91], v[156:159], v[66:69]
	s_waitcnt lgkmcnt(0)
	v_mfma_f32_16x16x32_bf16 v[16:19], v[88:91], v[174:177], v[16:19]
	v_mfma_f32_16x16x32_bf16 v[20:23], v[92:95], v[156:159], v[20:23]
	v_mfma_f32_16x16x32_bf16 v[24:27], v[92:95], v[174:177], v[24:27]
	v_mfma_f32_16x16x32_bf16 v[32:35], v[108:111], v[156:159], v[32:35]
	v_mfma_f32_16x16x32_bf16 v[28:31], v[108:111], v[174:177], v[28:31]
	v_mfma_f32_16x16x32_bf16 v[8:11], v[112:115], v[156:159], v[8:11]
	v_mfma_f32_16x16x32_bf16 v[12:15], v[112:115], v[174:177], v[12:15]
	v_lshlrev_b32_e32 v40, 16, v72
	v_fma_f32 v156, v36, v40, 0
	v_and_b32_e32 v36, 0xffff0000, v72
	v_fma_f32 v157, v37, v36, 0
	v_lshlrev_b32_e32 v36, 16, v73
	v_fma_f32 v158, v38, v36, 0
	v_and_b32_e32 v36, 0xffff0000, v73
	v_fma_f32 v159, v39, v36, 0
	v_lshlrev_b32_e32 v36, 16, v74
	v_fma_f32 v174, v16, v36, 0
	v_and_b32_e32 v16, 0xffff0000, v74
	v_fma_f32 v175, v17, v16, 0
	v_lshlrev_b32_e32 v16, 16, v75
	v_fma_f32 v176, v18, v16, 0
	v_and_b32_e32 v16, 0xffff0000, v75
	v_fma_f32 v177, v19, v16, 0
	v_lshlrev_b32_e32 v16, 16, v76
	v_fma_f32 v178, v20, v16, 0
	v_and_b32_e32 v16, 0xffff0000, v76
	v_fma_f32 v179, v21, v16, 0
	v_lshlrev_b32_e32 v16, 16, v77
	v_fma_f32 v180, v22, v16, 0
	v_and_b32_e32 v16, 0xffff0000, v77
	v_fma_f32 v181, v23, v16, 0
	v_lshlrev_b32_e32 v16, 16, v78
	v_fma_f32 v182, v24, v16, 0
	v_and_b32_e32 v16, 0xffff0000, v78
	v_fma_f32 v183, v25, v16, 0
	v_lshlrev_b32_e32 v16, 16, v79
	v_fma_f32 v184, v26, v16, 0
	v_and_b32_e32 v16, 0xffff0000, v79
	v_fma_f32 v185, v27, v16, 0
	v_lshlrev_b32_e32 v16, 16, v80
	v_fma_f32 v186, v32, v16, 0
	v_and_b32_e32 v16, 0xffff0000, v80
	v_fma_f32 v187, v33, v16, 0
	v_lshlrev_b32_e32 v16, 16, v81
	v_fma_f32 v188, v34, v16, 0
	v_and_b32_e32 v16, 0xffff0000, v81
	v_fma_f32 v189, v35, v16, 0
	v_lshlrev_b32_e32 v16, 16, v82
	v_fma_f32 v190, v28, v16, 0
	v_and_b32_e32 v16, 0xffff0000, v82
	v_fma_f32 v191, v29, v16, 0
	v_lshlrev_b32_e32 v16, 16, v83
	v_fma_f32 v192, v30, v16, 0
	v_and_b32_e32 v16, 0xffff0000, v83
	v_fma_f32 v193, v31, v16, 0
	v_lshlrev_b32_e32 v16, 16, v84
	v_fma_f32 v194, v8, v16, 0
	v_and_b32_e32 v8, 0xffff0000, v84
	v_fma_f32 v195, v9, v8, 0
	v_lshlrev_b32_e32 v8, 16, v85
	v_fma_f32 v196, v10, v8, 0
	v_and_b32_e32 v8, 0xffff0000, v85
	v_fma_f32 v197, v11, v8, 0
	v_lshlrev_b32_e32 v8, 16, v86
	v_fma_f32 v198, v12, v8, 0
	v_and_b32_e32 v8, 0xffff0000, v86
	v_fma_f32 v199, v13, v8, 0
	v_lshlrev_b32_e32 v8, 16, v64
	v_fma_f32 v200, v14, v8, 0
	v_and_b32_e32 v8, 0xffff0000, v64
	v_fma_f32 v201, v15, v8, 0
	v_add_co_u32_e64 v8, s[10:11], s36, v104
	s_mov_b32 s0, 0xe9000
	s_nop 0
	v_addc_co_u32_e64 v9, s[10:11], 0, v105, s[10:11]
	v_add_co_u32_e64 v108, s[10:11], s0, v104
	s_mov_b32 s0, 0x1d1000
	s_nop 0
	v_addc_co_u32_e64 v109, s[10:11], 0, v105, s[10:11]
	v_add_co_u32_e64 v110, s[10:11], s0, v104
	global_load_dwordx4 v[24:27], v[8:9], off offset:1024
	global_load_dwordx4 v[28:31], v[108:109], off offset:1024
	v_addc_co_u32_e64 v111, s[10:11], 0, v105, s[10:11]
	s_mov_b32 s0, 0x2b9000
	v_add_co_u32_e64 v112, s[10:11], s0, v104
	global_load_dwordx4 v[36:39], v[110:111], off offset:1024
	s_nop 0
	v_addc_co_u32_e64 v113, s[10:11], 0, v105, s[10:11]
	global_load_dwordx4 v[40:43], v[112:113], off offset:1024
	v_lshl_add_u64 v[114:115], v[98:99], 0, s[18:19]
	global_load_dwordx4 v[44:47], v[114:115], off
	global_load_dwordx4 v[20:23], v[8:9], off offset:1152
	global_load_dwordx4 v[16:19], v[108:109], off offset:1152
	global_load_dwordx4 v[12:15], v[110:111], off offset:1152
	s_nop 0
	global_load_dwordx4 v[8:11], v[112:113], off offset:1152
	global_load_dwordx4 v[32:35], v[114:115], off offset:128
	s_barrier
	s_waitcnt vmcnt(9)
	ds_write_b128 v125, v[24:27]
	s_waitcnt vmcnt(8)
	ds_write_b128 v145, v[28:31]
	s_waitcnt vmcnt(7)
	ds_write_b128 v145, v[36:39] offset:10240
	s_waitcnt vmcnt(6)
	ds_write_b128 v145, v[40:43] offset:20480
	s_waitcnt vmcnt(5)
	ds_write_b128 v125, v[44:47] offset:40960
	s_waitcnt lgkmcnt(0)
	s_barrier
	ds_read_b128 v[84:87], v124
	ds_read_b128 v[76:79], v124 offset:2560
	ds_read_b128 v[64:67], v124 offset:5120
	ds_read_b128 v[52:55], v124 offset:7680
	ds_read_b128 v[68:71], v202 offset:40960
	ds_read_b128 v[56:59], v202 offset:43520
	ds_read_b128 v[48:51], v124 offset:64
	ds_read_b128 v[36:39], v124 offset:2624
	ds_read_b128 v[28:31], v124 offset:5184
	ds_read_b128 v[24:27], v124 offset:7744
	ds_read_b128 v[40:43], v146 offset:41024
	ds_read_b128 v[44:47], v146 offset:43584
	global_load_dwordx4 v[88:91], v[106:107], off offset:256
	global_load_dwordx4 v[80:83], v[108:109], off offset:1280
	global_load_dwordx4 v[72:75], v[110:111], off offset:1280
	global_load_dwordx4 v[60:63], v[112:113], off offset:1280
	global_load_dwordx4 v[92:95], v[114:115], off offset:256
	s_waitcnt lgkmcnt(7)
	v_mfma_f32_16x16x32_bf16 v[220:223], v[84:87], v[68:71], 0
	s_waitcnt vmcnt(9)
	ds_write_b128 v125, v[20:23] offset:61440
	s_waitcnt vmcnt(5)
	ds_write_b128 v126, v[32:35]
	s_waitcnt lgkmcnt(8)
	v_mfma_f32_16x16x32_bf16 v[20:23], v[84:87], v[56:59], 0
	v_mfma_f32_16x16x32_bf16 v[32:35], v[76:79], v[68:71], 0
	ds_write_b128 v127, v[16:19] offset:61440
	v_mfma_f32_16x16x32_bf16 v[16:19], v[76:79], v[56:59], 0
	v_mfma_f32_16x16x32_bf16 v[76:79], v[64:67], v[68:71], 0
	ds_write_b128 v128, v[12:15] offset:61440
	v_mfma_f32_16x16x32_bf16 v[12:15], v[64:67], v[56:59], 0
	v_mfma_f32_16x16x32_bf16 v[64:67], v[52:55], v[68:71], 0
	ds_write_b128 v129, v[8:11] offset:61440
	v_mfma_f32_16x16x32_bf16 v[8:11], v[52:55], v[56:59], 0
	s_waitcnt lgkmcnt(0)
	s_barrier
;     ...
;   for (int k0 = 0; k0 < K; k0 += 128) {
;     G_READ(fa1, fb1, 0, 32);
;     if (k0 + 128 < K) G_LOAD(ra0, rb0, k0 + 128);
;     __builtin_amdgcn_sched_barrier(0);
;     G_MFMA_ST(fa0, fb0, ra1, rb1, 1);
;     __syncthreads();
;     G_READ(fa0, fb0, 1, 0);
;     __builtin_amdgcn_sched_barrier(0);
;     G_MFMA(fa1, fb1);
;     __builtin_amdgcn_sched_barrier(0);
;     G_READ(fa1, fb1, 1, 32);
;     if (k0 + 192 < K) G_LOAD(ra1, rb1, k0 + 192);
;     __builtin_amdgcn_sched_barrier(0);
;     if (k0 + 128 < K) {
;       G_MFMA_ST(fa0, fb0, ra0, rb0, 0);
;       __syncthreads();
;       G_READ(fa0, fb0, 0, 0);
;     } else {
;       G_MFMA(fa0, fb0);
;     }
;     __builtin_amdgcn_sched_barrier(0);
;     G_MFMA(fa1, fb1);
;     __builtin_amdgcn_sched_barrier(0);
;   }
	ds_read_b128 v[52:55], v124 offset:61440
	ds_read_b128 v[56:59], v124 offset:64000
	ds_read_b128 v[68:71], v147 offset:5120
	ds_read_b128 v[84:87], v147 offset:7680
	ds_read_b128 v[224:227], v151
	ds_read_b128 v[228:231], v151 offset:2560
	v_mfma_f32_16x16x32_bf16 v[220:223], v[48:51], v[40:43], v[220:223]
	v_mfma_f32_16x16x32_bf16 v[20:23], v[48:51], v[44:47], v[20:23]
	v_mfma_f32_16x16x32_bf16 v[32:35], v[36:39], v[40:43], v[32:35]
	v_mfma_f32_16x16x32_bf16 v[16:19], v[36:39], v[44:47], v[16:19]
	v_mfma_f32_16x16x32_bf16 v[36:39], v[28:31], v[40:43], v[76:79]
	v_mfma_f32_16x16x32_bf16 v[12:15], v[28:31], v[44:47], v[12:15]
	v_mfma_f32_16x16x32_bf16 v[28:31], v[24:27], v[40:43], v[64:67]
	v_mfma_f32_16x16x32_bf16 v[8:11], v[24:27], v[44:47], v[8:11]
	global_load_dwordx4 v[24:27], v[106:107], off offset:384
	global_load_dwordx4 v[40:43], v[108:109], off offset:1408
	global_load_dwordx4 v[44:47], v[110:111], off offset:1408
	global_load_dwordx4 v[48:51], v[112:113], off offset:1408
	global_load_dwordx4 v[64:67], v[114:115], off offset:384
	ds_read_b128 v[76:79], v124 offset:61504
	ds_read_b128 v[232:235], v124 offset:64064
	ds_read_b128 v[236:239], v152 offset:64
	ds_read_b128 v[240:243], v153 offset:64
	ds_read_b128 v[244:247], v203 offset:64
	ds_read_b128 v[170:173], v154 offset:64
	s_waitcnt lgkmcnt(7)
	v_mfma_f32_16x16x32_bf16 v[220:223], v[52:55], v[224:227], v[220:223]
	s_waitcnt vmcnt(9)
	ds_write_b128 v125, v[88:91]
	s_waitcnt vmcnt(5)
	ds_write_b128 v125, v[92:95] offset:40960
	s_waitcnt lgkmcnt(8)
	v_mfma_f32_16x16x32_bf16 v[20:23], v[52:55], v[228:231], v[20:23]
	v_mfma_f32_16x16x32_bf16 v[32:35], v[56:59], v[224:227], v[32:35]
	ds_write_b128 v125, v[80:83] offset:10240
	v_mfma_f32_16x16x32_bf16 v[16:19], v[56:59], v[228:231], v[16:19]
	v_mfma_f32_16x16x32_bf16 v[36:39], v[68:71], v[224:227], v[36:39]
	ds_write_b128 v125, v[72:75] offset:20480
	v_mfma_f32_16x16x32_bf16 v[12:15], v[68:71], v[228:231], v[12:15]
	v_mfma_f32_16x16x32_bf16 v[28:31], v[84:87], v[224:227], v[28:31]
	ds_write_b128 v125, v[60:63] offset:30720
	v_mfma_f32_16x16x32_bf16 v[8:11], v[84:87], v[228:231], v[8:11]
	s_waitcnt lgkmcnt(0)
	s_barrier
	ds_read_b128 v[52:55], v124
	ds_read_b128 v[56:59], v124 offset:2560
	ds_read_b128 v[60:63], v124 offset:5120
	ds_read_b128 v[68:71], v124 offset:7680
	ds_read_b128 v[72:75], v202 offset:40960
	ds_read_b128 v[80:83], v202 offset:43520
	v_mfma_f32_16x16x32_bf16 v[84:87], v[76:79], v[244:247], v[220:223]
	v_mfma_f32_16x16x32_bf16 v[20:23], v[76:79], v[170:173], v[20:23]
	v_mfma_f32_16x16x32_bf16 v[32:35], v[232:235], v[244:247], v[32:35]
	v_mfma_f32_16x16x32_bf16 v[16:19], v[232:235], v[170:173], v[16:19]
	v_mfma_f32_16x16x32_bf16 v[36:39], v[236:239], v[244:247], v[36:39]
	v_mfma_f32_16x16x32_bf16 v[12:15], v[236:239], v[170:173], v[12:15]
	v_mfma_f32_16x16x32_bf16 v[28:31], v[240:243], v[244:247], v[28:31]
	v_mfma_f32_16x16x32_bf16 v[8:11], v[240:243], v[170:173], v[8:11]
	global_load_dwordx4 v[76:79], v[106:107], off offset:512
	global_load_dwordx4 v[88:91], v[108:109], off offset:1536
	global_load_dwordx4 v[92:95], v[110:111], off offset:1536
	global_load_dwordx4 v[170:173], v[112:113], off offset:1536
	global_load_dwordx4 v[220:223], v[114:115], off offset:512
	ds_read_b128 v[224:227], v124 offset:64
	ds_read_b128 v[228:231], v124 offset:2624
	ds_read_b128 v[232:235], v124 offset:5184
	ds_read_b128 v[236:239], v124 offset:7744
	ds_read_b128 v[240:243], v146 offset:41024
	ds_read_b128 v[244:247], v146 offset:43584
	s_waitcnt lgkmcnt(7)
	v_mfma_f32_16x16x32_bf16 v[84:87], v[52:55], v[72:75], v[84:87]
	s_waitcnt vmcnt(9)
	ds_write_b128 v125, v[24:27] offset:61440
	s_waitcnt vmcnt(5)
	ds_write_b128 v126, v[64:67]
	s_waitcnt lgkmcnt(8)
	v_mfma_f32_16x16x32_bf16 v[20:23], v[52:55], v[80:83], v[20:23]
	v_mfma_f32_16x16x32_bf16 v[24:27], v[56:59], v[72:75], v[32:35]
	ds_write_b128 v127, v[40:43] offset:61440
	v_mfma_f32_16x16x32_bf16 v[16:19], v[56:59], v[80:83], v[16:19]
	v_mfma_f32_16x16x32_bf16 v[32:35], v[60:63], v[72:75], v[36:39]
	ds_write_b128 v128, v[44:47] offset:61440
	v_mfma_f32_16x16x32_bf16 v[12:15], v[60:63], v[80:83], v[12:15]
	v_mfma_f32_16x16x32_bf16 v[28:31], v[68:71], v[72:75], v[28:31]
	ds_write_b128 v129, v[48:51] offset:61440
	v_mfma_f32_16x16x32_bf16 v[8:11], v[68:71], v[80:83], v[8:11]
	s_waitcnt lgkmcnt(0)
	s_barrier
	ds_read_b128 v[36:39], v124 offset:61440
	ds_read_b128 v[40:43], v124 offset:64000
	ds_read_b128 v[44:47], v147 offset:5120
	ds_read_b128 v[48:51], v147 offset:7680
	ds_read_b128 v[52:55], v151
	ds_read_b128 v[56:59], v151 offset:2560
	v_mfma_f32_16x16x32_bf16 v[60:63], v[224:227], v[240:243], v[84:87]
	v_mfma_f32_16x16x32_bf16 v[20:23], v[224:227], v[244:247], v[20:23]
	v_mfma_f32_16x16x32_bf16 v[24:27], v[228:231], v[240:243], v[24:27]
	v_mfma_f32_16x16x32_bf16 v[16:19], v[228:231], v[244:247], v[16:19]
	v_mfma_f32_16x16x32_bf16 v[32:35], v[232:235], v[240:243], v[32:35]
	v_mfma_f32_16x16x32_bf16 v[12:15], v[232:235], v[244:247], v[12:15]
	v_mfma_f32_16x16x32_bf16 v[28:31], v[236:239], v[240:243], v[28:31]
	v_mfma_f32_16x16x32_bf16 v[8:11], v[236:239], v[244:247], v[8:11]
	global_load_dwordx4 v[64:67], v[106:107], off offset:640
	global_load_dwordx4 v[68:71], v[108:109], off offset:1664
	global_load_dwordx4 v[72:75], v[110:111], off offset:1664
	global_load_dwordx4 v[80:83], v[112:113], off offset:1664
	global_load_dwordx4 v[84:87], v[114:115], off offset:640
	ds_read_b128 v[224:227], v124 offset:61504
	ds_read_b128 v[228:231], v124 offset:64064
	ds_read_b128 v[232:235], v152 offset:64
	ds_read_b128 v[236:239], v153 offset:64
	ds_read_b128 v[240:243], v203 offset:64
	ds_read_b128 v[244:247], v154 offset:64
	s_waitcnt lgkmcnt(7)
	v_mfma_f32_16x16x32_bf16 v[60:63], v[36:39], v[52:55], v[60:63]
	s_waitcnt vmcnt(9)
	ds_write_b128 v125, v[76:79]
	s_waitcnt vmcnt(5)
	ds_write_b128 v125, v[220:223] offset:40960
	s_waitcnt lgkmcnt(8)
	v_mfma_f32_16x16x32_bf16 v[20:23], v[36:39], v[56:59], v[20:23]
	v_mfma_f32_16x16x32_bf16 v[24:27], v[40:43], v[52:55], v[24:27]
	ds_write_b128 v125, v[88:91] offset:10240
	v_mfma_f32_16x16x32_bf16 v[16:19], v[40:43], v[56:59], v[16:19]
	v_mfma_f32_16x16x32_bf16 v[32:35], v[44:47], v[52:55], v[32:35]
	ds_write_b128 v125, v[92:95] offset:20480
	v_mfma_f32_16x16x32_bf16 v[12:15], v[44:47], v[56:59], v[12:15]
	v_mfma_f32_16x16x32_bf16 v[28:31], v[48:51], v[52:55], v[28:31]
	ds_write_b128 v125, v[170:173] offset:30720
	v_mfma_f32_16x16x32_bf16 v[8:11], v[48:51], v[56:59], v[8:11]
	s_waitcnt lgkmcnt(0)
	s_barrier
;     ...
;   for (int k0 = 0; k0 < K; k0 += 128) {
;     G_READ(fa1, fb1, 0, 32);
;     if (k0 + 128 < K) G_LOAD(ra0, rb0, k0 + 128);
;     __builtin_amdgcn_sched_barrier(0);
;     G_MFMA_ST(fa0, fb0, ra1, rb1, 1);
;     __syncthreads();
;     G_READ(fa0, fb0, 1, 0);
;     __builtin_amdgcn_sched_barrier(0);
;     G_MFMA(fa1, fb1);
;     __builtin_amdgcn_sched_barrier(0);
;     G_READ(fa1, fb1, 1, 32);
;     if (k0 + 192 < K) G_LOAD(ra1, rb1, k0 + 192);
;     __builtin_amdgcn_sched_barrier(0);
;     if (k0 + 128 < K) {
;       G_MFMA_ST(fa0, fb0, ra0, rb0, 0);
;       __syncthreads();
;       G_READ(fa0, fb0, 0, 0);
;     } else {
;       G_MFMA(fa0, fb0);
;     }
;     __builtin_amdgcn_sched_barrier(0);
;     G_MFMA(fa1, fb1);
;     __builtin_amdgcn_sched_barrier(0);
;   }
	ds_read_b128 v[36:39], v124
	ds_read_b128 v[40:43], v124 offset:2560
	ds_read_b128 v[44:47], v124 offset:5120
	ds_read_b128 v[48:51], v124 offset:7680
	ds_read_b128 v[52:55], v202 offset:40960
	ds_read_b128 v[56:59], v202 offset:43520
	v_mfma_f32_16x16x32_bf16 v[60:63], v[224:227], v[240:243], v[60:63]
	v_mfma_f32_16x16x32_bf16 v[20:23], v[224:227], v[244:247], v[20:23]
	v_mfma_f32_16x16x32_bf16 v[24:27], v[228:231], v[240:243], v[24:27]
	v_mfma_f32_16x16x32_bf16 v[16:19], v[228:231], v[244:247], v[16:19]
	v_mfma_f32_16x16x32_bf16 v[32:35], v[232:235], v[240:243], v[32:35]
	v_mfma_f32_16x16x32_bf16 v[12:15], v[232:235], v[244:247], v[12:15]
	v_mfma_f32_16x16x32_bf16 v[28:31], v[236:239], v[240:243], v[28:31]
	v_mfma_f32_16x16x32_bf16 v[8:11], v[236:239], v[244:247], v[8:11]
	global_load_dwordx4 v[76:79], v[106:107], off offset:768
	global_load_dwordx4 v[88:91], v[108:109], off offset:1792
	global_load_dwordx4 v[92:95], v[110:111], off offset:1792
	global_load_dwordx4 v[170:173], v[112:113], off offset:1792
	global_load_dwordx4 v[220:223], v[114:115], off offset:768
	ds_read_b128 v[224:227], v124 offset:64
	ds_read_b128 v[228:231], v124 offset:2624
	ds_read_b128 v[232:235], v124 offset:5184
	ds_read_b128 v[236:239], v124 offset:7744
	ds_read_b128 v[240:243], v146 offset:41024
	ds_read_b128 v[244:247], v146 offset:43584
	s_waitcnt lgkmcnt(7)
	v_mfma_f32_16x16x32_bf16 v[60:63], v[36:39], v[52:55], v[60:63]
	s_waitcnt vmcnt(9)
	ds_write_b128 v125, v[64:67] offset:61440
	s_waitcnt vmcnt(5)
	ds_write_b128 v126, v[84:87]
	s_waitcnt lgkmcnt(8)
	v_mfma_f32_16x16x32_bf16 v[20:23], v[36:39], v[56:59], v[20:23]
	v_mfma_f32_16x16x32_bf16 v[24:27], v[40:43], v[52:55], v[24:27]
	ds_write_b128 v127, v[68:71] offset:61440
	v_mfma_f32_16x16x32_bf16 v[16:19], v[40:43], v[56:59], v[16:19]
	v_mfma_f32_16x16x32_bf16 v[32:35], v[44:47], v[52:55], v[32:35]
	ds_write_b128 v128, v[72:75] offset:61440
	v_mfma_f32_16x16x32_bf16 v[12:15], v[44:47], v[56:59], v[12:15]
	v_mfma_f32_16x16x32_bf16 v[28:31], v[48:51], v[52:55], v[28:31]
	ds_write_b128 v129, v[80:83] offset:61440
	v_mfma_f32_16x16x32_bf16 v[8:11], v[48:51], v[56:59], v[8:11]
	s_waitcnt lgkmcnt(0)
	s_barrier
	ds_read_b128 v[36:39], v124 offset:61440
	ds_read_b128 v[40:43], v124 offset:64000
	ds_read_b128 v[44:47], v147 offset:5120
	ds_read_b128 v[48:51], v147 offset:7680
	ds_read_b128 v[52:55], v151
	ds_read_b128 v[56:59], v151 offset:2560
	v_mfma_f32_16x16x32_bf16 v[60:63], v[224:227], v[240:243], v[60:63]
	v_mfma_f32_16x16x32_bf16 v[20:23], v[224:227], v[244:247], v[20:23]
	v_mfma_f32_16x16x32_bf16 v[24:27], v[228:231], v[240:243], v[24:27]
	v_mfma_f32_16x16x32_bf16 v[16:19], v[228:231], v[244:247], v[16:19]
	v_mfma_f32_16x16x32_bf16 v[32:35], v[232:235], v[240:243], v[32:35]
	v_mfma_f32_16x16x32_bf16 v[12:15], v[232:235], v[244:247], v[12:15]
	v_mfma_f32_16x16x32_bf16 v[28:31], v[236:239], v[240:243], v[28:31]
	v_mfma_f32_16x16x32_bf16 v[8:11], v[236:239], v[244:247], v[8:11]
	global_load_dwordx4 v[64:67], v[106:107], off offset:896
	global_load_dwordx4 v[68:71], v[108:109], off offset:1920
	global_load_dwordx4 v[72:75], v[110:111], off offset:1920
	global_load_dwordx4 v[80:83], v[112:113], off offset:1920
	global_load_dwordx4 v[84:87], v[114:115], off offset:896
	ds_read_b128 v[106:109], v124 offset:61504
	ds_read_b128 v[110:113], v124 offset:64064
	ds_read_b128 v[224:227], v152 offset:64
	ds_read_b128 v[228:231], v153 offset:64
	ds_read_b128 v[232:235], v203 offset:64
	ds_read_b128 v[236:239], v154 offset:64
	s_waitcnt lgkmcnt(7)
	v_mfma_f32_16x16x32_bf16 v[60:63], v[36:39], v[52:55], v[60:63]
	s_waitcnt vmcnt(9)
	ds_write_b128 v125, v[76:79]
	s_waitcnt vmcnt(5)
	ds_write_b128 v125, v[220:223] offset:40960
	s_waitcnt lgkmcnt(8)
	v_mfma_f32_16x16x32_bf16 v[20:23], v[36:39], v[56:59], v[20:23]
	v_mfma_f32_16x16x32_bf16 v[24:27], v[40:43], v[52:55], v[24:27]
	ds_write_b128 v125, v[88:91] offset:10240
	v_mfma_f32_16x16x32_bf16 v[16:19], v[40:43], v[56:59], v[16:19]
	v_mfma_f32_16x16x32_bf16 v[32:35], v[44:47], v[52:55], v[32:35]
	ds_write_b128 v125, v[92:95] offset:20480
	v_mfma_f32_16x16x32_bf16 v[12:15], v[44:47], v[56:59], v[12:15]
	v_mfma_f32_16x16x32_bf16 v[28:31], v[48:51], v[52:55], v[28:31]
	ds_write_b128 v125, v[170:173] offset:30720
	v_mfma_f32_16x16x32_bf16 v[8:11], v[48:51], v[56:59], v[8:11]
	s_waitcnt lgkmcnt(0)
	s_barrier
	ds_read_b128 v[36:39], v124
	ds_read_b128 v[40:43], v124 offset:2560
	ds_read_b128 v[44:47], v124 offset:5120
	ds_read_b128 v[48:51], v124 offset:7680
	ds_read_b128 v[52:55], v202 offset:40960
	ds_read_b128 v[56:59], v202 offset:43520
	v_mfma_f32_16x16x32_bf16 v[60:63], v[106:109], v[232:235], v[60:63]
	v_mfma_f32_16x16x32_bf16 v[20:23], v[106:109], v[236:239], v[20:23]
	v_mfma_f32_16x16x32_bf16 v[24:27], v[110:113], v[232:235], v[24:27]
	v_mfma_f32_16x16x32_bf16 v[16:19], v[110:113], v[236:239], v[16:19]
	v_mfma_f32_16x16x32_bf16 v[32:35], v[224:227], v[232:235], v[32:35]
	v_mfma_f32_16x16x32_bf16 v[12:15], v[224:227], v[236:239], v[12:15]
	v_mfma_f32_16x16x32_bf16 v[28:31], v[228:231], v[232:235], v[28:31]
	v_mfma_f32_16x16x32_bf16 v[8:11], v[228:231], v[236:239], v[8:11]
	ds_read_b128 v[76:79], v124 offset:64
	ds_read_b128 v[88:91], v124 offset:2624
	ds_read_b128 v[92:95], v124 offset:5184
	ds_read_b128 v[106:109], v124 offset:7744
	ds_read_b128 v[110:113], v146 offset:41024
	ds_read_b128 v[170:173], v146 offset:43584
	s_waitcnt lgkmcnt(7)
	v_mfma_f32_16x16x32_bf16 v[60:63], v[36:39], v[52:55], v[60:63]
	s_waitcnt vmcnt(4)
	ds_write_b128 v125, v[64:67] offset:61440
	s_waitcnt vmcnt(0)
	ds_write_b128 v126, v[84:87]
	s_waitcnt lgkmcnt(8)
	v_mfma_f32_16x16x32_bf16 v[20:23], v[36:39], v[56:59], v[20:23]
	v_mfma_f32_16x16x32_bf16 v[24:27], v[40:43], v[52:55], v[24:27]
	ds_write_b128 v127, v[68:71] offset:61440
	v_mfma_f32_16x16x32_bf16 v[16:19], v[40:43], v[56:59], v[16:19]
	v_mfma_f32_16x16x32_bf16 v[32:35], v[44:47], v[52:55], v[32:35]
	ds_write_b128 v128, v[72:75] offset:61440
	v_mfma_f32_16x16x32_bf16 v[12:15], v[44:47], v[56:59], v[12:15]
	v_mfma_f32_16x16x32_bf16 v[28:31], v[48:51], v[52:55], v[28:31]
	ds_write_b128 v129, v[80:83] offset:61440
	v_mfma_f32_16x16x32_bf16 v[8:11], v[48:51], v[56:59], v[8:11]
	s_waitcnt lgkmcnt(0)
	s_barrier
; __device__ __forceinline__ float bflo(unsigned w) { return __uint_as_float(w << 16); }
; __device__ __forceinline__ float bfhi(unsigned w) { return __uint_as_float(w & 0xffff0000u); }
;     ...
;   G_LOAD(ra0, rb0, 0);
;   G_LOAD(ra1, rb1, 64);
;   __syncthreads();
;   G_STORE(ra0, rb0, 0);
;   __syncthreads();
;   G_READ(fa0, fb0, 0, 0);
; #pragma unroll
;   for (int k0 = 0; k0 < K; k0 += 128) {
;     G_READ(fa1, fb1, 0, 32);
;     if (k0 + 128 < K) G_LOAD(ra0, rb0, k0 + 128);
;     __builtin_amdgcn_sched_barrier(0);
;     G_MFMA_ST(fa0, fb0, ra1, rb1, 1);
;     __syncthreads();
;     G_READ(fa0, fb0, 1, 0);
; __device__ __forceinline__ void phase_merge(const Params& p, const int tidx) {
;     ...
; #pragma unroll
;       for (int i = 0; i < 4; i++)
; #pragma unroll
;         for (int j = 0; j < 2; j++) {
;           unsigned g0, g1;
;           if (br < 2) { g0 = gp[br < 2 ? br : 0][i][j][0]; g1 = gp[br < 2 ? br : 0][i][j][1]; }
;           else { g0 = sGate[((i * 2 + j) * 2 + 0) * NT + tidx]; g1 = sGate[((i * 2 + j) * 2 + 1) * NT + tidx]; }
;           mg[i][j][0] += bflo(g0) * t[i][j][0];
;           mg[i][j][1] += bfhi(g0) * t[i][j][1];
;           mg[i][j][2] += bflo(g1) * t[i][j][2];
;           mg[i][j][3] += bfhi(g1) * t[i][j][3];
;         }
	ds_read_b128 v[36:39], v124 offset:61440
	ds_read_b128 v[40:43], v124 offset:64000
	ds_read_b128 v[44:47], v147 offset:5120
	ds_read_b128 v[48:51], v147 offset:7680
	ds_read_b128 v[52:55], v151
	ds_read_b128 v[56:59], v151 offset:2560
	v_mfma_f32_16x16x32_bf16 v[60:63], v[76:79], v[110:113], v[60:63]
	v_mfma_f32_16x16x32_bf16 v[20:23], v[76:79], v[170:173], v[20:23]
	v_mfma_f32_16x16x32_bf16 v[24:27], v[88:91], v[110:113], v[24:27]
	v_mfma_f32_16x16x32_bf16 v[16:19], v[88:91], v[170:173], v[16:19]
	v_mfma_f32_16x16x32_bf16 v[32:35], v[92:95], v[110:113], v[32:35]
	v_mfma_f32_16x16x32_bf16 v[12:15], v[92:95], v[170:173], v[12:15]
	v_mfma_f32_16x16x32_bf16 v[28:31], v[106:109], v[110:113], v[28:31]
	v_mfma_f32_16x16x32_bf16 v[8:11], v[106:109], v[170:173], v[8:11]
	ds_read_b128 v[64:67], v124 offset:61504
	ds_read_b128 v[68:71], v124 offset:64064
	ds_read_b128 v[72:75], v152 offset:64
	ds_read_b128 v[76:79], v153 offset:64
	ds_read_b128 v[80:83], v203 offset:64
	ds_read_b128 v[84:87], v154 offset:64
	s_waitcnt lgkmcnt(7)
	v_mfma_f32_16x16x32_bf16 v[60:63], v[36:39], v[52:55], v[60:63]
	s_waitcnt lgkmcnt(6)
	v_mfma_f32_16x16x32_bf16 v[20:23], v[36:39], v[56:59], v[20:23]
	v_mfma_f32_16x16x32_bf16 v[24:27], v[40:43], v[52:55], v[24:27]
	v_mfma_f32_16x16x32_bf16 v[16:19], v[40:43], v[56:59], v[16:19]
	v_mfma_f32_16x16x32_bf16 v[32:35], v[44:47], v[52:55], v[32:35]
	v_mfma_f32_16x16x32_bf16 v[12:15], v[44:47], v[56:59], v[12:15]
	v_mfma_f32_16x16x32_bf16 v[28:31], v[48:51], v[52:55], v[28:31]
	v_mfma_f32_16x16x32_bf16 v[8:11], v[48:51], v[56:59], v[8:11]
	s_waitcnt lgkmcnt(1)
	v_mfma_f32_16x16x32_bf16 v[36:39], v[64:67], v[80:83], v[60:63]
	s_waitcnt lgkmcnt(0)
	v_mfma_f32_16x16x32_bf16 v[20:23], v[64:67], v[84:87], v[20:23]
	v_mfma_f32_16x16x32_bf16 v[24:27], v[68:71], v[80:83], v[24:27]
	v_mfma_f32_16x16x32_bf16 v[16:19], v[68:71], v[84:87], v[16:19]
	v_mfma_f32_16x16x32_bf16 v[32:35], v[72:75], v[80:83], v[32:35]
	v_mfma_f32_16x16x32_bf16 v[12:15], v[72:75], v[84:87], v[12:15]
	v_mfma_f32_16x16x32_bf16 v[28:31], v[76:79], v[80:83], v[28:31]
	v_mfma_f32_16x16x32_bf16 v[8:11], v[76:79], v[84:87], v[8:11]
	v_lshlrev_b32_e32 v40, 16, v204
	v_fmac_f32_e32 v156, v36, v40
	v_and_b32_e32 v36, 0xffff0000, v204
	v_fmac_f32_e32 v157, v37, v36
	v_lshlrev_b32_e32 v36, 16, v205
	v_fmac_f32_e32 v158, v38, v36
	v_and_b32_e32 v36, 0xffff0000, v205
	v_fmac_f32_e32 v159, v39, v36
	v_lshlrev_b32_e32 v36, 16, v206
	v_fmac_f32_e32 v174, v20, v36
	v_and_b32_e32 v20, 0xffff0000, v206
	v_fmac_f32_e32 v175, v21, v20
	v_lshlrev_b32_e32 v20, 16, v207
	v_fmac_f32_e32 v176, v22, v20
	v_and_b32_e32 v20, 0xffff0000, v207
	v_fmac_f32_e32 v177, v23, v20
	v_lshlrev_b32_e32 v20, 16, v208
	v_fmac_f32_e32 v178, v24, v20
	v_and_b32_e32 v20, 0xffff0000, v208
	v_fmac_f32_e32 v179, v25, v20
	v_lshlrev_b32_e32 v20, 16, v209
	v_fmac_f32_e32 v180, v26, v20
	v_and_b32_e32 v20, 0xffff0000, v209
	v_fmac_f32_e32 v181, v27, v20
	v_lshlrev_b32_e32 v20, 16, v210
	v_fmac_f32_e32 v182, v16, v20
	v_and_b32_e32 v16, 0xffff0000, v210
	v_fmac_f32_e32 v183, v17, v16
	v_lshlrev_b32_e32 v16, 16, v211
	v_fmac_f32_e32 v184, v18, v16
	v_and_b32_e32 v16, 0xffff0000, v211
	v_fmac_f32_e32 v185, v19, v16
	v_lshlrev_b32_e32 v16, 16, v212
	v_fmac_f32_e32 v186, v32, v16
	v_and_b32_e32 v16, 0xffff0000, v212
	v_fmac_f32_e32 v187, v33, v16
	v_lshlrev_b32_e32 v16, 16, v213
	v_fmac_f32_e32 v188, v34, v16
	v_and_b32_e32 v16, 0xffff0000, v213
	v_fmac_f32_e32 v189, v35, v16
	v_lshlrev_b32_e32 v16, 16, v214
	v_fmac_f32_e32 v190, v12, v16
	v_and_b32_e32 v12, 0xffff0000, v214
	v_fmac_f32_e32 v191, v13, v12
	v_lshlrev_b32_e32 v12, 16, v215
	v_fmac_f32_e32 v192, v14, v12
	v_and_b32_e32 v12, 0xffff0000, v215
	v_fmac_f32_e32 v193, v15, v12
	v_lshlrev_b32_e32 v12, 16, v216
	v_fmac_f32_e32 v194, v28, v12
	v_and_b32_e32 v12, 0xffff0000, v216
	v_fmac_f32_e32 v195, v29, v12
	v_lshlrev_b32_e32 v12, 16, v217
	v_fmac_f32_e32 v196, v30, v12
	v_and_b32_e32 v12, 0xffff0000, v217
	v_fmac_f32_e32 v197, v31, v12
	v_lshlrev_b32_e32 v12, 16, v218
	v_fmac_f32_e32 v198, v8, v12
	v_and_b32_e32 v8, 0xffff0000, v218
	v_fmac_f32_e32 v199, v9, v8
	v_lshlrev_b32_e32 v8, 16, v219
	v_fmac_f32_e32 v200, v10, v8
	v_and_b32_e32 v8, 0xffff0000, v219
	v_fmac_f32_e32 v201, v11, v8
	v_add_co_u32_e64 v8, s[10:11], s2, v104
	s_mov_b32 s0, 0xeb000
	s_nop 0
	v_addc_co_u32_e64 v9, s[10:11], 0, v105, s[10:11]
	v_add_co_u32_e64 v106, s[10:11], s0, v104
	s_mov_b32 s0, 0x1d3000
	s_nop 0
	v_addc_co_u32_e64 v107, s[10:11], 0, v105, s[10:11]
	v_add_co_u32_e64 v108, s[10:11], s0, v104
	global_load_dwordx4 v[28:31], v[8:9], off offset:512
	s_nop 0
	v_addc_co_u32_e64 v109, s[10:11], 0, v105, s[10:11]
	s_mov_b32 s0, 0x2bb000
	global_load_dwordx4 v[32:35], v[106:107], off offset:512
	global_load_dwordx4 v[36:39], v[108:109], off offset:512
	v_add_co_u32_e64 v104, s[10:11], s0, v104
	v_lshl_add_u64 v[110:111], v[100:101], 0, s[16:17]
	s_nop 0
	v_addc_co_u32_e64 v105, s[10:11], 0, v105, s[10:11]
	global_load_dwordx4 v[40:43], v[104:105], off offset:512
	global_load_dwordx4 v[44:47], v[110:111], off
	global_load_dwordx4 v[20:23], v[8:9], off offset:640
	global_load_dwordx4 v[16:19], v[106:107], off offset:640
	global_load_dwordx4 v[12:15], v[108:109], off offset:640
	s_nop 0
	global_load_dwordx4 v[8:11], v[104:105], off offset:640
	global_load_dwordx4 v[24:27], v[110:111], off offset:128
	s_barrier
	s_waitcnt vmcnt(9)
	ds_write_b128 v125, v[28:31]
	s_waitcnt vmcnt(8)
	ds_write_b128 v145, v[32:35]
	s_waitcnt vmcnt(7)
	ds_write_b128 v145, v[36:39] offset:10240
	s_waitcnt vmcnt(6)
	ds_write_b128 v145, v[40:43] offset:20480
	s_waitcnt vmcnt(5)
	ds_write_b128 v125, v[44:47] offset:40960
	s_waitcnt lgkmcnt(0)
	s_barrier
;     ...
;   G_LOAD(ra0, rb0, 0);
;   G_LOAD(ra1, rb1, 64);
;   __syncthreads();
;   G_STORE(ra0, rb0, 0);
;   __syncthreads();
;   G_READ(fa0, fb0, 0, 0);
; #pragma unroll
;   for (int k0 = 0; k0 < K; k0 += 128) {
;     G_READ(fa1, fb1, 0, 32);
;     if (k0 + 128 < K) G_LOAD(ra0, rb0, k0 + 128);
;     __builtin_amdgcn_sched_barrier(0);
;     G_MFMA_ST(fa0, fb0, ra1, rb1, 1);
;     __syncthreads();
;     G_READ(fa0, fb0, 1, 0);
;     __builtin_amdgcn_sched_barrier(0);
;     G_MFMA(fa1, fb1);
;     __builtin_amdgcn_sched_barrier(0);
;     G_READ(fa1, fb1, 1, 32);
;     if (k0 + 192 < K) G_LOAD(ra1, rb1, k0 + 192);
;     __builtin_amdgcn_sched_barrier(0);
;     if (k0 + 128 < K) {
;       G_MFMA_ST(fa0, fb0, ra0, rb0, 0);
;       __syncthreads();
;       G_READ(fa0, fb0, 0, 0);
;     } else {
;       G_MFMA(fa0, fb0);
;     }
;     __builtin_amdgcn_sched_barrier(0);
;     G_MFMA(fa1, fb1);
;     __builtin_amdgcn_sched_barrier(0);
;   }
	ds_read_b128 v[84:87], v124
	ds_read_b128 v[76:79], v124 offset:2560
	ds_read_b128 v[64:67], v124 offset:5120
	ds_read_b128 v[52:55], v124 offset:7680
	ds_read_b128 v[68:71], v202 offset:40960
	ds_read_b128 v[56:59], v202 offset:43520
	ds_read_b128 v[48:51], v124 offset:64
	ds_read_b128 v[36:39], v124 offset:2624
	ds_read_b128 v[32:35], v124 offset:5184
	ds_read_b128 v[28:31], v124 offset:7744
	ds_read_b128 v[40:43], v146 offset:41024
	ds_read_b128 v[44:47], v146 offset:43584
	global_load_dwordx4 v[88:91], v[102:103], off offset:256
	global_load_dwordx4 v[80:83], v[106:107], off offset:768
	global_load_dwordx4 v[72:75], v[108:109], off offset:768
	global_load_dwordx4 v[60:63], v[104:105], off offset:768
	global_load_dwordx4 v[92:95], v[110:111], off offset:256
	s_waitcnt lgkmcnt(7)
	v_mfma_f32_16x16x32_bf16 v[112:115], v[84:87], v[68:71], 0
	s_waitcnt vmcnt(9)
	ds_write_b128 v125, v[20:23] offset:61440
	s_waitcnt vmcnt(5)
	ds_write_b128 v126, v[24:27]
	s_waitcnt lgkmcnt(8)
	v_mfma_f32_16x16x32_bf16 v[20:23], v[84:87], v[56:59], 0
	v_mfma_f32_16x16x32_bf16 v[24:27], v[76:79], v[68:71], 0
	ds_write_b128 v127, v[16:19] offset:61440
	v_mfma_f32_16x16x32_bf16 v[16:19], v[76:79], v[56:59], 0
	v_mfma_f32_16x16x32_bf16 v[76:79], v[64:67], v[68:71], 0
	ds_write_b128 v128, v[12:15] offset:61440
	v_mfma_f32_16x16x32_bf16 v[12:15], v[64:67], v[56:59], 0
	v_mfma_f32_16x16x32_bf16 v[64:67], v[52:55], v[68:71], 0
	ds_write_b128 v129, v[8:11] offset:61440
	v_mfma_f32_16x16x32_bf16 v[8:11], v[52:55], v[56:59], 0
	s_waitcnt lgkmcnt(0)
	s_barrier
	ds_read_b128 v[52:55], v124 offset:61440
	ds_read_b128 v[56:59], v124 offset:64000
	ds_read_b128 v[68:71], v147 offset:5120
	ds_read_b128 v[84:87], v147 offset:7680
	ds_read_b128 v[170:173], v151
	ds_read_b128 v[204:207], v151 offset:2560
	v_mfma_f32_16x16x32_bf16 v[112:115], v[48:51], v[40:43], v[112:115]
	v_mfma_f32_16x16x32_bf16 v[20:23], v[48:51], v[44:47], v[20:23]
	v_mfma_f32_16x16x32_bf16 v[24:27], v[36:39], v[40:43], v[24:27]
	v_mfma_f32_16x16x32_bf16 v[16:19], v[36:39], v[44:47], v[16:19]
	v_mfma_f32_16x16x32_bf16 v[36:39], v[32:35], v[40:43], v[76:79]
	v_mfma_f32_16x16x32_bf16 v[12:15], v[32:35], v[44:47], v[12:15]
	v_mfma_f32_16x16x32_bf16 v[32:35], v[28:31], v[40:43], v[64:67]
	v_mfma_f32_16x16x32_bf16 v[8:11], v[28:31], v[44:47], v[8:11]
	global_load_dwordx4 v[28:31], v[102:103], off offset:384
	global_load_dwordx4 v[40:43], v[106:107], off offset:896
	global_load_dwordx4 v[44:47], v[108:109], off offset:896
	global_load_dwordx4 v[48:51], v[104:105], off offset:896
	global_load_dwordx4 v[64:67], v[110:111], off offset:384
	ds_read_b128 v[76:79], v124 offset:61504
	ds_read_b128 v[208:211], v124 offset:64064
	ds_read_b128 v[212:215], v152 offset:64
	ds_read_b128 v[216:219], v153 offset:64
	ds_read_b128 v[220:223], v203 offset:64
	ds_read_b128 v[224:227], v154 offset:64
	s_waitcnt lgkmcnt(7)
	v_mfma_f32_16x16x32_bf16 v[112:115], v[52:55], v[170:173], v[112:115]
	s_waitcnt vmcnt(9)
	ds_write_b128 v125, v[88:91]
	s_waitcnt vmcnt(5)
	ds_write_b128 v125, v[92:95] offset:40960
	s_waitcnt lgkmcnt(8)
	v_mfma_f32_16x16x32_bf16 v[20:23], v[52:55], v[204:207], v[20:23]
	v_mfma_f32_16x16x32_bf16 v[24:27], v[56:59], v[170:173], v[24:27]
	ds_write_b128 v125, v[80:83] offset:10240
	v_mfma_f32_16x16x32_bf16 v[16:19], v[56:59], v[204:207], v[16:19]
	v_mfma_f32_16x16x32_bf16 v[36:39], v[68:71], v[170:173], v[36:39]
	ds_write_b128 v125, v[72:75] offset:20480
	v_mfma_f32_16x16x32_bf16 v[12:15], v[68:71], v[204:207], v[12:15]
	v_mfma_f32_16x16x32_bf16 v[32:35], v[84:87], v[170:173], v[32:35]
	ds_write_b128 v125, v[60:63] offset:30720
	v_mfma_f32_16x16x32_bf16 v[8:11], v[84:87], v[204:207], v[8:11]
	s_waitcnt lgkmcnt(0)
	s_barrier
	ds_read_b128 v[52:55], v124
	ds_read_b128 v[56:59], v124 offset:2560
	ds_read_b128 v[60:63], v124 offset:5120
	ds_read_b128 v[68:71], v124 offset:7680
	ds_read_b128 v[72:75], v202 offset:40960
	ds_read_b128 v[80:83], v202 offset:43520
	v_mfma_f32_16x16x32_bf16 v[84:87], v[76:79], v[220:223], v[112:115]
	v_mfma_f32_16x16x32_bf16 v[20:23], v[76:79], v[224:227], v[20:23]
	v_mfma_f32_16x16x32_bf16 v[24:27], v[208:211], v[220:223], v[24:27]
	v_mfma_f32_16x16x32_bf16 v[16:19], v[208:211], v[224:227], v[16:19]
	v_mfma_f32_16x16x32_bf16 v[36:39], v[212:215], v[220:223], v[36:39]
	v_mfma_f32_16x16x32_bf16 v[12:15], v[212:215], v[224:227], v[12:15]
	v_mfma_f32_16x16x32_bf16 v[32:35], v[216:219], v[220:223], v[32:35]
	v_mfma_f32_16x16x32_bf16 v[8:11], v[216:219], v[224:227], v[8:11]
	global_load_dwordx4 v[76:79], v[102:103], off offset:512
	global_load_dwordx4 v[88:91], v[106:107], off offset:1024
	global_load_dwordx4 v[92:95], v[108:109], off offset:1024
	global_load_dwordx4 v[112:115], v[104:105], off offset:1024
	global_load_dwordx4 v[170:173], v[110:111], off offset:512
	ds_read_b128 v[204:207], v124 offset:64
	ds_read_b128 v[208:211], v124 offset:2624
	ds_read_b128 v[212:215], v124 offset:5184
	ds_read_b128 v[216:219], v124 offset:7744
	ds_read_b128 v[220:223], v146 offset:41024
	ds_read_b128 v[224:227], v146 offset:43584
	s_waitcnt lgkmcnt(7)
	v_mfma_f32_16x16x32_bf16 v[84:87], v[52:55], v[72:75], v[84:87]
	s_waitcnt vmcnt(9)
	ds_write_b128 v125, v[28:31] offset:61440
	s_waitcnt vmcnt(5)
	ds_write_b128 v126, v[64:67]
	s_waitcnt lgkmcnt(8)
	v_mfma_f32_16x16x32_bf16 v[20:23], v[52:55], v[80:83], v[20:23]
	v_mfma_f32_16x16x32_bf16 v[24:27], v[56:59], v[72:75], v[24:27]
	ds_write_b128 v127, v[40:43] offset:61440
	v_mfma_f32_16x16x32_bf16 v[16:19], v[56:59], v[80:83], v[16:19]
	v_mfma_f32_16x16x32_bf16 v[28:31], v[60:63], v[72:75], v[36:39]
	ds_write_b128 v128, v[44:47] offset:61440
	v_mfma_f32_16x16x32_bf16 v[12:15], v[60:63], v[80:83], v[12:15]
	v_mfma_f32_16x16x32_bf16 v[32:35], v[68:71], v[72:75], v[32:35]
	ds_write_b128 v129, v[48:51] offset:61440
	v_mfma_f32_16x16x32_bf16 v[8:11], v[68:71], v[80:83], v[8:11]
	s_waitcnt lgkmcnt(0)
	s_barrier
;     ...
;   for (int k0 = 0; k0 < K; k0 += 128) {
;     G_READ(fa1, fb1, 0, 32);
;     if (k0 + 128 < K) G_LOAD(ra0, rb0, k0 + 128);
;     __builtin_amdgcn_sched_barrier(0);
;     G_MFMA_ST(fa0, fb0, ra1, rb1, 1);
;     __syncthreads();
;     G_READ(fa0, fb0, 1, 0);
;     __builtin_amdgcn_sched_barrier(0);
;     G_MFMA(fa1, fb1);
;     __builtin_amdgcn_sched_barrier(0);
;     G_READ(fa1, fb1, 1, 32);
;     if (k0 + 192 < K) G_LOAD(ra1, rb1, k0 + 192);
;     __builtin_amdgcn_sched_barrier(0);
;     if (k0 + 128 < K) {
;       G_MFMA_ST(fa0, fb0, ra0, rb0, 0);
;       __syncthreads();
;       G_READ(fa0, fb0, 0, 0);
;     } else {
;       G_MFMA(fa0, fb0);
;     }
;     __builtin_amdgcn_sched_barrier(0);
;     G_MFMA(fa1, fb1);
;     __builtin_amdgcn_sched_barrier(0);
;   }
	ds_read_b128 v[36:39], v124 offset:61440
	ds_read_b128 v[40:43], v124 offset:64000
	ds_read_b128 v[44:47], v147 offset:5120
	ds_read_b128 v[48:51], v147 offset:7680
	ds_read_b128 v[52:55], v151
	ds_read_b128 v[56:59], v151 offset:2560
	v_mfma_f32_16x16x32_bf16 v[60:63], v[204:207], v[220:223], v[84:87]
	v_mfma_f32_16x16x32_bf16 v[20:23], v[204:207], v[224:227], v[20:23]
	v_mfma_f32_16x16x32_bf16 v[24:27], v[208:211], v[220:223], v[24:27]
	v_mfma_f32_16x16x32_bf16 v[16:19], v[208:211], v[224:227], v[16:19]
	v_mfma_f32_16x16x32_bf16 v[28:31], v[212:215], v[220:223], v[28:31]
	v_mfma_f32_16x16x32_bf16 v[12:15], v[212:215], v[224:227], v[12:15]
	v_mfma_f32_16x16x32_bf16 v[32:35], v[216:219], v[220:223], v[32:35]
	v_mfma_f32_16x16x32_bf16 v[8:11], v[216:219], v[224:227], v[8:11]
	global_load_dwordx4 v[64:67], v[102:103], off offset:640
	global_load_dwordx4 v[68:71], v[106:107], off offset:1152
	global_load_dwordx4 v[72:75], v[108:109], off offset:1152
	global_load_dwordx4 v[80:83], v[104:105], off offset:1152
	global_load_dwordx4 v[84:87], v[110:111], off offset:640
	ds_read_b128 v[204:207], v124 offset:61504
	ds_read_b128 v[208:211], v124 offset:64064
	ds_read_b128 v[212:215], v152 offset:64
	ds_read_b128 v[216:219], v153 offset:64
	ds_read_b128 v[220:223], v203 offset:64
	ds_read_b128 v[224:227], v154 offset:64
	s_waitcnt lgkmcnt(7)
	v_mfma_f32_16x16x32_bf16 v[60:63], v[36:39], v[52:55], v[60:63]
	s_waitcnt vmcnt(9)
	ds_write_b128 v125, v[76:79]
	s_waitcnt vmcnt(5)
	ds_write_b128 v125, v[170:173] offset:40960
	s_waitcnt lgkmcnt(8)
	v_mfma_f32_16x16x32_bf16 v[20:23], v[36:39], v[56:59], v[20:23]
	v_mfma_f32_16x16x32_bf16 v[24:27], v[40:43], v[52:55], v[24:27]
	ds_write_b128 v125, v[88:91] offset:10240
	v_mfma_f32_16x16x32_bf16 v[16:19], v[40:43], v[56:59], v[16:19]
	v_mfma_f32_16x16x32_bf16 v[28:31], v[44:47], v[52:55], v[28:31]
	ds_write_b128 v125, v[92:95] offset:20480
	v_mfma_f32_16x16x32_bf16 v[12:15], v[44:47], v[56:59], v[12:15]
	v_mfma_f32_16x16x32_bf16 v[32:35], v[48:51], v[52:55], v[32:35]
	ds_write_b128 v125, v[112:115] offset:30720
	v_mfma_f32_16x16x32_bf16 v[8:11], v[48:51], v[56:59], v[8:11]
	s_waitcnt lgkmcnt(0)
	s_barrier
	ds_read_b128 v[36:39], v124
	ds_read_b128 v[40:43], v124 offset:2560
	ds_read_b128 v[44:47], v124 offset:5120
	ds_read_b128 v[48:51], v124 offset:7680
	ds_read_b128 v[52:55], v202 offset:40960
	ds_read_b128 v[56:59], v202 offset:43520
	v_mfma_f32_16x16x32_bf16 v[60:63], v[204:207], v[220:223], v[60:63]
	v_mfma_f32_16x16x32_bf16 v[20:23], v[204:207], v[224:227], v[20:23]
	v_mfma_f32_16x16x32_bf16 v[24:27], v[208:211], v[220:223], v[24:27]
	v_mfma_f32_16x16x32_bf16 v[16:19], v[208:211], v[224:227], v[16:19]
	v_mfma_f32_16x16x32_bf16 v[28:31], v[212:215], v[220:223], v[28:31]
	v_mfma_f32_16x16x32_bf16 v[12:15], v[212:215], v[224:227], v[12:15]
	v_mfma_f32_16x16x32_bf16 v[32:35], v[216:219], v[220:223], v[32:35]
	v_mfma_f32_16x16x32_bf16 v[8:11], v[216:219], v[224:227], v[8:11]
	global_load_dwordx4 v[76:79], v[102:103], off offset:768
	global_load_dwordx4 v[88:91], v[106:107], off offset:1280
	global_load_dwordx4 v[92:95], v[108:109], off offset:1280
	global_load_dwordx4 v[112:115], v[104:105], off offset:1280
	global_load_dwordx4 v[170:173], v[110:111], off offset:768
	ds_read_b128 v[204:207], v124 offset:64
	ds_read_b128 v[208:211], v124 offset:2624
	ds_read_b128 v[212:215], v124 offset:5184
	ds_read_b128 v[216:219], v124 offset:7744
	ds_read_b128 v[220:223], v146 offset:41024
	ds_read_b128 v[224:227], v146 offset:43584
	s_waitcnt lgkmcnt(7)
	v_mfma_f32_16x16x32_bf16 v[60:63], v[36:39], v[52:55], v[60:63]
	s_waitcnt vmcnt(9)
	ds_write_b128 v125, v[64:67] offset:61440
	s_waitcnt vmcnt(5)
	ds_write_b128 v126, v[84:87]
	s_waitcnt lgkmcnt(8)
	v_mfma_f32_16x16x32_bf16 v[20:23], v[36:39], v[56:59], v[20:23]
	v_mfma_f32_16x16x32_bf16 v[24:27], v[40:43], v[52:55], v[24:27]
	ds_write_b128 v127, v[68:71] offset:61440
	v_mfma_f32_16x16x32_bf16 v[16:19], v[40:43], v[56:59], v[16:19]
	v_mfma_f32_16x16x32_bf16 v[28:31], v[44:47], v[52:55], v[28:31]
	ds_write_b128 v128, v[72:75] offset:61440
	v_mfma_f32_16x16x32_bf16 v[12:15], v[44:47], v[56:59], v[12:15]
	v_mfma_f32_16x16x32_bf16 v[32:35], v[48:51], v[52:55], v[32:35]
	ds_write_b128 v129, v[80:83] offset:61440
	v_mfma_f32_16x16x32_bf16 v[8:11], v[48:51], v[56:59], v[8:11]
	s_waitcnt lgkmcnt(0)
	s_barrier
	ds_read_b128 v[36:39], v124 offset:61440
	ds_read_b128 v[40:43], v124 offset:64000
	ds_read_b128 v[44:47], v147 offset:5120
	ds_read_b128 v[48:51], v147 offset:7680
	ds_read_b128 v[52:55], v151
	ds_read_b128 v[56:59], v151 offset:2560
	v_mfma_f32_16x16x32_bf16 v[60:63], v[204:207], v[220:223], v[60:63]
	v_mfma_f32_16x16x32_bf16 v[20:23], v[204:207], v[224:227], v[20:23]
	v_mfma_f32_16x16x32_bf16 v[24:27], v[208:211], v[220:223], v[24:27]
	v_mfma_f32_16x16x32_bf16 v[16:19], v[208:211], v[224:227], v[16:19]
	v_mfma_f32_16x16x32_bf16 v[28:31], v[212:215], v[220:223], v[28:31]
	v_mfma_f32_16x16x32_bf16 v[12:15], v[212:215], v[224:227], v[12:15]
	v_mfma_f32_16x16x32_bf16 v[32:35], v[216:219], v[220:223], v[32:35]
	v_mfma_f32_16x16x32_bf16 v[8:11], v[216:219], v[224:227], v[8:11]
	global_load_dwordx4 v[64:67], v[102:103], off offset:896
	global_load_dwordx4 v[68:71], v[106:107], off offset:1408
	global_load_dwordx4 v[72:75], v[108:109], off offset:1408
	global_load_dwordx4 v[80:83], v[104:105], off offset:1408
	global_load_dwordx4 v[84:87], v[110:111], off offset:896
	ds_read_b128 v[204:207], v124 offset:61504
	ds_read_b128 v[208:211], v124 offset:64064
	ds_read_b128 v[212:215], v152 offset:64
	ds_read_b128 v[216:219], v153 offset:64
	ds_read_b128 v[220:223], v203 offset:64
	ds_read_b128 v[224:227], v154 offset:64
	s_waitcnt lgkmcnt(7)
	v_mfma_f32_16x16x32_bf16 v[60:63], v[36:39], v[52:55], v[60:63]
	s_waitcnt vmcnt(9)
	ds_write_b128 v125, v[76:79]
	s_waitcnt vmcnt(5)
	ds_write_b128 v125, v[170:173] offset:40960
	s_waitcnt lgkmcnt(8)
	v_mfma_f32_16x16x32_bf16 v[20:23], v[36:39], v[56:59], v[20:23]
	v_mfma_f32_16x16x32_bf16 v[24:27], v[40:43], v[52:55], v[24:27]
	ds_write_b128 v125, v[88:91] offset:10240
	v_mfma_f32_16x16x32_bf16 v[16:19], v[40:43], v[56:59], v[16:19]
	v_mfma_f32_16x16x32_bf16 v[28:31], v[44:47], v[52:55], v[28:31]
	ds_write_b128 v125, v[92:95] offset:20480
	v_mfma_f32_16x16x32_bf16 v[12:15], v[44:47], v[56:59], v[12:15]
	v_mfma_f32_16x16x32_bf16 v[32:35], v[48:51], v[52:55], v[32:35]
	ds_write_b128 v125, v[112:115] offset:30720
	v_mfma_f32_16x16x32_bf16 v[8:11], v[48:51], v[56:59], v[8:11]
	s_waitcnt lgkmcnt(0)
	s_barrier
;     ...
;   for (int k0 = 0; k0 < K; k0 += 128) {
;     G_READ(fa1, fb1, 0, 32);
;     if (k0 + 128 < K) G_LOAD(ra0, rb0, k0 + 128);
;     __builtin_amdgcn_sched_barrier(0);
;     G_MFMA_ST(fa0, fb0, ra1, rb1, 1);
;     __syncthreads();
;     G_READ(fa0, fb0, 1, 0);
;     __builtin_amdgcn_sched_barrier(0);
;     G_MFMA(fa1, fb1);
;     __builtin_amdgcn_sched_barrier(0);
;     G_READ(fa1, fb1, 1, 32);
;     if (k0 + 192 < K) G_LOAD(ra1, rb1, k0 + 192);
;     __builtin_amdgcn_sched_barrier(0);
;     if (k0 + 128 < K) {
;       G_MFMA_ST(fa0, fb0, ra0, rb0, 0);
;       __syncthreads();
;       G_READ(fa0, fb0, 0, 0);
;     } else {
;       G_MFMA(fa0, fb0);
;     }
;     __builtin_amdgcn_sched_barrier(0);
;     G_MFMA(fa1, fb1);
;     __builtin_amdgcn_sched_barrier(0);
;   }
	ds_read_b128 v[36:39], v124
	ds_read_b128 v[40:43], v124 offset:2560
	ds_read_b128 v[44:47], v124 offset:5120
	ds_read_b128 v[48:51], v124 offset:7680
	ds_read_b128 v[52:55], v202 offset:40960
	ds_read_b128 v[56:59], v202 offset:43520
	v_mfma_f32_16x16x32_bf16 v[60:63], v[204:207], v[220:223], v[60:63]
	v_mfma_f32_16x16x32_bf16 v[20:23], v[204:207], v[224:227], v[20:23]
	v_mfma_f32_16x16x32_bf16 v[24:27], v[208:211], v[220:223], v[24:27]
	v_mfma_f32_16x16x32_bf16 v[16:19], v[208:211], v[224:227], v[16:19]
	v_mfma_f32_16x16x32_bf16 v[28:31], v[212:215], v[220:223], v[28:31]
	v_mfma_f32_16x16x32_bf16 v[12:15], v[212:215], v[224:227], v[12:15]
	v_mfma_f32_16x16x32_bf16 v[32:35], v[216:219], v[220:223], v[32:35]
	v_mfma_f32_16x16x32_bf16 v[8:11], v[216:219], v[224:227], v[8:11]
	global_load_dwordx4 v[76:79], v[102:103], off offset:1024
	global_load_dwordx4 v[88:91], v[106:107], off offset:1536
	global_load_dwordx4 v[92:95], v[108:109], off offset:1536
	global_load_dwordx4 v[112:115], v[104:105], off offset:1536
	global_load_dwordx4 v[170:173], v[110:111], off offset:1024
	ds_read_b128 v[204:207], v124 offset:64
	ds_read_b128 v[208:211], v124 offset:2624
	ds_read_b128 v[212:215], v124 offset:5184
	ds_read_b128 v[216:219], v124 offset:7744
	ds_read_b128 v[220:223], v146 offset:41024
	ds_read_b128 v[224:227], v146 offset:43584
	s_waitcnt lgkmcnt(7)
	v_mfma_f32_16x16x32_bf16 v[60:63], v[36:39], v[52:55], v[60:63]
	s_waitcnt vmcnt(9)
	ds_write_b128 v125, v[64:67] offset:61440
	s_waitcnt vmcnt(5)
	ds_write_b128 v126, v[84:87]
	s_waitcnt lgkmcnt(8)
	v_mfma_f32_16x16x32_bf16 v[20:23], v[36:39], v[56:59], v[20:23]
	v_mfma_f32_16x16x32_bf16 v[24:27], v[40:43], v[52:55], v[24:27]
	ds_write_b128 v127, v[68:71] offset:61440
	v_mfma_f32_16x16x32_bf16 v[16:19], v[40:43], v[56:59], v[16:19]
	v_mfma_f32_16x16x32_bf16 v[28:31], v[44:47], v[52:55], v[28:31]
	ds_write_b128 v128, v[72:75] offset:61440
	v_mfma_f32_16x16x32_bf16 v[12:15], v[44:47], v[56:59], v[12:15]
	v_mfma_f32_16x16x32_bf16 v[32:35], v[48:51], v[52:55], v[32:35]
	ds_write_b128 v129, v[80:83] offset:61440
	v_mfma_f32_16x16x32_bf16 v[8:11], v[48:51], v[56:59], v[8:11]
	s_waitcnt lgkmcnt(0)
	s_barrier
	ds_read_b128 v[36:39], v124 offset:61440
	ds_read_b128 v[40:43], v124 offset:64000
	ds_read_b128 v[44:47], v147 offset:5120
	ds_read_b128 v[48:51], v147 offset:7680
	ds_read_b128 v[52:55], v151
	ds_read_b128 v[56:59], v151 offset:2560
	v_mfma_f32_16x16x32_bf16 v[60:63], v[204:207], v[220:223], v[60:63]
	v_mfma_f32_16x16x32_bf16 v[20:23], v[204:207], v[224:227], v[20:23]
	v_mfma_f32_16x16x32_bf16 v[24:27], v[208:211], v[220:223], v[24:27]
	v_mfma_f32_16x16x32_bf16 v[16:19], v[208:211], v[224:227], v[16:19]
	v_mfma_f32_16x16x32_bf16 v[28:31], v[212:215], v[220:223], v[28:31]
	v_mfma_f32_16x16x32_bf16 v[12:15], v[212:215], v[224:227], v[12:15]
	v_mfma_f32_16x16x32_bf16 v[32:35], v[216:219], v[220:223], v[32:35]
	v_mfma_f32_16x16x32_bf16 v[8:11], v[216:219], v[224:227], v[8:11]
	global_load_dwordx4 v[64:67], v[102:103], off offset:1152
	global_load_dwordx4 v[68:71], v[106:107], off offset:1664
	global_load_dwordx4 v[72:75], v[108:109], off offset:1664
	global_load_dwordx4 v[80:83], v[104:105], off offset:1664
	global_load_dwordx4 v[84:87], v[110:111], off offset:1152
	ds_read_b128 v[204:207], v124 offset:61504
	ds_read_b128 v[208:211], v124 offset:64064
	ds_read_b128 v[212:215], v152 offset:64
	ds_read_b128 v[216:219], v153 offset:64
	ds_read_b128 v[220:223], v203 offset:64
	ds_read_b128 v[224:227], v154 offset:64
	s_waitcnt lgkmcnt(7)
	v_mfma_f32_16x16x32_bf16 v[60:63], v[36:39], v[52:55], v[60:63]
	s_waitcnt vmcnt(9)
	ds_write_b128 v125, v[76:79]
	s_waitcnt vmcnt(5)
	ds_write_b128 v125, v[170:173] offset:40960
	s_waitcnt lgkmcnt(8)
	v_mfma_f32_16x16x32_bf16 v[20:23], v[36:39], v[56:59], v[20:23]
	v_mfma_f32_16x16x32_bf16 v[24:27], v[40:43], v[52:55], v[24:27]
	ds_write_b128 v125, v[88:91] offset:10240
	v_mfma_f32_16x16x32_bf16 v[16:19], v[40:43], v[56:59], v[16:19]
	v_mfma_f32_16x16x32_bf16 v[28:31], v[44:47], v[52:55], v[28:31]
	ds_write_b128 v125, v[92:95] offset:20480
	v_mfma_f32_16x16x32_bf16 v[12:15], v[44:47], v[56:59], v[12:15]
	v_mfma_f32_16x16x32_bf16 v[32:35], v[48:51], v[52:55], v[32:35]
	ds_write_b128 v125, v[112:115] offset:30720
	v_mfma_f32_16x16x32_bf16 v[8:11], v[48:51], v[56:59], v[8:11]
	s_waitcnt lgkmcnt(0)
	s_barrier
	ds_read_b128 v[36:39], v124
	ds_read_b128 v[40:43], v124 offset:2560
	ds_read_b128 v[44:47], v124 offset:5120
	ds_read_b128 v[48:51], v124 offset:7680
	ds_read_b128 v[52:55], v202 offset:40960
	ds_read_b128 v[56:59], v202 offset:43520
	v_mfma_f32_16x16x32_bf16 v[60:63], v[204:207], v[220:223], v[60:63]
	v_mfma_f32_16x16x32_bf16 v[20:23], v[204:207], v[224:227], v[20:23]
	v_mfma_f32_16x16x32_bf16 v[24:27], v[208:211], v[220:223], v[24:27]
	v_mfma_f32_16x16x32_bf16 v[16:19], v[208:211], v[224:227], v[16:19]
	v_mfma_f32_16x16x32_bf16 v[28:31], v[212:215], v[220:223], v[28:31]
	v_mfma_f32_16x16x32_bf16 v[12:15], v[212:215], v[224:227], v[12:15]
	v_mfma_f32_16x16x32_bf16 v[32:35], v[216:219], v[220:223], v[32:35]
	v_mfma_f32_16x16x32_bf16 v[8:11], v[216:219], v[224:227], v[8:11]
	global_load_dwordx4 v[76:79], v[102:103], off offset:1280
	global_load_dwordx4 v[88:91], v[106:107], off offset:1792
	global_load_dwordx4 v[92:95], v[108:109], off offset:1792
	global_load_dwordx4 v[112:115], v[104:105], off offset:1792
	global_load_dwordx4 v[170:173], v[110:111], off offset:1280
	ds_read_b128 v[204:207], v124 offset:64
	ds_read_b128 v[208:211], v124 offset:2624
	ds_read_b128 v[212:215], v124 offset:5184
	ds_read_b128 v[216:219], v124 offset:7744
	ds_read_b128 v[220:223], v146 offset:41024
	ds_read_b128 v[224:227], v146 offset:43584
	s_waitcnt lgkmcnt(7)
	v_mfma_f32_16x16x32_bf16 v[60:63], v[36:39], v[52:55], v[60:63]
	s_waitcnt vmcnt(9)
	ds_write_b128 v125, v[64:67] offset:61440
	s_waitcnt vmcnt(5)
	ds_write_b128 v126, v[84:87]
	s_waitcnt lgkmcnt(8)
	v_mfma_f32_16x16x32_bf16 v[20:23], v[36:39], v[56:59], v[20:23]
	v_mfma_f32_16x16x32_bf16 v[24:27], v[40:43], v[52:55], v[24:27]
	ds_write_b128 v127, v[68:71] offset:61440
	v_mfma_f32_16x16x32_bf16 v[16:19], v[40:43], v[56:59], v[16:19]
	v_mfma_f32_16x16x32_bf16 v[28:31], v[44:47], v[52:55], v[28:31]
	ds_write_b128 v128, v[72:75] offset:61440
	v_mfma_f32_16x16x32_bf16 v[12:15], v[44:47], v[56:59], v[12:15]
	v_mfma_f32_16x16x32_bf16 v[32:35], v[48:51], v[52:55], v[32:35]
	ds_write_b128 v129, v[80:83] offset:61440
	v_mfma_f32_16x16x32_bf16 v[8:11], v[48:51], v[56:59], v[8:11]
	s_waitcnt lgkmcnt(0)
	s_barrier
;     ...
;   for (int k0 = 0; k0 < K; k0 += 128) {
;     G_READ(fa1, fb1, 0, 32);
;     if (k0 + 128 < K) G_LOAD(ra0, rb0, k0 + 128);
;     __builtin_amdgcn_sched_barrier(0);
;     G_MFMA_ST(fa0, fb0, ra1, rb1, 1);
;     __syncthreads();
;     G_READ(fa0, fb0, 1, 0);
;     __builtin_amdgcn_sched_barrier(0);
;     G_MFMA(fa1, fb1);
;     __builtin_amdgcn_sched_barrier(0);
;     G_READ(fa1, fb1, 1, 32);
;     if (k0 + 192 < K) G_LOAD(ra1, rb1, k0 + 192);
;     __builtin_amdgcn_sched_barrier(0);
;     if (k0 + 128 < K) {
;       G_MFMA_ST(fa0, fb0, ra0, rb0, 0);
;       __syncthreads();
;       G_READ(fa0, fb0, 0, 0);
;     } else {
;       G_MFMA(fa0, fb0);
;     }
;     __builtin_amdgcn_sched_barrier(0);
;     G_MFMA(fa1, fb1);
;     __builtin_amdgcn_sched_barrier(0);
;   }
	ds_read_b128 v[36:39], v124 offset:61440
	ds_read_b128 v[40:43], v124 offset:64000
	ds_read_b128 v[44:47], v147 offset:5120
	ds_read_b128 v[48:51], v147 offset:7680
	ds_read_b128 v[52:55], v151
	ds_read_b128 v[56:59], v151 offset:2560
	v_mfma_f32_16x16x32_bf16 v[60:63], v[204:207], v[220:223], v[60:63]
	v_mfma_f32_16x16x32_bf16 v[20:23], v[204:207], v[224:227], v[20:23]
	v_mfma_f32_16x16x32_bf16 v[24:27], v[208:211], v[220:223], v[24:27]
	v_mfma_f32_16x16x32_bf16 v[16:19], v[208:211], v[224:227], v[16:19]
	v_mfma_f32_16x16x32_bf16 v[28:31], v[212:215], v[220:223], v[28:31]
	v_mfma_f32_16x16x32_bf16 v[12:15], v[212:215], v[224:227], v[12:15]
	v_mfma_f32_16x16x32_bf16 v[32:35], v[216:219], v[220:223], v[32:35]
	v_mfma_f32_16x16x32_bf16 v[8:11], v[216:219], v[224:227], v[8:11]
	global_load_dwordx4 v[64:67], v[102:103], off offset:1408
	global_load_dwordx4 v[68:71], v[106:107], off offset:1920
	global_load_dwordx4 v[72:75], v[108:109], off offset:1920
	global_load_dwordx4 v[80:83], v[104:105], off offset:1920
	global_load_dwordx4 v[84:87], v[110:111], off offset:1408
	ds_read_b128 v[204:207], v124 offset:61504
	ds_read_b128 v[208:211], v124 offset:64064
	ds_read_b128 v[212:215], v152 offset:64
	ds_read_b128 v[216:219], v153 offset:64
	ds_read_b128 v[220:223], v203 offset:64
	ds_read_b128 v[224:227], v154 offset:64
	s_waitcnt lgkmcnt(7)
	v_mfma_f32_16x16x32_bf16 v[60:63], v[36:39], v[52:55], v[60:63]
	s_waitcnt vmcnt(9)
	ds_write_b128 v125, v[76:79]
	s_waitcnt vmcnt(5)
	ds_write_b128 v125, v[170:173] offset:40960
	s_waitcnt lgkmcnt(8)
	v_mfma_f32_16x16x32_bf16 v[20:23], v[36:39], v[56:59], v[20:23]
	v_mfma_f32_16x16x32_bf16 v[24:27], v[40:43], v[52:55], v[24:27]
	ds_write_b128 v125, v[88:91] offset:10240
	v_mfma_f32_16x16x32_bf16 v[16:19], v[40:43], v[56:59], v[16:19]
	v_mfma_f32_16x16x32_bf16 v[28:31], v[44:47], v[52:55], v[28:31]
	ds_write_b128 v125, v[92:95] offset:20480
	v_mfma_f32_16x16x32_bf16 v[12:15], v[44:47], v[56:59], v[12:15]
	v_mfma_f32_16x16x32_bf16 v[32:35], v[48:51], v[52:55], v[32:35]
	ds_write_b128 v125, v[112:115] offset:30720
	v_mfma_f32_16x16x32_bf16 v[8:11], v[48:51], v[56:59], v[8:11]
	s_waitcnt lgkmcnt(0)
	s_barrier
	ds_read_b128 v[36:39], v124
	ds_read_b128 v[40:43], v124 offset:2560
	ds_read_b128 v[44:47], v124 offset:5120
	ds_read_b128 v[48:51], v124 offset:7680
	ds_read_b128 v[52:55], v202 offset:40960
	ds_read_b128 v[56:59], v202 offset:43520
	v_mfma_f32_16x16x32_bf16 v[60:63], v[204:207], v[220:223], v[60:63]
	v_mfma_f32_16x16x32_bf16 v[20:23], v[204:207], v[224:227], v[20:23]
	v_mfma_f32_16x16x32_bf16 v[24:27], v[208:211], v[220:223], v[24:27]
	v_mfma_f32_16x16x32_bf16 v[16:19], v[208:211], v[224:227], v[16:19]
	v_mfma_f32_16x16x32_bf16 v[28:31], v[212:215], v[220:223], v[28:31]
	v_mfma_f32_16x16x32_bf16 v[12:15], v[212:215], v[224:227], v[12:15]
	v_mfma_f32_16x16x32_bf16 v[32:35], v[216:219], v[220:223], v[32:35]
	v_mfma_f32_16x16x32_bf16 v[8:11], v[216:219], v[224:227], v[8:11]
	global_load_dwordx4 v[76:79], v[102:103], off offset:1536
	global_load_dwordx4 v[88:91], v[106:107], off offset:2048
	global_load_dwordx4 v[92:95], v[108:109], off offset:2048
	global_load_dwordx4 v[112:115], v[104:105], off offset:2048
	global_load_dwordx4 v[170:173], v[110:111], off offset:1536
	ds_read_b128 v[204:207], v124 offset:64
	ds_read_b128 v[208:211], v124 offset:2624
	ds_read_b128 v[212:215], v124 offset:5184
	ds_read_b128 v[216:219], v124 offset:7744
	ds_read_b128 v[220:223], v146 offset:41024
	ds_read_b128 v[224:227], v146 offset:43584
	s_waitcnt lgkmcnt(7)
	v_mfma_f32_16x16x32_bf16 v[60:63], v[36:39], v[52:55], v[60:63]
	s_waitcnt vmcnt(9)
	ds_write_b128 v125, v[64:67] offset:61440
	s_waitcnt vmcnt(5)
	ds_write_b128 v126, v[84:87]
	s_waitcnt lgkmcnt(8)
	v_mfma_f32_16x16x32_bf16 v[20:23], v[36:39], v[56:59], v[20:23]
	v_mfma_f32_16x16x32_bf16 v[24:27], v[40:43], v[52:55], v[24:27]
	ds_write_b128 v127, v[68:71] offset:61440
	v_mfma_f32_16x16x32_bf16 v[16:19], v[40:43], v[56:59], v[16:19]
	v_mfma_f32_16x16x32_bf16 v[28:31], v[44:47], v[52:55], v[28:31]
	ds_write_b128 v128, v[72:75] offset:61440
	v_mfma_f32_16x16x32_bf16 v[12:15], v[44:47], v[56:59], v[12:15]
	v_mfma_f32_16x16x32_bf16 v[32:35], v[48:51], v[52:55], v[32:35]
	ds_write_b128 v129, v[80:83] offset:61440
	v_mfma_f32_16x16x32_bf16 v[8:11], v[48:51], v[56:59], v[8:11]
	s_waitcnt lgkmcnt(0)
	s_barrier
	ds_read_b128 v[36:39], v124 offset:61440
	ds_read_b128 v[40:43], v124 offset:64000
	ds_read_b128 v[44:47], v147 offset:5120
	ds_read_b128 v[48:51], v147 offset:7680
	ds_read_b128 v[52:55], v151
	ds_read_b128 v[56:59], v151 offset:2560
	v_mfma_f32_16x16x32_bf16 v[60:63], v[204:207], v[220:223], v[60:63]
	v_mfma_f32_16x16x32_bf16 v[20:23], v[204:207], v[224:227], v[20:23]
	v_mfma_f32_16x16x32_bf16 v[24:27], v[208:211], v[220:223], v[24:27]
	v_mfma_f32_16x16x32_bf16 v[16:19], v[208:211], v[224:227], v[16:19]
	v_mfma_f32_16x16x32_bf16 v[28:31], v[212:215], v[220:223], v[28:31]
	v_mfma_f32_16x16x32_bf16 v[12:15], v[212:215], v[224:227], v[12:15]
	v_mfma_f32_16x16x32_bf16 v[32:35], v[216:219], v[220:223], v[32:35]
	v_mfma_f32_16x16x32_bf16 v[8:11], v[216:219], v[224:227], v[8:11]
	global_load_dwordx4 v[64:67], v[102:103], off offset:1664
	global_load_dwordx4 v[68:71], v[106:107], off offset:2176
	global_load_dwordx4 v[72:75], v[108:109], off offset:2176
	global_load_dwordx4 v[80:83], v[104:105], off offset:2176
	global_load_dwordx4 v[84:87], v[110:111], off offset:1664
	ds_read_b128 v[204:207], v124 offset:61504
	ds_read_b128 v[208:211], v124 offset:64064
	ds_read_b128 v[212:215], v152 offset:64
	ds_read_b128 v[216:219], v153 offset:64
	ds_read_b128 v[220:223], v203 offset:64
	ds_read_b128 v[224:227], v154 offset:64
	s_waitcnt lgkmcnt(7)
	v_mfma_f32_16x16x32_bf16 v[60:63], v[36:39], v[52:55], v[60:63]
	s_waitcnt vmcnt(9)
	ds_write_b128 v125, v[76:79]
	s_waitcnt vmcnt(5)
	ds_write_b128 v125, v[170:173] offset:40960
	s_waitcnt lgkmcnt(8)
	v_mfma_f32_16x16x32_bf16 v[20:23], v[36:39], v[56:59], v[20:23]
	v_mfma_f32_16x16x32_bf16 v[24:27], v[40:43], v[52:55], v[24:27]
	ds_write_b128 v125, v[88:91] offset:10240
	v_mfma_f32_16x16x32_bf16 v[16:19], v[40:43], v[56:59], v[16:19]
	v_mfma_f32_16x16x32_bf16 v[28:31], v[44:47], v[52:55], v[28:31]
	ds_write_b128 v125, v[92:95] offset:20480
	v_mfma_f32_16x16x32_bf16 v[12:15], v[44:47], v[56:59], v[12:15]
	v_mfma_f32_16x16x32_bf16 v[32:35], v[48:51], v[52:55], v[32:35]
	ds_write_b128 v125, v[112:115] offset:30720
	v_mfma_f32_16x16x32_bf16 v[8:11], v[48:51], v[56:59], v[8:11]
	s_waitcnt lgkmcnt(0)
	s_barrier
;     ...
;   for (int k0 = 0; k0 < K; k0 += 128) {
;     G_READ(fa1, fb1, 0, 32);
;     if (k0 + 128 < K) G_LOAD(ra0, rb0, k0 + 128);
;     __builtin_amdgcn_sched_barrier(0);
;     G_MFMA_ST(fa0, fb0, ra1, rb1, 1);
;     __syncthreads();
;     G_READ(fa0, fb0, 1, 0);
;     __builtin_amdgcn_sched_barrier(0);
;     G_MFMA(fa1, fb1);
;     __builtin_amdgcn_sched_barrier(0);
;     G_READ(fa1, fb1, 1, 32);
;     if (k0 + 192 < K) G_LOAD(ra1, rb1, k0 + 192);
;     __builtin_amdgcn_sched_barrier(0);
;     if (k0 + 128 < K) {
;       G_MFMA_ST(fa0, fb0, ra0, rb0, 0);
;       __syncthreads();
;       G_READ(fa0, fb0, 0, 0);
;     } else {
;       G_MFMA(fa0, fb0);
;     }
;     __builtin_amdgcn_sched_barrier(0);
;     G_MFMA(fa1, fb1);
;     __builtin_amdgcn_sched_barrier(0);
;   }
	ds_read_b128 v[36:39], v124
	ds_read_b128 v[40:43], v124 offset:2560
	ds_read_b128 v[44:47], v124 offset:5120
	ds_read_b128 v[48:51], v124 offset:7680
	ds_read_b128 v[52:55], v202 offset:40960
	ds_read_b128 v[56:59], v202 offset:43520
	v_mfma_f32_16x16x32_bf16 v[60:63], v[204:207], v[220:223], v[60:63]
	v_mfma_f32_16x16x32_bf16 v[20:23], v[204:207], v[224:227], v[20:23]
	v_mfma_f32_16x16x32_bf16 v[24:27], v[208:211], v[220:223], v[24:27]
	v_mfma_f32_16x16x32_bf16 v[16:19], v[208:211], v[224:227], v[16:19]
	v_mfma_f32_16x16x32_bf16 v[28:31], v[212:215], v[220:223], v[28:31]
	v_mfma_f32_16x16x32_bf16 v[12:15], v[212:215], v[224:227], v[12:15]
	v_mfma_f32_16x16x32_bf16 v[32:35], v[216:219], v[220:223], v[32:35]
	v_mfma_f32_16x16x32_bf16 v[8:11], v[216:219], v[224:227], v[8:11]
	global_load_dwordx4 v[76:79], v[102:103], off offset:1792
	global_load_dwordx4 v[88:91], v[106:107], off offset:2304
	global_load_dwordx4 v[92:95], v[108:109], off offset:2304
	global_load_dwordx4 v[112:115], v[104:105], off offset:2304
	global_load_dwordx4 v[170:173], v[110:111], off offset:1792
	ds_read_b128 v[204:207], v124 offset:64
	ds_read_b128 v[208:211], v124 offset:2624
	ds_read_b128 v[212:215], v124 offset:5184
	ds_read_b128 v[216:219], v124 offset:7744
	ds_read_b128 v[220:223], v146 offset:41024
	ds_read_b128 v[224:227], v146 offset:43584
	s_waitcnt lgkmcnt(7)
	v_mfma_f32_16x16x32_bf16 v[60:63], v[36:39], v[52:55], v[60:63]
	s_waitcnt vmcnt(9)
	ds_write_b128 v125, v[64:67] offset:61440
	s_waitcnt vmcnt(5)
	ds_write_b128 v126, v[84:87]
	s_waitcnt lgkmcnt(8)
	v_mfma_f32_16x16x32_bf16 v[20:23], v[36:39], v[56:59], v[20:23]
	v_mfma_f32_16x16x32_bf16 v[24:27], v[40:43], v[52:55], v[24:27]
	ds_write_b128 v127, v[68:71] offset:61440
	v_mfma_f32_16x16x32_bf16 v[16:19], v[40:43], v[56:59], v[16:19]
	v_mfma_f32_16x16x32_bf16 v[28:31], v[44:47], v[52:55], v[28:31]
	ds_write_b128 v128, v[72:75] offset:61440
	v_mfma_f32_16x16x32_bf16 v[12:15], v[44:47], v[56:59], v[12:15]
	v_mfma_f32_16x16x32_bf16 v[32:35], v[48:51], v[52:55], v[32:35]
	ds_write_b128 v129, v[80:83] offset:61440
	v_mfma_f32_16x16x32_bf16 v[8:11], v[48:51], v[56:59], v[8:11]
	s_waitcnt lgkmcnt(0)
	s_barrier
	ds_read_b128 v[36:39], v124 offset:61440
	ds_read_b128 v[40:43], v124 offset:64000
	ds_read_b128 v[44:47], v147 offset:5120
	ds_read_b128 v[48:51], v147 offset:7680
	ds_read_b128 v[52:55], v151
	ds_read_b128 v[56:59], v151 offset:2560
	v_mfma_f32_16x16x32_bf16 v[60:63], v[204:207], v[220:223], v[60:63]
	v_mfma_f32_16x16x32_bf16 v[20:23], v[204:207], v[224:227], v[20:23]
	v_mfma_f32_16x16x32_bf16 v[24:27], v[208:211], v[220:223], v[24:27]
	v_mfma_f32_16x16x32_bf16 v[16:19], v[208:211], v[224:227], v[16:19]
	v_mfma_f32_16x16x32_bf16 v[28:31], v[212:215], v[220:223], v[28:31]
	v_mfma_f32_16x16x32_bf16 v[12:15], v[212:215], v[224:227], v[12:15]
	v_mfma_f32_16x16x32_bf16 v[32:35], v[216:219], v[220:223], v[32:35]
	v_mfma_f32_16x16x32_bf16 v[8:11], v[216:219], v[224:227], v[8:11]
	global_load_dwordx4 v[64:67], v[102:103], off offset:1920
	global_load_dwordx4 v[68:71], v[106:107], off offset:2432
	global_load_dwordx4 v[72:75], v[108:109], off offset:2432
	global_load_dwordx4 v[80:83], v[104:105], off offset:2432
	global_load_dwordx4 v[84:87], v[110:111], off offset:1920
	ds_read_b128 v[102:105], v124 offset:61504
	ds_read_b128 v[106:109], v124 offset:64064
	ds_read_b128 v[204:207], v152 offset:64
	ds_read_b128 v[208:211], v153 offset:64
	ds_read_b128 v[212:215], v203 offset:64
	ds_read_b128 v[216:219], v154 offset:64
	s_waitcnt lgkmcnt(7)
	v_mfma_f32_16x16x32_bf16 v[60:63], v[36:39], v[52:55], v[60:63]
	s_waitcnt vmcnt(9)
	ds_write_b128 v125, v[76:79]
	s_waitcnt vmcnt(5)
	ds_write_b128 v125, v[170:173] offset:40960
	s_waitcnt lgkmcnt(8)
	v_mfma_f32_16x16x32_bf16 v[20:23], v[36:39], v[56:59], v[20:23]
	v_mfma_f32_16x16x32_bf16 v[24:27], v[40:43], v[52:55], v[24:27]
	ds_write_b128 v125, v[88:91] offset:10240
	v_mfma_f32_16x16x32_bf16 v[16:19], v[40:43], v[56:59], v[16:19]
	v_mfma_f32_16x16x32_bf16 v[28:31], v[44:47], v[52:55], v[28:31]
	ds_write_b128 v125, v[92:95] offset:20480
	v_mfma_f32_16x16x32_bf16 v[12:15], v[44:47], v[56:59], v[12:15]
	v_mfma_f32_16x16x32_bf16 v[32:35], v[48:51], v[52:55], v[32:35]
	ds_write_b128 v125, v[112:115] offset:30720
	v_mfma_f32_16x16x32_bf16 v[8:11], v[48:51], v[56:59], v[8:11]
	s_waitcnt lgkmcnt(0)
	s_barrier
	ds_read_b128 v[36:39], v124
	ds_read_b128 v[40:43], v124 offset:2560
	ds_read_b128 v[44:47], v124 offset:5120
	ds_read_b128 v[48:51], v124 offset:7680
	ds_read_b128 v[52:55], v202 offset:40960
	ds_read_b128 v[56:59], v202 offset:43520
	v_mfma_f32_16x16x32_bf16 v[60:63], v[102:105], v[212:215], v[60:63]
	v_mfma_f32_16x16x32_bf16 v[20:23], v[102:105], v[216:219], v[20:23]
	v_mfma_f32_16x16x32_bf16 v[24:27], v[106:109], v[212:215], v[24:27]
	v_mfma_f32_16x16x32_bf16 v[16:19], v[106:109], v[216:219], v[16:19]
	v_mfma_f32_16x16x32_bf16 v[28:31], v[204:207], v[212:215], v[28:31]
	v_mfma_f32_16x16x32_bf16 v[12:15], v[204:207], v[216:219], v[12:15]
	v_mfma_f32_16x16x32_bf16 v[32:35], v[208:211], v[212:215], v[32:35]
	v_mfma_f32_16x16x32_bf16 v[8:11], v[208:211], v[216:219], v[8:11]
	ds_read_b128 v[76:79], v124 offset:64
	ds_read_b128 v[88:91], v124 offset:2624
	ds_read_b128 v[92:95], v124 offset:5184
	ds_read_b128 v[102:105], v124 offset:7744
	ds_read_b128 v[106:109], v146 offset:41024
	ds_read_b128 v[110:113], v146 offset:43584
	s_waitcnt lgkmcnt(7)
	v_mfma_f32_16x16x32_bf16 v[60:63], v[36:39], v[52:55], v[60:63]
	s_waitcnt vmcnt(4)
	ds_write_b128 v125, v[64:67] offset:61440
	s_waitcnt vmcnt(0)
	ds_write_b128 v126, v[84:87]
	s_waitcnt lgkmcnt(8)
	v_mfma_f32_16x16x32_bf16 v[20:23], v[36:39], v[56:59], v[20:23]
	v_mfma_f32_16x16x32_bf16 v[24:27], v[40:43], v[52:55], v[24:27]
	ds_write_b128 v127, v[68:71] offset:61440
	v_mfma_f32_16x16x32_bf16 v[16:19], v[40:43], v[56:59], v[16:19]
	v_mfma_f32_16x16x32_bf16 v[28:31], v[44:47], v[52:55], v[28:31]
	ds_write_b128 v128, v[72:75] offset:61440
	v_mfma_f32_16x16x32_bf16 v[12:15], v[44:47], v[56:59], v[12:15]
	v_mfma_f32_16x16x32_bf16 v[32:35], v[48:51], v[52:55], v[32:35]
	ds_write_b128 v129, v[80:83] offset:61440
	v_mfma_f32_16x16x32_bf16 v[8:11], v[48:51], v[56:59], v[8:11]
	s_waitcnt lgkmcnt(0)
	s_barrier
; __device__ __forceinline__ float bflo(unsigned w) { return __uint_as_float(w << 16); }
; __device__ __forceinline__ float bfhi(unsigned w) { return __uint_as_float(w & 0xffff0000u); }
; template <int TN, bool NTS = false>
; __device__ __forceinline__ void store_tile_bf16(const f32x4 (&acc)[4][TN], bf16_t* __restrict__ dst, int ldd, bf16_t* sT,
;                                                 const int tidx) {
;     ...
;   __syncthreads();
; #pragma unroll
;   for (int i = 0; i < 4; i++)
; #pragma unroll
;     for (int j = 0; j < TN; j++)
; #pragma unroll
;       for (int r = 0; r < 4; r++)
;         sT[(wm * 64 + i * 16 + quad * 4 + r) * TS + wn * TN * 16 + j * 16 + l15] = f2bf(acc[i][j][r]);
; __device__ __forceinline__ void phase_merge(const Params& p, const int tidx) {
;     ...
; #pragma unroll
;       for (int i = 0; i < 4; i++)
; #pragma unroll
;         for (int j = 0; j < 2; j++) {
;           unsigned g0, g1;
;           if (br < 2) { g0 = gp[br < 2 ? br : 0][i][j][0]; g1 = gp[br < 2 ? br : 0][i][j][1]; }
;           else { g0 = sGate[((i * 2 + j) * 2 + 0) * NT + tidx]; g1 = sGate[((i * 2 + j) * 2 + 1) * NT + tidx]; }
;           mg[i][j][0] += bflo(g0) * t[i][j][0];
;           mg[i][j][1] += bfhi(g0) * t[i][j][1];
;           mg[i][j][2] += bflo(g1) * t[i][j][2];
;           mg[i][j][3] += bfhi(g1) * t[i][j][3];
;         }
	ds_read_b128 v[36:39], v124 offset:61440
	ds_read_b128 v[40:43], v124 offset:64000
	ds_read_b128 v[44:47], v147 offset:5120
	ds_read_b128 v[48:51], v147 offset:7680
	ds_read_b128 v[52:55], v151
	ds_read_b128 v[56:59], v151 offset:2560
	v_mfma_f32_16x16x32_bf16 v[60:63], v[76:79], v[106:109], v[60:63]
	v_mfma_f32_16x16x32_bf16 v[20:23], v[76:79], v[110:113], v[20:23]
	v_mfma_f32_16x16x32_bf16 v[24:27], v[88:91], v[106:109], v[24:27]
	v_mfma_f32_16x16x32_bf16 v[16:19], v[88:91], v[110:113], v[16:19]
	v_mfma_f32_16x16x32_bf16 v[28:31], v[92:95], v[106:109], v[28:31]
	v_mfma_f32_16x16x32_bf16 v[12:15], v[92:95], v[110:113], v[12:15]
	v_mfma_f32_16x16x32_bf16 v[32:35], v[102:105], v[106:109], v[32:35]
	v_mfma_f32_16x16x32_bf16 v[8:11], v[102:105], v[110:113], v[8:11]
	ds_read_b128 v[64:67], v124 offset:61504
	ds_read_b128 v[68:71], v124 offset:64064
	ds_read_b128 v[72:75], v152 offset:64
	ds_read_b128 v[76:79], v153 offset:64
	ds_read_b128 v[80:83], v203 offset:64
	ds_read_b128 v[84:87], v154 offset:64
	s_waitcnt lgkmcnt(7)
	v_mfma_f32_16x16x32_bf16 v[60:63], v[36:39], v[52:55], v[60:63]
	s_waitcnt lgkmcnt(6)
	v_mfma_f32_16x16x32_bf16 v[20:23], v[36:39], v[56:59], v[20:23]
	v_mfma_f32_16x16x32_bf16 v[24:27], v[40:43], v[52:55], v[24:27]
	v_mfma_f32_16x16x32_bf16 v[16:19], v[40:43], v[56:59], v[16:19]
	v_mfma_f32_16x16x32_bf16 v[28:31], v[44:47], v[52:55], v[28:31]
	v_mfma_f32_16x16x32_bf16 v[12:15], v[44:47], v[56:59], v[12:15]
	v_mfma_f32_16x16x32_bf16 v[32:35], v[48:51], v[52:55], v[32:35]
	v_mfma_f32_16x16x32_bf16 v[8:11], v[48:51], v[56:59], v[8:11]
	s_waitcnt lgkmcnt(1)
	v_mfma_f32_16x16x32_bf16 v[36:39], v[64:67], v[80:83], v[60:63]
	s_waitcnt lgkmcnt(0)
	v_mfma_f32_16x16x32_bf16 v[20:23], v[64:67], v[84:87], v[20:23]
	v_mfma_f32_16x16x32_bf16 v[24:27], v[68:71], v[80:83], v[24:27]
	v_mfma_f32_16x16x32_bf16 v[16:19], v[68:71], v[84:87], v[16:19]
	v_mfma_f32_16x16x32_bf16 v[28:31], v[72:75], v[80:83], v[28:31]
	v_mfma_f32_16x16x32_bf16 v[40:43], v[72:75], v[84:87], v[12:15]
	v_mfma_f32_16x16x32_bf16 v[12:15], v[76:79], v[80:83], v[32:35]
	v_mfma_f32_16x16x32_bf16 v[8:11], v[76:79], v[84:87], v[8:11]
	s_nop 1
	ds_read2st64_b32 v[32:33], v122 offset1:16
	ds_read_b32 v34, v131
	s_waitcnt lgkmcnt(1)
	v_lshlrev_b32_e32 v35, 16, v32
	v_and_b32_e32 v32, 0xffff0000, v32
	v_fmac_f32_e32 v157, v37, v32
	s_waitcnt lgkmcnt(0)
	v_lshlrev_b32_e32 v32, 16, v34
	v_fmac_f32_e32 v158, v38, v32
	v_and_b32_e32 v32, 0xffff0000, v34
	v_fmac_f32_e32 v159, v39, v32
	ds_read_b32 v32, v132
	v_lshlrev_b32_e32 v34, 16, v33
	v_fmac_f32_e32 v174, v20, v34
	v_and_b32_e32 v20, 0xffff0000, v33
	v_fmac_f32_e32 v175, v21, v20
	s_waitcnt lgkmcnt(0)
	v_lshlrev_b32_e32 v20, 16, v32
	v_fmac_f32_e32 v176, v22, v20
	v_and_b32_e32 v20, 0xffff0000, v32
	v_fmac_f32_e32 v177, v23, v20
	ds_read2st64_b32 v[20:21], v122 offset0:32 offset1:48
	ds_read_b32 v22, v133
	v_fmac_f32_e32 v156, v36, v35
	s_waitcnt lgkmcnt(1)
	v_lshlrev_b32_e32 v23, 16, v20
	v_and_b32_e32 v20, 0xffff0000, v20
	v_fmac_f32_e32 v179, v25, v20
	s_waitcnt lgkmcnt(0)
	v_lshlrev_b32_e32 v20, 16, v22
	v_fmac_f32_e32 v180, v26, v20
	v_and_b32_e32 v20, 0xffff0000, v22
	v_fmac_f32_e32 v181, v27, v20
	ds_read_b32 v20, v134
	v_lshlrev_b32_e32 v22, 16, v21
	v_fmac_f32_e32 v182, v16, v22
	v_and_b32_e32 v16, 0xffff0000, v21
	v_fmac_f32_e32 v183, v17, v16
	s_waitcnt lgkmcnt(0)
	v_lshlrev_b32_e32 v16, 16, v20
	v_fmac_f32_e32 v184, v18, v16
	v_and_b32_e32 v16, 0xffff0000, v20
	v_fmac_f32_e32 v185, v19, v16
	ds_read2st64_b32 v[16:17], v122 offset0:64 offset1:80
	ds_read_b32 v18, v135
	v_fmac_f32_e32 v178, v24, v23
	s_waitcnt lgkmcnt(1)
	v_lshlrev_b32_e32 v19, 16, v16
	v_and_b32_e32 v16, 0xffff0000, v16
	v_fmac_f32_e32 v187, v29, v16
	s_waitcnt lgkmcnt(0)
	v_lshlrev_b32_e32 v16, 16, v18
	v_fmac_f32_e32 v188, v30, v16
	v_and_b32_e32 v16, 0xffff0000, v18
	v_fmac_f32_e32 v189, v31, v16
	ds_read_b32 v16, v136
	v_lshlrev_b32_e32 v18, 16, v17
	v_and_b32_e32 v17, 0xffff0000, v17
	v_fmac_f32_e32 v191, v41, v17
	v_fmac_f32_e32 v190, v40, v18
	s_waitcnt lgkmcnt(0)
	v_lshlrev_b32_e32 v17, 16, v16
	v_and_b32_e32 v16, 0xffff0000, v16
	v_fmac_f32_e32 v192, v42, v17
	v_fmac_f32_e32 v193, v43, v16
	ds_read2st64_b32 v[16:17], v122 offset0:96 offset1:112
	ds_read_b32 v18, v137
	v_fmac_f32_e32 v186, v28, v19
	s_waitcnt lgkmcnt(1)
	v_lshlrev_b32_e32 v19, 16, v16
	v_fmac_f32_e32 v194, v12, v19
	v_and_b32_e32 v12, 0xffff0000, v16
	v_fmac_f32_e32 v195, v13, v12
	s_waitcnt lgkmcnt(0)
	v_lshlrev_b32_e32 v12, 16, v18
	v_fmac_f32_e32 v196, v14, v12
	v_and_b32_e32 v12, 0xffff0000, v18
	v_fmac_f32_e32 v197, v15, v12
	ds_read_b32 v12, v138
	v_lshlrev_b32_e32 v13, 16, v17
	v_fmac_f32_e32 v198, v8, v13
	v_and_b32_e32 v8, 0xffff0000, v17
	v_fmac_f32_e32 v199, v9, v8
	s_waitcnt lgkmcnt(0)
	v_lshlrev_b32_e32 v8, 16, v12
	v_fmac_f32_e32 v200, v10, v8
	v_and_b32_e32 v8, 0xffff0000, v12
	v_fmac_f32_e32 v201, v11, v8
	v_cvt_pk_bf16_f32 v8, v156, s0
	s_barrier
; template <int TN, bool NTS = false>
; __device__ __forceinline__ void store_tile_bf16(const f32x4 (&acc)[4][TN], bf16_t* __restrict__ dst, int ldd, bf16_t* sT,
;                                                 const int tidx) {
;     ...
;   __syncthreads();
; #pragma unroll
;   for (int i = 0; i < 4; i++)
; #pragma unroll
;     for (int j = 0; j < TN; j++)
; #pragma unroll
;       for (int r = 0; r < 4; r++)
;         sT[(wm * 64 + i * 16 + quad * 4 + r) * TS + wn * TN * 16 + j * 16 + l15] = f2bf(acc[i][j][r]);
;   __syncthreads();
; #pragma unroll
;   for (int c = tidx; c < 256 * CPR; c += NT) {
;     int row = c / CPR, cc = c % CPR;
;     const u32x4 v_ = *(const u32x4*)(sT + row * TS + cc * 8);
;     if (NTS) __builtin_nontemporal_store(v_, (u32x4*)(dst + (size_t)row * ldd + cc * 8));
;     else *(u32x4*)(dst + (size_t)row * ldd + cc * 8) = v_;
;   }
	ds_write_b16 v155, v8
	v_cvt_pk_bf16_f32 v8, v157, s0
	ds_write_b16 v155, v8 offset:144
	v_cvt_pk_bf16_f32 v8, v158, s0
	ds_write_b16 v155, v8 offset:288
	v_cvt_pk_bf16_f32 v8, v159, s0
	ds_write_b16 v155, v8 offset:432
	v_cvt_pk_bf16_f32 v8, v174, s0
	ds_write_b16 v155, v8 offset:32
	v_cvt_pk_bf16_f32 v8, v175, s0
	ds_write_b16 v155, v8 offset:176
	v_cvt_pk_bf16_f32 v8, v176, s0
	ds_write_b16 v155, v8 offset:320
	v_cvt_pk_bf16_f32 v8, v177, s0
	ds_write_b16 v155, v8 offset:464
	v_cvt_pk_bf16_f32 v8, v178, s0
	ds_write_b16 v155, v8 offset:2304
	v_cvt_pk_bf16_f32 v8, v179, s0
	ds_write_b16 v155, v8 offset:2448
	v_cvt_pk_bf16_f32 v8, v180, s0
	ds_write_b16 v155, v8 offset:2592
	v_cvt_pk_bf16_f32 v8, v181, s0
	ds_write_b16 v155, v8 offset:2736
	v_cvt_pk_bf16_f32 v8, v182, s0
	ds_write_b16 v155, v8 offset:2336
	v_cvt_pk_bf16_f32 v8, v183, s0
	ds_write_b16 v155, v8 offset:2480
	v_cvt_pk_bf16_f32 v8, v184, s0
	ds_write_b16 v155, v8 offset:2624
	v_cvt_pk_bf16_f32 v8, v185, s0
	ds_write_b16 v155, v8 offset:2768
	v_cvt_pk_bf16_f32 v8, v186, s0
	ds_write_b16 v155, v8 offset:4608
	v_cvt_pk_bf16_f32 v8, v187, s0
	ds_write_b16 v155, v8 offset:4752
	v_cvt_pk_bf16_f32 v8, v188, s0
	ds_write_b16 v155, v8 offset:4896
	v_cvt_pk_bf16_f32 v8, v189, s0
	ds_write_b16 v155, v8 offset:5040
	v_cvt_pk_bf16_f32 v8, v190, s0
	ds_write_b16 v155, v8 offset:4640
	v_cvt_pk_bf16_f32 v8, v191, s0
	ds_write_b16 v155, v8 offset:4784
	v_cvt_pk_bf16_f32 v8, v192, s0
	ds_write_b16 v155, v8 offset:4928
	v_cvt_pk_bf16_f32 v8, v193, s0
	ds_write_b16 v155, v8 offset:5072
	v_cvt_pk_bf16_f32 v8, v194, s0
	ds_write_b16 v155, v8 offset:6912
	v_cvt_pk_bf16_f32 v8, v195, s0
	ds_write_b16 v155, v8 offset:7056
	v_cvt_pk_bf16_f32 v8, v196, s0
	ds_write_b16 v155, v8 offset:7200
	v_cvt_pk_bf16_f32 v8, v197, s0
	ds_write_b16 v155, v8 offset:7344
	v_cvt_pk_bf16_f32 v8, v198, s0
	ds_write_b16 v155, v8 offset:6944
	v_cvt_pk_bf16_f32 v8, v199, s0
	ds_write_b16 v155, v8 offset:7088
	v_cvt_pk_bf16_f32 v8, v200, s0
	ds_write_b16 v155, v8 offset:7232
	v_cvt_pk_bf16_f32 v8, v201, s0
	ds_write_b16 v155, v8 offset:7376
	s_waitcnt lgkmcnt(0)
	s_barrier
	s_and_saveexec_b64 s[16:17], vcc
	s_cbranch_execz .LBB0_84
	s_ashr_i32 s13, s12, 31
	s_lshl_b64 s[10:11], s[12:13], 1
	s_add_u32 s0, s14, s10
	s_addc_u32 s10, s15, s11
	s_add_u32 s12, s0, 0x1800
	s_addc_u32 s13, s10, 0
	v_lshl_add_u32 v8, v150, 4, 0
	s_mov_b64 s[14:15], 0
	v_mov_b32_e32 v9, v116
	v_mov_b32_e32 v10, v150
